# P7/P11 row loads hoisted with counted waits; wave_sum via DPP/permlane instead of ds_bpermute; P6/P8/P12/P2 epilogues; sc1 transposes; DT half
# speedup vs baseline: 1.0390x; 1.0160x over previous
; #define LAS __attribute__((address_space(3)))
; __device__ __forceinline__ f32x4 ld_bf4(const bf16_t* p) { u32x2 w = *(const u32x2*)p; return (f32x4){__uint_as_float(w.x << 16), __uint_as_float(w.x & 0xffff0000u), __uint_as_float(w.y << 16), __uint_as_float(w.y & 0xffff0000u)}; }
; __device__ __forceinline__ void st_bf4(bf16_t* p, f32x4 v) { u32x2 w; w.x = pk2(v[0], v[1]); w.y = pk2(v[2], v[3]); *(u32x2*)p = w; }
; #define LBAR() do { asm volatile("s_waitcnt lgkmcnt(0)" ::: "memory"); __builtin_amdgcn_s_barrier(); asm volatile("" ::: "memory"); } while (0)
; __device__ __forceinline__ float wave_sum(float v) {
; #pragma unroll
;     for (int o = 1; o < 64; o <<= 1) v += __shfl_xor(v, o);
;     return v;
; template <int MODOFF, int STORE  , bool BASE_BF16>
; __device__ __forceinline__ void epi_rows_part1(LAS unsigned char* lds, const f32x4 (&acc)[2][2][4][2], const Unit& u, const float* base, const float* mod, float* outp, float* slots, f32x4 (&xr)[2][16]) {
;     ...
;     const f32x4 gt = *(const f32x4*)(mod + ((u.pm * BM) >> 11) * MODW + MODOFF * DM + colg);
; #pragma unroll
;     for (int ai = 0; ai < 2; ++ai) {
;         if (ai) LBAR();
; #pragma unroll
;         for (int m = 0; m < 4; ++m)
; #pragma unroll
;             for (int bj = 0; bj < 2; ++bj)
; #pragma unroll
;                 for (int n = 0; n < 2; ++n) { const int rl = wr * 64 + m * 16 + fr, c4 = (bj * HALF + wc * 32 + n * 16 + 4 * fq) >> 2;
;                     *(LAS f32x4*)(T + rl * 256 + ((c4 ^ (rl & 15)) << 2)) = acc[ai][bj][m][n]; }
;         LBAR();
; #pragma unroll
;         for (int j = 0; j < 16; ++j) { const int rl = wid * 16 + j, row = u.pm * BM + ai * HALF + rl; const size_t o = (size_t)row * DM + colg;
;             const f32x4 v = *(const LAS f32x4*)(T + rl * 256 + ((lane ^ j) << 2));
;             const f32x4 bs = BASE_BF16 ? ld_bf4((const bf16_t*)base + o) : *(const f32x4*)(base + o);
;             const f32x4 x1 = bs + gt * v; xr[ai][j] = x1; if (STORE == 2) st_bf4((bf16_t*)outp + o, x1);
;             const float sq = wave_sum((x1[0] * x1[0] + x1[1] * x1[1]) + (x1[2] * x1[2] + x1[3] * x1[3]));
;             if (lane == 0) __hip_atomic_store((unsigned*)slots + (size_t)row * 8 + u.pn, __float_as_uint(sq), __ATOMIC_RELAXED, __HIP_MEMORY_SCOPE_AGENT); }
.LBB0_1622:
	s_add_u32 s46, s66, 0x50000
	s_addc_u32 s47, s67, 0
	s_lshr_b32 s0, s3, 3
	v_mov_b32_e32 v134, v189
	s_mulk_i32 s0, 0x3000
	s_ashr_i32 s1, s0, 31
	v_readfirstlane_b32 s4, v134
	s_ashr_i32 s9, s4, 6
	s_lshl_b32 s48, s2, 8
	s_lshl_b64 s[0:1], s[0:1], 2
	s_add_u32 s0, s92, s0
	s_addc_u32 s1, s93, s1
	s_lshr_b32 s4, s4, 2
	v_and_b32_e32 v135, 15, v134
	s_and_b32 s4, s4, 0x3fffc0
	v_and_b32_e32 v139, 63, v134
	v_or_b32_e32 v136, s4, v135
	s_lshl_b32 s4, s9, 5
	v_lshrrev_b32_e32 v134, 2, v134
	s_and_b32 s4, s4, 0x60
	v_and_b32_e32 v134, 12, v134
	v_lshlrev_b32_e32 v138, 2, v135
	v_or_b32_e32 v137, s4, v134
	v_lshl_add_u32 v140, v136, 10, 0
	v_bitop3_b32 v134, s4, v138, v134 bitop3:0x36
	s_lshl_b32 s49, s3, 8
	s_ashr_i32 s3, s2, 31
	v_lshl_add_u32 v134, v134, 2, v140
	s_lshl_b32 s8, s9, 4
	s_lshl_b64 s[2:3], s[2:3], 2
	ds_write_b128 v134, v[128:131]
	v_bitop3_b32 v128, v137, v138, 16 bitop3:0x36
	s_add_u32 s6, s46, s2
	v_lshl_add_u32 v135, v128, 2, v140
	s_movk_i32 s2, 0x80
	v_lshl_or_b32 v132, v139, 2, s48
	ds_write_b128 v135, v[124:127]
	v_bitop3_b32 v124, v137, v138, s2 bitop3:0x36
	v_ashrrev_i32_e32 v133, 31, v132
	v_lshl_add_u32 v136, v124, 2, v140
	s_movk_i32 s2, 0x90
	v_lshl_add_u64 v[0:1], v[132:133], 2, s[0:1]
	s_movk_i32 s5, 0x4000
	s_addc_u32 s7, s47, s3
	ds_write_b128 v136, v[120:123]
	v_bitop3_b32 v120, v137, v138, s2 bitop3:0x36
	s_add_i32 s2, s8, s49
	v_add_co_u32_e32 v0, vcc, s5, v0
	s_ashr_i32 s3, s2, 31
	s_nop 0
	v_addc_co_u32_e32 v1, vcc, 0, v1, vcc
	v_lshl_add_u32 v137, v120, 2, v140
	s_lshl_b64 s[4:5], s[2:3], 11
	v_readlane_b32 s12, v254, 1
	global_load_dwordx4 v[0:3], v[0:1], off
	ds_write_b128 v137, v[116:119]
	ds_write_b128 v134, v[112:115] offset:16384
	ds_write_b128 v135, v[108:111] offset:16384
	ds_write_b128 v136, v[104:107] offset:16384
	ds_write_b128 v137, v[100:103] offset:16384
	ds_write_b128 v134, v[96:99] offset:32768
	ds_write_b128 v135, v[92:95] offset:32768
	ds_write_b128 v136, v[88:91] offset:32768
	ds_write_b128 v137, v[84:87] offset:32768
	ds_write_b128 v134, v[80:83] offset:49152
	ds_write_b128 v135, v[76:79] offset:49152
	ds_write_b128 v136, v[72:75] offset:49152
	ds_write_b128 v137, v[68:71] offset:49152
	v_lshl_add_u64 v[78:79], s[4:5], 0, v[132:133]
	v_readlane_b32 s13, v254, 2
	s_waitcnt lgkmcnt(0)
	s_barrier
	s_lshl_b32 s4, s9, 14
	v_lshl_add_u64 v[68:69], v[78:79], 2, s[12:13]
	s_mov_b64 s[98:99], 0x2000
	global_load_dwordx4 v[164:167], v[68:69], off
	v_lshl_add_u64 v[252:253], v[68:69], 0, s[98:99]
	global_load_dwordx4 v[168:171], v[252:253], off
	v_lshl_add_u64 v[252:253], v[252:253], 0, s[98:99]
	global_load_dwordx4 v[172:175], v[252:253], off
	v_lshl_add_u64 v[252:253], v[252:253], 0, s[98:99]
	global_load_dwordx4 v[176:179], v[252:253], off
	v_lshl_add_u64 v[252:253], v[252:253], 0, s[98:99]
	global_load_dwordx4 v[180:183], v[252:253], off
	v_lshl_add_u64 v[252:253], v[252:253], 0, s[98:99]
	global_load_dwordx4 v[184:187], v[252:253], off
	v_lshl_add_u64 v[252:253], v[252:253], 0, s[98:99]
	global_load_dwordx4 v[196:199], v[252:253], off
	v_lshl_add_u64 v[252:253], v[252:253], 0, s[98:99]
	global_load_dwordx4 v[200:203], v[252:253], off
	v_lshl_add_u64 v[252:253], v[252:253], 0, s[98:99]
	global_load_dwordx4 v[204:207], v[252:253], off
	v_lshl_add_u64 v[252:253], v[252:253], 0, s[98:99]
	global_load_dwordx4 v[208:211], v[252:253], off
	v_lshl_add_u64 v[252:253], v[252:253], 0, s[98:99]
	global_load_dwordx4 v[212:215], v[252:253], off
	v_lshl_add_u64 v[252:253], v[252:253], 0, s[98:99]
	global_load_dwordx4 v[216:219], v[252:253], off
	v_lshl_add_u64 v[252:253], v[252:253], 0, s[98:99]
	global_load_dwordx4 v[220:223], v[252:253], off
	v_lshl_add_u64 v[252:253], v[252:253], 0, s[98:99]
	global_load_dwordx4 v[224:227], v[252:253], off
	v_lshl_add_u64 v[252:253], v[252:253], 0, s[98:99]
	global_load_dwordx4 v[228:231], v[252:253], off
	v_lshl_add_u64 v[252:253], v[252:253], 0, s[98:99]
	global_load_dwordx4 v[232:235], v[252:253], off
	v_lshlrev_b32_e32 v128, 4, v139
	s_add_i32 s4, s4, 0
	v_mbcnt_lo_u32_b32 v68, -1, 0
	v_add_u32_e32 v138, s4, v128
	v_mbcnt_hi_u32_b32 v80, -1, v68
	ds_read_b128 v[74:77], v138
	v_and_b32_e32 v68, 64, v80
	v_xor_b32_e32 v69, 1, v80
	v_add_u32_e32 v81, 64, v68
	v_cmp_lt_i32_e64 s[4:5], v69, v81
	v_cmp_eq_u32_e32 vcc, 0, v139
	v_readlane_b32 s14, v254, 3
	v_cndmask_b32_e64 v68, v80, v69, s[4:5]
	v_lshlrev_b32_e32 v188, 2, v68
	v_readlane_b32 s15, v254, 4
	v_readlane_b32 s16, v254, 5
	v_readlane_b32 s17, v254, 6
	v_readlane_b32 s18, v254, 7
	v_readlane_b32 s19, v254, 8
	v_readlane_b32 s20, v254, 9
	v_readlane_b32 s21, v254, 10
	v_readlane_b32 s22, v254, 11
	v_readlane_b32 s23, v254, 12
	v_readlane_b32 s24, v254, 13
	v_readlane_b32 s25, v254, 14
	v_readlane_b32 s26, v254, 15
	v_readlane_b32 s27, v254, 16
	s_waitcnt vmcnt(15) lgkmcnt(0)
	v_mov_b32_e32 v70, v164
	v_mov_b32_e32 v71, v165
	v_mov_b32_e32 v72, v166
	v_mov_b32_e32 v73, v167
	v_pk_fma_f32 v[68:69], v[2:3], v[76:77], v[72:73]
	v_pk_fma_f32 v[70:71], v[0:1], v[74:75], v[70:71]
	v_mul_f32_e32 v73, v69, v69
	v_mul_f32_e32 v72, v71, v71
	v_fmac_f32_e32 v72, v70, v70
	v_fmac_f32_e32 v73, v68, v68
	v_add_f32_e32 v72, v72, v73
	s_nop 1
	v_mov_b32_dpp v73, v72 quad_perm:[1,0,3,2] row_mask:0xf bank_mask:0xf
	v_xor_b32_e32 v74, 2, v80
	v_cmp_lt_i32_e64 s[4:5], v74, v81
	v_cvt_pk_bf16_f32 v76, v70, v71
	v_cvt_pk_bf16_f32 v77, v68, v69
	v_cndmask_b32_e64 v74, v80, v74, s[4:5]
	v_lshlrev_b32_e32 v190, 2, v74
	s_waitcnt lgkmcnt(0)
	v_add_f32_e32 v72, v72, v73
	s_nop 1
	v_mov_b32_dpp v73, v72 quad_perm:[2,3,0,1] row_mask:0xf bank_mask:0xf
	v_xor_b32_e32 v74, 4, v80
	v_cmp_lt_i32_e64 s[4:5], v74, v81
	s_waitcnt lgkmcnt(0)
	v_add_f32_e32 v72, v72, v73
	v_cndmask_b32_e64 v74, v80, v74, s[4:5]
	v_lshlrev_b32_e32 v191, 2, v74
	s_nop 1
	v_mov_b32_dpp v73, v72 row_ror:12 row_mask:0xf bank_mask:0xf
	v_xor_b32_e32 v74, 8, v80
	v_cmp_lt_i32_e64 s[4:5], v74, v81
	s_waitcnt lgkmcnt(0)
	v_add_f32_e32 v72, v72, v73
	v_cndmask_b32_e64 v74, v80, v74, s[4:5]
	v_lshlrev_b32_e32 v192, 2, v74
	s_nop 1
	v_mov_b32_dpp v73, v72 row_ror:8 row_mask:0xf bank_mask:0xf
	v_xor_b32_e32 v74, 16, v80
	v_cmp_lt_i32_e64 s[4:5], v74, v81
	s_waitcnt lgkmcnt(0)
	v_add_f32_e32 v72, v72, v73
	v_cndmask_b32_e64 v74, v80, v74, s[4:5]
	v_lshlrev_b32_e32 v193, 2, v74
	v_mov_b32_e32 v73, v72
	s_nop 1
	v_permlane16_swap_b32_e32 v72, v73
	v_xor_b32_e32 v74, 32, v80
	v_cmp_lt_i32_e64 s[4:5], v74, v81
	s_waitcnt lgkmcnt(0)
	v_add_f32_e32 v72, v72, v73
	v_cndmask_b32_e64 v74, v80, v74, s[4:5]
	v_lshlrev_b32_e32 v194, 2, v74
	v_mov_b32_e32 v73, v72
	s_nop 1
	v_permlane32_swap_b32_e32 v72, v73
	v_lshl_add_u64 v[74:75], v[78:79], 1, s[64:65]
	global_store_dwordx2 v[74:75], v[76:77], off
	s_and_saveexec_b64 s[4:5], vcc
	s_cbranch_execz .LBB0_1624
	s_lshl_b64 s[2:3], s[2:3], 5
	s_add_u32 s2, s6, s2
	s_addc_u32 s3, s7, s3
	v_mov_b32_e32 v74, 0
	s_waitcnt lgkmcnt(0)
	v_add_f32_e32 v72, v72, v73
	global_store_dword v74, v72, s[2:3] sc1
; #define LAS __attribute__((address_space(3)))
; __device__ __forceinline__ f32x4 ld_bf4(const bf16_t* p) { u32x2 w = *(const u32x2*)p; return (f32x4){__uint_as_float(w.x << 16), __uint_as_float(w.x & 0xffff0000u), __uint_as_float(w.y << 16), __uint_as_float(w.y & 0xffff0000u)}; }
; __device__ __forceinline__ void st_bf4(bf16_t* p, f32x4 v) { u32x2 w; w.x = pk2(v[0], v[1]); w.y = pk2(v[2], v[3]); *(u32x2*)p = w; }
; __device__ __forceinline__ float wave_sum(float v) {
; #pragma unroll
;     for (int o = 1; o < 64; o <<= 1) v += __shfl_xor(v, o);
;     return v;
; template <int MODOFF, int STORE  , bool BASE_BF16>
; __device__ __forceinline__ void epi_rows_part1(LAS unsigned char* lds, const f32x4 (&acc)[2][2][4][2], const Unit& u, const float* base, const float* mod, float* outp, float* slots, f32x4 (&xr)[2][16]) {
;     ...
;         for (int j = 0; j < 16; ++j) { const int rl = wid * 16 + j, row = u.pm * BM + ai * HALF + rl; const size_t o = (size_t)row * DM + colg;
;             const f32x4 v = *(const LAS f32x4*)(T + rl * 256 + ((lane ^ j) << 2));
;             const f32x4 bs = BASE_BF16 ? ld_bf4((const bf16_t*)base + o) : *(const f32x4*)(base + o);
;             const f32x4 x1 = bs + gt * v; xr[ai][j] = x1; if (STORE == 2) st_bf4((bf16_t*)outp + o, x1);
;             const float sq = wave_sum((x1[0] * x1[0] + x1[1] * x1[1]) + (x1[2] * x1[2] + x1[3] * x1[3]));
;             if (lane == 0) __hip_atomic_store((unsigned*)slots + (size_t)row * 8 + u.pn, __float_as_uint(sq), __ATOMIC_RELAXED, __HIP_MEMORY_SCOPE_AGENT); }
.LBB0_1624:
	s_or_b64 exec, exec, s[4:5]
	s_or_b32 s9, s8, 1
	s_add_i32 s2, s9, s49
	s_ashr_i32 s3, s2, 31
	s_lshl_b64 s[4:5], s[2:3], 11
	v_readlane_b32 s12, v254, 1
	v_lshl_add_u64 v[82:83], s[4:5], 0, v[132:133]
	v_readlane_b32 s13, v254, 2
	s_lshl_b32 s4, s9, 10
	s_add_i32 s4, s4, 0
	s_waitcnt lgkmcnt(0)
	v_lshl_add_u64 v[72:73], v[82:83], 2, s[12:13]
	v_xor_b32_e32 v72, 16, v128
	v_add_u32_e32 v139, s4, v72
	ds_read_b128 v[78:81], v139
	v_readlane_b32 s14, v254, 3
	v_readlane_b32 s15, v254, 4
	v_readlane_b32 s16, v254, 5
	v_readlane_b32 s17, v254, 6
	v_readlane_b32 s18, v254, 7
	v_readlane_b32 s19, v254, 8
	v_readlane_b32 s20, v254, 9
	v_readlane_b32 s21, v254, 10
	v_readlane_b32 s22, v254, 11
	v_readlane_b32 s23, v254, 12
	v_readlane_b32 s24, v254, 13
	v_readlane_b32 s25, v254, 14
	v_readlane_b32 s26, v254, 15
	v_readlane_b32 s27, v254, 16
	s_waitcnt vmcnt(16) lgkmcnt(0)
	v_mov_b32_e32 v74, v168
	v_mov_b32_e32 v75, v169
	v_mov_b32_e32 v76, v170
	v_mov_b32_e32 v77, v171
	v_pk_fma_f32 v[72:73], v[2:3], v[80:81], v[76:77]
	v_pk_fma_f32 v[74:75], v[0:1], v[78:79], v[74:75]
	v_mul_f32_e32 v77, v73, v73
	v_mul_f32_e32 v76, v75, v75
	v_fmac_f32_e32 v76, v74, v74
	v_fmac_f32_e32 v77, v72, v72
	v_add_f32_e32 v76, v76, v77
	s_nop 1
	v_mov_b32_dpp v77, v76 quad_perm:[1,0,3,2] row_mask:0xf bank_mask:0xf
	v_lshl_add_u64 v[78:79], v[82:83], 1, s[64:65]
	v_cvt_pk_bf16_f32 v80, v74, v75
	v_cvt_pk_bf16_f32 v81, v72, v73
	global_store_dwordx2 v[78:79], v[80:81], off
	s_waitcnt lgkmcnt(0)
	v_add_f32_e32 v76, v76, v77
	s_nop 1
	v_mov_b32_dpp v77, v76 quad_perm:[2,3,0,1] row_mask:0xf bank_mask:0xf
	s_waitcnt lgkmcnt(0)
	v_add_f32_e32 v76, v76, v77
	s_nop 1
	v_mov_b32_dpp v77, v76 row_ror:12 row_mask:0xf bank_mask:0xf
	s_waitcnt lgkmcnt(0)
	v_add_f32_e32 v76, v76, v77
	s_nop 1
	v_mov_b32_dpp v77, v76 row_ror:8 row_mask:0xf bank_mask:0xf
	s_waitcnt lgkmcnt(0)
	v_add_f32_e32 v76, v76, v77
	v_mov_b32_e32 v77, v76
	s_nop 1
	v_permlane16_swap_b32_e32 v76, v77
	s_waitcnt lgkmcnt(0)
	v_add_f32_e32 v76, v76, v77
	v_mov_b32_e32 v77, v76
	s_nop 1
	v_permlane32_swap_b32_e32 v76, v77
	s_and_saveexec_b64 s[4:5], vcc
	s_cbranch_execz .LBB0_1626
	s_lshl_b64 s[2:3], s[2:3], 5
	s_add_u32 s2, s6, s2
	s_addc_u32 s3, s7, s3
	v_mov_b32_e32 v78, 0
	s_waitcnt lgkmcnt(0)
	v_add_f32_e32 v76, v76, v77
	global_store_dword v78, v76, s[2:3] sc1
.LBB0_1626:
	s_or_b64 exec, exec, s[4:5]
	s_or_b32 s10, s8, 2
	s_add_i32 s2, s10, s49
	s_ashr_i32 s3, s2, 31
	s_lshl_b64 s[4:5], s[2:3], 11
	v_readlane_b32 s12, v254, 1
	v_lshl_add_u64 v[86:87], s[4:5], 0, v[132:133]
	v_readlane_b32 s13, v254, 2
	s_lshl_b32 s4, s10, 10
	s_add_i32 s4, s4, 0
	s_waitcnt lgkmcnt(0)
	v_lshl_add_u64 v[76:77], v[86:87], 2, s[12:13]
	v_xor_b32_e32 v76, 32, v128
	v_add_u32_e32 v140, s4, v76
	ds_read_b128 v[82:85], v140
	v_readlane_b32 s14, v254, 3
	v_readlane_b32 s15, v254, 4
	v_readlane_b32 s16, v254, 5
	v_readlane_b32 s17, v254, 6
	v_readlane_b32 s18, v254, 7
	v_readlane_b32 s19, v254, 8
	v_readlane_b32 s20, v254, 9
	v_readlane_b32 s21, v254, 10
	v_readlane_b32 s22, v254, 11
	v_readlane_b32 s23, v254, 12
	v_readlane_b32 s24, v254, 13
	v_readlane_b32 s25, v254, 14
	v_readlane_b32 s26, v254, 15
	v_readlane_b32 s27, v254, 16
	s_waitcnt vmcnt(17) lgkmcnt(0)
	v_mov_b32_e32 v78, v172
	v_mov_b32_e32 v79, v173
	v_mov_b32_e32 v80, v174
	v_mov_b32_e32 v81, v175
	v_pk_fma_f32 v[76:77], v[2:3], v[84:85], v[80:81]
	v_pk_fma_f32 v[78:79], v[0:1], v[82:83], v[78:79]
	v_mul_f32_e32 v81, v77, v77
	v_mul_f32_e32 v80, v79, v79
	v_fmac_f32_e32 v80, v78, v78
	v_fmac_f32_e32 v81, v76, v76
	v_add_f32_e32 v80, v80, v81
	s_nop 1
	v_mov_b32_dpp v81, v80 quad_perm:[1,0,3,2] row_mask:0xf bank_mask:0xf
	v_lshl_add_u64 v[82:83], v[86:87], 1, s[64:65]
	v_cvt_pk_bf16_f32 v84, v78, v79
	v_cvt_pk_bf16_f32 v85, v76, v77
	global_store_dwordx2 v[82:83], v[84:85], off
	s_waitcnt lgkmcnt(0)
	v_add_f32_e32 v80, v80, v81
	s_nop 1
	v_mov_b32_dpp v81, v80 quad_perm:[2,3,0,1] row_mask:0xf bank_mask:0xf
	s_waitcnt lgkmcnt(0)
	v_add_f32_e32 v80, v80, v81
	s_nop 1
	v_mov_b32_dpp v81, v80 row_ror:12 row_mask:0xf bank_mask:0xf
	s_waitcnt lgkmcnt(0)
	v_add_f32_e32 v80, v80, v81
	s_nop 1
	v_mov_b32_dpp v81, v80 row_ror:8 row_mask:0xf bank_mask:0xf
	s_waitcnt lgkmcnt(0)
	v_add_f32_e32 v80, v80, v81
	v_mov_b32_e32 v81, v80
	s_nop 1
	v_permlane16_swap_b32_e32 v80, v81
	s_waitcnt lgkmcnt(0)
	v_add_f32_e32 v80, v80, v81
	v_mov_b32_e32 v81, v80
	s_nop 1
	v_permlane32_swap_b32_e32 v80, v81
	s_and_saveexec_b64 s[4:5], vcc
	s_cbranch_execz .LBB0_1628
	s_lshl_b64 s[2:3], s[2:3], 5
	s_add_u32 s2, s6, s2
	s_addc_u32 s3, s7, s3
	v_mov_b32_e32 v82, 0
	s_waitcnt lgkmcnt(0)
	v_add_f32_e32 v80, v80, v81
	global_store_dword v82, v80, s[2:3] sc1
; #define LAS __attribute__((address_space(3)))
; __device__ __forceinline__ f32x4 ld_bf4(const bf16_t* p) { u32x2 w = *(const u32x2*)p; return (f32x4){__uint_as_float(w.x << 16), __uint_as_float(w.x & 0xffff0000u), __uint_as_float(w.y << 16), __uint_as_float(w.y & 0xffff0000u)}; }
; __device__ __forceinline__ void st_bf4(bf16_t* p, f32x4 v) { u32x2 w; w.x = pk2(v[0], v[1]); w.y = pk2(v[2], v[3]); *(u32x2*)p = w; }
; __device__ __forceinline__ float wave_sum(float v) {
; #pragma unroll
;     for (int o = 1; o < 64; o <<= 1) v += __shfl_xor(v, o);
;     return v;
; template <int MODOFF, int STORE  , bool BASE_BF16>
; __device__ __forceinline__ void epi_rows_part1(LAS unsigned char* lds, const f32x4 (&acc)[2][2][4][2], const Unit& u, const float* base, const float* mod, float* outp, float* slots, f32x4 (&xr)[2][16]) {
;     ...
;         for (int j = 0; j < 16; ++j) { const int rl = wid * 16 + j, row = u.pm * BM + ai * HALF + rl; const size_t o = (size_t)row * DM + colg;
;             const f32x4 v = *(const LAS f32x4*)(T + rl * 256 + ((lane ^ j) << 2));
;             const f32x4 bs = BASE_BF16 ? ld_bf4((const bf16_t*)base + o) : *(const f32x4*)(base + o);
;             const f32x4 x1 = bs + gt * v; xr[ai][j] = x1; if (STORE == 2) st_bf4((bf16_t*)outp + o, x1);
;             const float sq = wave_sum((x1[0] * x1[0] + x1[1] * x1[1]) + (x1[2] * x1[2] + x1[3] * x1[3]));
;             if (lane == 0) __hip_atomic_store((unsigned*)slots + (size_t)row * 8 + u.pn, __float_as_uint(sq), __ATOMIC_RELAXED, __HIP_MEMORY_SCOPE_AGENT); }
.LBB0_1628:
	s_or_b64 exec, exec, s[4:5]
	s_or_b32 s11, s8, 3
	s_add_i32 s2, s11, s49
	s_ashr_i32 s3, s2, 31
	s_lshl_b64 s[4:5], s[2:3], 11
	v_readlane_b32 s12, v254, 1
	v_lshl_add_u64 v[90:91], s[4:5], 0, v[132:133]
	v_readlane_b32 s13, v254, 2
	s_lshl_b32 s4, s11, 10
	s_add_i32 s4, s4, 0
	s_waitcnt lgkmcnt(0)
	v_lshl_add_u64 v[80:81], v[90:91], 2, s[12:13]
	v_xor_b32_e32 v80, 48, v128
	v_add_u32_e32 v141, s4, v80
	ds_read_b128 v[86:89], v141
	v_readlane_b32 s14, v254, 3
	v_readlane_b32 s15, v254, 4
	v_readlane_b32 s16, v254, 5
	v_readlane_b32 s17, v254, 6
	v_readlane_b32 s18, v254, 7
	v_readlane_b32 s19, v254, 8
	v_readlane_b32 s20, v254, 9
	v_readlane_b32 s21, v254, 10
	v_readlane_b32 s22, v254, 11
	v_readlane_b32 s23, v254, 12
	v_readlane_b32 s24, v254, 13
	v_readlane_b32 s25, v254, 14
	v_readlane_b32 s26, v254, 15
	v_readlane_b32 s27, v254, 16
	s_waitcnt vmcnt(18) lgkmcnt(0)
	v_mov_b32_e32 v82, v176
	v_mov_b32_e32 v83, v177
	v_mov_b32_e32 v84, v178
	v_mov_b32_e32 v85, v179
	v_pk_fma_f32 v[80:81], v[2:3], v[88:89], v[84:85]
	v_pk_fma_f32 v[82:83], v[0:1], v[86:87], v[82:83]
	v_mul_f32_e32 v85, v81, v81
	v_mul_f32_e32 v84, v83, v83
	v_fmac_f32_e32 v84, v82, v82
	v_fmac_f32_e32 v85, v80, v80
	v_add_f32_e32 v84, v84, v85
	s_nop 1
	v_mov_b32_dpp v85, v84 quad_perm:[1,0,3,2] row_mask:0xf bank_mask:0xf
	v_lshl_add_u64 v[86:87], v[90:91], 1, s[64:65]
	v_cvt_pk_bf16_f32 v88, v82, v83
	v_cvt_pk_bf16_f32 v89, v80, v81
	global_store_dwordx2 v[86:87], v[88:89], off
	s_waitcnt lgkmcnt(0)
	v_add_f32_e32 v84, v84, v85
	s_nop 1
	v_mov_b32_dpp v85, v84 quad_perm:[2,3,0,1] row_mask:0xf bank_mask:0xf
	s_waitcnt lgkmcnt(0)
	v_add_f32_e32 v84, v84, v85
	s_nop 1
	v_mov_b32_dpp v85, v84 row_ror:12 row_mask:0xf bank_mask:0xf
	s_waitcnt lgkmcnt(0)
	v_add_f32_e32 v84, v84, v85
	s_nop 1
	v_mov_b32_dpp v85, v84 row_ror:8 row_mask:0xf bank_mask:0xf
	s_waitcnt lgkmcnt(0)
	v_add_f32_e32 v84, v84, v85
	v_mov_b32_e32 v85, v84
	s_nop 1
	v_permlane16_swap_b32_e32 v84, v85
	s_waitcnt lgkmcnt(0)
	v_add_f32_e32 v84, v84, v85
	v_mov_b32_e32 v85, v84
	s_nop 1
	v_permlane32_swap_b32_e32 v84, v85
	s_and_saveexec_b64 s[4:5], vcc
	s_cbranch_execz .LBB0_1630
	s_lshl_b64 s[2:3], s[2:3], 5
	s_add_u32 s2, s6, s2
	s_addc_u32 s3, s7, s3
	v_mov_b32_e32 v86, 0
	s_waitcnt lgkmcnt(0)
	v_add_f32_e32 v84, v84, v85
	global_store_dword v86, v84, s[2:3] sc1
.LBB0_1630:
	s_or_b64 exec, exec, s[4:5]
	s_or_b32 s12, s8, 4
	s_add_i32 s2, s12, s49
	s_ashr_i32 s3, s2, 31
	s_lshl_b64 s[4:5], s[2:3], 11
	v_readlane_b32 s16, v254, 1
	v_lshl_add_u64 v[94:95], s[4:5], 0, v[132:133]
	v_readlane_b32 s17, v254, 2
	s_lshl_b32 s4, s12, 10
	s_add_i32 s4, s4, 0
	s_waitcnt lgkmcnt(0)
	v_lshl_add_u64 v[84:85], v[94:95], 2, s[16:17]
	v_xor_b32_e32 v84, 64, v128
	v_add_u32_e32 v142, s4, v84
	ds_read_b128 v[90:93], v142
	v_readlane_b32 s18, v254, 3
	v_readlane_b32 s19, v254, 4
	v_readlane_b32 s20, v254, 5
	v_readlane_b32 s21, v254, 6
	v_readlane_b32 s22, v254, 7
	v_readlane_b32 s23, v254, 8
	v_readlane_b32 s24, v254, 9
	v_readlane_b32 s25, v254, 10
	v_readlane_b32 s26, v254, 11
	v_readlane_b32 s27, v254, 12
	v_readlane_b32 s28, v254, 13
	v_readlane_b32 s29, v254, 14
	v_readlane_b32 s30, v254, 15
	v_readlane_b32 s31, v254, 16
	s_waitcnt vmcnt(19) lgkmcnt(0)
	v_mov_b32_e32 v86, v180
	v_mov_b32_e32 v87, v181
	v_mov_b32_e32 v88, v182
	v_mov_b32_e32 v89, v183
	v_pk_fma_f32 v[84:85], v[2:3], v[92:93], v[88:89]
	v_pk_fma_f32 v[86:87], v[0:1], v[90:91], v[86:87]
	v_mul_f32_e32 v89, v85, v85
	v_mul_f32_e32 v88, v87, v87
	v_fmac_f32_e32 v88, v86, v86
	v_fmac_f32_e32 v89, v84, v84
	v_add_f32_e32 v88, v88, v89
	s_nop 1
	v_mov_b32_dpp v89, v88 quad_perm:[1,0,3,2] row_mask:0xf bank_mask:0xf
	v_lshl_add_u64 v[90:91], v[94:95], 1, s[64:65]
	v_cvt_pk_bf16_f32 v92, v86, v87
	v_cvt_pk_bf16_f32 v93, v84, v85
	global_store_dwordx2 v[90:91], v[92:93], off
	s_waitcnt lgkmcnt(0)
	v_add_f32_e32 v88, v88, v89
	s_nop 1
	v_mov_b32_dpp v89, v88 quad_perm:[2,3,0,1] row_mask:0xf bank_mask:0xf
	s_waitcnt lgkmcnt(0)
	v_add_f32_e32 v88, v88, v89
	s_nop 1
	v_mov_b32_dpp v89, v88 row_ror:12 row_mask:0xf bank_mask:0xf
	s_waitcnt lgkmcnt(0)
	v_add_f32_e32 v88, v88, v89
	s_nop 1
	v_mov_b32_dpp v89, v88 row_ror:8 row_mask:0xf bank_mask:0xf
	s_waitcnt lgkmcnt(0)
	v_add_f32_e32 v88, v88, v89
	v_mov_b32_e32 v89, v88
	s_nop 1
	v_permlane16_swap_b32_e32 v88, v89
	s_waitcnt lgkmcnt(0)
	v_add_f32_e32 v88, v88, v89
	v_mov_b32_e32 v89, v88
	s_nop 1
	v_permlane32_swap_b32_e32 v88, v89
	s_and_saveexec_b64 s[4:5], vcc
	s_cbranch_execz .LBB0_1632
	s_lshl_b64 s[2:3], s[2:3], 5
	s_add_u32 s2, s6, s2
	s_addc_u32 s3, s7, s3
	v_mov_b32_e32 v90, 0
	s_waitcnt lgkmcnt(0)
	v_add_f32_e32 v88, v88, v89
	global_store_dword v90, v88, s[2:3] sc1
; #define LAS __attribute__((address_space(3)))
; __device__ __forceinline__ f32x4 ld_bf4(const bf16_t* p) { u32x2 w = *(const u32x2*)p; return (f32x4){__uint_as_float(w.x << 16), __uint_as_float(w.x & 0xffff0000u), __uint_as_float(w.y << 16), __uint_as_float(w.y & 0xffff0000u)}; }
; __device__ __forceinline__ void st_bf4(bf16_t* p, f32x4 v) { u32x2 w; w.x = pk2(v[0], v[1]); w.y = pk2(v[2], v[3]); *(u32x2*)p = w; }
; __device__ __forceinline__ float wave_sum(float v) {
; #pragma unroll
;     for (int o = 1; o < 64; o <<= 1) v += __shfl_xor(v, o);
;     return v;
; template <int MODOFF, int STORE  , bool BASE_BF16>
; __device__ __forceinline__ void epi_rows_part1(LAS unsigned char* lds, const f32x4 (&acc)[2][2][4][2], const Unit& u, const float* base, const float* mod, float* outp, float* slots, f32x4 (&xr)[2][16]) {
;     ...
;         for (int j = 0; j < 16; ++j) { const int rl = wid * 16 + j, row = u.pm * BM + ai * HALF + rl; const size_t o = (size_t)row * DM + colg;
;             const f32x4 v = *(const LAS f32x4*)(T + rl * 256 + ((lane ^ j) << 2));
;             const f32x4 bs = BASE_BF16 ? ld_bf4((const bf16_t*)base + o) : *(const f32x4*)(base + o);
;             const f32x4 x1 = bs + gt * v; xr[ai][j] = x1; if (STORE == 2) st_bf4((bf16_t*)outp + o, x1);
;             const float sq = wave_sum((x1[0] * x1[0] + x1[1] * x1[1]) + (x1[2] * x1[2] + x1[3] * x1[3]));
;             if (lane == 0) __hip_atomic_store((unsigned*)slots + (size_t)row * 8 + u.pn, __float_as_uint(sq), __ATOMIC_RELAXED, __HIP_MEMORY_SCOPE_AGENT); }
.LBB0_1632:
	s_or_b64 exec, exec, s[4:5]
	s_or_b32 s13, s8, 5
	s_add_i32 s2, s13, s49
	s_ashr_i32 s3, s2, 31
	s_lshl_b64 s[4:5], s[2:3], 11
	v_readlane_b32 s16, v254, 1
	v_lshl_add_u64 v[98:99], s[4:5], 0, v[132:133]
	v_readlane_b32 s17, v254, 2
	s_lshl_b32 s4, s13, 10
	s_add_i32 s4, s4, 0
	s_waitcnt lgkmcnt(0)
	v_lshl_add_u64 v[88:89], v[98:99], 2, s[16:17]
	v_xor_b32_e32 v88, 0x50, v128
	v_add_u32_e32 v143, s4, v88
	ds_read_b128 v[94:97], v143
	v_readlane_b32 s18, v254, 3
	v_readlane_b32 s19, v254, 4
	v_readlane_b32 s20, v254, 5
	v_readlane_b32 s21, v254, 6
	v_readlane_b32 s22, v254, 7
	v_readlane_b32 s23, v254, 8
	v_readlane_b32 s24, v254, 9
	v_readlane_b32 s25, v254, 10
	v_readlane_b32 s26, v254, 11
	v_readlane_b32 s27, v254, 12
	v_readlane_b32 s28, v254, 13
	v_readlane_b32 s29, v254, 14
	v_readlane_b32 s30, v254, 15
	v_readlane_b32 s31, v254, 16
	s_waitcnt vmcnt(20) lgkmcnt(0)
	v_mov_b32_e32 v90, v184
	v_mov_b32_e32 v91, v185
	v_mov_b32_e32 v92, v186
	v_mov_b32_e32 v93, v187
	v_pk_fma_f32 v[88:89], v[2:3], v[96:97], v[92:93]
	v_pk_fma_f32 v[90:91], v[0:1], v[94:95], v[90:91]
	v_mul_f32_e32 v93, v89, v89
	v_mul_f32_e32 v92, v91, v91
	v_fmac_f32_e32 v92, v90, v90
	v_fmac_f32_e32 v93, v88, v88
	v_add_f32_e32 v92, v92, v93
	s_nop 1
	v_mov_b32_dpp v93, v92 quad_perm:[1,0,3,2] row_mask:0xf bank_mask:0xf
	v_lshl_add_u64 v[94:95], v[98:99], 1, s[64:65]
	v_cvt_pk_bf16_f32 v96, v90, v91
	v_cvt_pk_bf16_f32 v97, v88, v89
	global_store_dwordx2 v[94:95], v[96:97], off
	s_waitcnt lgkmcnt(0)
	v_add_f32_e32 v92, v92, v93
	s_nop 1
	v_mov_b32_dpp v93, v92 quad_perm:[2,3,0,1] row_mask:0xf bank_mask:0xf
	s_waitcnt lgkmcnt(0)
	v_add_f32_e32 v92, v92, v93
	s_nop 1
	v_mov_b32_dpp v93, v92 row_ror:12 row_mask:0xf bank_mask:0xf
	s_waitcnt lgkmcnt(0)
	v_add_f32_e32 v92, v92, v93
	s_nop 1
	v_mov_b32_dpp v93, v92 row_ror:8 row_mask:0xf bank_mask:0xf
	s_waitcnt lgkmcnt(0)
	v_add_f32_e32 v92, v92, v93
	v_mov_b32_e32 v93, v92
	s_nop 1
	v_permlane16_swap_b32_e32 v92, v93
	s_waitcnt lgkmcnt(0)
	v_add_f32_e32 v92, v92, v93
	v_mov_b32_e32 v93, v92
	s_nop 1
	v_permlane32_swap_b32_e32 v92, v93
	s_and_saveexec_b64 s[4:5], vcc
	s_cbranch_execz .LBB0_1634
	s_lshl_b64 s[2:3], s[2:3], 5
	s_add_u32 s2, s6, s2
	s_addc_u32 s3, s7, s3
	v_mov_b32_e32 v94, 0
	s_waitcnt lgkmcnt(0)
	v_add_f32_e32 v92, v92, v93
	global_store_dword v94, v92, s[2:3] sc1
.LBB0_1634:
	s_or_b64 exec, exec, s[4:5]
	s_or_b32 s14, s8, 6
	s_add_i32 s2, s14, s49
	s_ashr_i32 s3, s2, 31
	s_lshl_b64 s[4:5], s[2:3], 11
	v_readlane_b32 s16, v254, 1
	v_lshl_add_u64 v[102:103], s[4:5], 0, v[132:133]
	v_readlane_b32 s17, v254, 2
	s_lshl_b32 s4, s14, 10
	s_add_i32 s4, s4, 0
	s_waitcnt lgkmcnt(0)
	v_lshl_add_u64 v[92:93], v[102:103], 2, s[16:17]
	v_xor_b32_e32 v92, 0x60, v128
	v_add_u32_e32 v144, s4, v92
	ds_read_b128 v[98:101], v144
	v_readlane_b32 s18, v254, 3
	v_readlane_b32 s19, v254, 4
	v_readlane_b32 s20, v254, 5
	v_readlane_b32 s21, v254, 6
	v_readlane_b32 s22, v254, 7
	v_readlane_b32 s23, v254, 8
	v_readlane_b32 s24, v254, 9
	v_readlane_b32 s25, v254, 10
	v_readlane_b32 s26, v254, 11
	v_readlane_b32 s27, v254, 12
	v_readlane_b32 s28, v254, 13
	v_readlane_b32 s29, v254, 14
	v_readlane_b32 s30, v254, 15
	v_readlane_b32 s31, v254, 16
	s_waitcnt vmcnt(21) lgkmcnt(0)
	v_mov_b32_e32 v94, v196
	v_mov_b32_e32 v95, v197
	v_mov_b32_e32 v96, v198
	v_mov_b32_e32 v97, v199
	v_pk_fma_f32 v[92:93], v[2:3], v[100:101], v[96:97]
	v_pk_fma_f32 v[94:95], v[0:1], v[98:99], v[94:95]
	v_mul_f32_e32 v97, v93, v93
	v_mul_f32_e32 v96, v95, v95
	v_fmac_f32_e32 v96, v94, v94
	v_fmac_f32_e32 v97, v92, v92
	v_add_f32_e32 v96, v96, v97
	s_nop 1
	v_mov_b32_dpp v97, v96 quad_perm:[1,0,3,2] row_mask:0xf bank_mask:0xf
	v_lshl_add_u64 v[98:99], v[102:103], 1, s[64:65]
	v_cvt_pk_bf16_f32 v100, v94, v95
	v_cvt_pk_bf16_f32 v101, v92, v93
	global_store_dwordx2 v[98:99], v[100:101], off
	s_waitcnt lgkmcnt(0)
	v_add_f32_e32 v96, v96, v97
	s_nop 1
	v_mov_b32_dpp v97, v96 quad_perm:[2,3,0,1] row_mask:0xf bank_mask:0xf
	s_waitcnt lgkmcnt(0)
	v_add_f32_e32 v96, v96, v97
	s_nop 1
	v_mov_b32_dpp v97, v96 row_ror:12 row_mask:0xf bank_mask:0xf
	s_waitcnt lgkmcnt(0)
	v_add_f32_e32 v96, v96, v97
	s_nop 1
	v_mov_b32_dpp v97, v96 row_ror:8 row_mask:0xf bank_mask:0xf
	s_waitcnt lgkmcnt(0)
	v_add_f32_e32 v96, v96, v97
	v_mov_b32_e32 v97, v96
	s_nop 1
	v_permlane16_swap_b32_e32 v96, v97
	s_waitcnt lgkmcnt(0)
	v_add_f32_e32 v96, v96, v97
	v_mov_b32_e32 v97, v96
	s_nop 1
	v_permlane32_swap_b32_e32 v96, v97
	s_and_saveexec_b64 s[4:5], vcc
	s_cbranch_execz .LBB0_1636
	s_lshl_b64 s[2:3], s[2:3], 5
	s_add_u32 s2, s6, s2
	s_addc_u32 s3, s7, s3
	v_mov_b32_e32 v98, 0
	s_waitcnt lgkmcnt(0)
	v_add_f32_e32 v96, v96, v97
	global_store_dword v98, v96, s[2:3] sc1
; #define LAS __attribute__((address_space(3)))
; __device__ __forceinline__ f32x4 ld_bf4(const bf16_t* p) { u32x2 w = *(const u32x2*)p; return (f32x4){__uint_as_float(w.x << 16), __uint_as_float(w.x & 0xffff0000u), __uint_as_float(w.y << 16), __uint_as_float(w.y & 0xffff0000u)}; }
; __device__ __forceinline__ void st_bf4(bf16_t* p, f32x4 v) { u32x2 w; w.x = pk2(v[0], v[1]); w.y = pk2(v[2], v[3]); *(u32x2*)p = w; }
; __device__ __forceinline__ float wave_sum(float v) {
; #pragma unroll
;     for (int o = 1; o < 64; o <<= 1) v += __shfl_xor(v, o);
;     return v;
; template <int MODOFF, int STORE  , bool BASE_BF16>
; __device__ __forceinline__ void epi_rows_part1(LAS unsigned char* lds, const f32x4 (&acc)[2][2][4][2], const Unit& u, const float* base, const float* mod, float* outp, float* slots, f32x4 (&xr)[2][16]) {
;     ...
;         for (int j = 0; j < 16; ++j) { const int rl = wid * 16 + j, row = u.pm * BM + ai * HALF + rl; const size_t o = (size_t)row * DM + colg;
;             const f32x4 v = *(const LAS f32x4*)(T + rl * 256 + ((lane ^ j) << 2));
;             const f32x4 bs = BASE_BF16 ? ld_bf4((const bf16_t*)base + o) : *(const f32x4*)(base + o);
;             const f32x4 x1 = bs + gt * v; xr[ai][j] = x1; if (STORE == 2) st_bf4((bf16_t*)outp + o, x1);
;             const float sq = wave_sum((x1[0] * x1[0] + x1[1] * x1[1]) + (x1[2] * x1[2] + x1[3] * x1[3]));
;             if (lane == 0) __hip_atomic_store((unsigned*)slots + (size_t)row * 8 + u.pn, __float_as_uint(sq), __ATOMIC_RELAXED, __HIP_MEMORY_SCOPE_AGENT); }
.LBB0_1636:
	s_or_b64 exec, exec, s[4:5]
	s_or_b32 s15, s8, 7
	s_add_i32 s2, s15, s49
	s_ashr_i32 s3, s2, 31
	s_lshl_b64 s[4:5], s[2:3], 11
	v_readlane_b32 s16, v254, 1
	v_lshl_add_u64 v[106:107], s[4:5], 0, v[132:133]
	v_readlane_b32 s17, v254, 2
	s_lshl_b32 s4, s15, 10
	s_add_i32 s4, s4, 0
	s_waitcnt lgkmcnt(0)
	v_lshl_add_u64 v[96:97], v[106:107], 2, s[16:17]
	v_xor_b32_e32 v96, 0x70, v128
	v_add_u32_e32 v145, s4, v96
	ds_read_b128 v[102:105], v145
	v_readlane_b32 s18, v254, 3
	v_readlane_b32 s19, v254, 4
	v_readlane_b32 s20, v254, 5
	v_readlane_b32 s21, v254, 6
	v_readlane_b32 s22, v254, 7
	v_readlane_b32 s23, v254, 8
	v_readlane_b32 s24, v254, 9
	v_readlane_b32 s25, v254, 10
	v_readlane_b32 s26, v254, 11
	v_readlane_b32 s27, v254, 12
	v_readlane_b32 s28, v254, 13
	v_readlane_b32 s29, v254, 14
	v_readlane_b32 s30, v254, 15
	v_readlane_b32 s31, v254, 16
	s_waitcnt vmcnt(22) lgkmcnt(0)
	v_mov_b32_e32 v98, v200
	v_mov_b32_e32 v99, v201
	v_mov_b32_e32 v100, v202
	v_mov_b32_e32 v101, v203
	v_pk_fma_f32 v[96:97], v[2:3], v[104:105], v[100:101]
	v_pk_fma_f32 v[98:99], v[0:1], v[102:103], v[98:99]
	v_mul_f32_e32 v101, v97, v97
	v_mul_f32_e32 v100, v99, v99
	v_fmac_f32_e32 v100, v98, v98
	v_fmac_f32_e32 v101, v96, v96
	v_add_f32_e32 v100, v100, v101
	s_nop 1
	v_mov_b32_dpp v101, v100 quad_perm:[1,0,3,2] row_mask:0xf bank_mask:0xf
	v_lshl_add_u64 v[102:103], v[106:107], 1, s[64:65]
	v_cvt_pk_bf16_f32 v104, v98, v99
	v_cvt_pk_bf16_f32 v105, v96, v97
	global_store_dwordx2 v[102:103], v[104:105], off
	s_waitcnt lgkmcnt(0)
	v_add_f32_e32 v100, v100, v101
	s_nop 1
	v_mov_b32_dpp v101, v100 quad_perm:[2,3,0,1] row_mask:0xf bank_mask:0xf
	s_waitcnt lgkmcnt(0)
	v_add_f32_e32 v100, v100, v101
	s_nop 1
	v_mov_b32_dpp v101, v100 row_ror:12 row_mask:0xf bank_mask:0xf
	s_waitcnt lgkmcnt(0)
	v_add_f32_e32 v100, v100, v101
	s_nop 1
	v_mov_b32_dpp v101, v100 row_ror:8 row_mask:0xf bank_mask:0xf
	s_waitcnt lgkmcnt(0)
	v_add_f32_e32 v100, v100, v101
	v_mov_b32_e32 v101, v100
	s_nop 1
	v_permlane16_swap_b32_e32 v100, v101
	s_waitcnt lgkmcnt(0)
	v_add_f32_e32 v100, v100, v101
	v_mov_b32_e32 v101, v100
	s_nop 1
	v_permlane32_swap_b32_e32 v100, v101
	s_and_saveexec_b64 s[4:5], vcc
	s_cbranch_execz .LBB0_1638
	s_lshl_b64 s[2:3], s[2:3], 5
	s_add_u32 s2, s6, s2
	s_addc_u32 s3, s7, s3
	v_mov_b32_e32 v102, 0
	s_waitcnt lgkmcnt(0)
	v_add_f32_e32 v100, v100, v101
	global_store_dword v102, v100, s[2:3] sc1
.LBB0_1638:
	s_or_b64 exec, exec, s[4:5]
	s_or_b32 s16, s8, 8
	s_add_i32 s2, s16, s49
	s_ashr_i32 s3, s2, 31
	s_lshl_b64 s[4:5], s[2:3], 11
	v_readlane_b32 s72, v254, 1
	v_lshl_add_u64 v[110:111], s[4:5], 0, v[132:133]
	v_readlane_b32 s73, v254, 2
	s_lshl_b32 s4, s16, 10
	s_add_i32 s4, s4, 0
	s_waitcnt lgkmcnt(0)
	v_lshl_add_u64 v[100:101], v[110:111], 2, s[72:73]
	v_xor_b32_e32 v100, 0x80, v128
	v_add_u32_e32 v146, s4, v100
	ds_read_b128 v[106:109], v146
	v_readlane_b32 s74, v254, 3
	v_readlane_b32 s75, v254, 4
	v_readlane_b32 s76, v254, 5
	v_readlane_b32 s77, v254, 6
	v_readlane_b32 s78, v254, 7
	v_readlane_b32 s79, v254, 8
	v_readlane_b32 s80, v254, 9
	v_readlane_b32 s81, v254, 10
	v_readlane_b32 s82, v254, 11
	v_readlane_b32 s83, v254, 12
	v_readlane_b32 s84, v254, 13
	v_readlane_b32 s85, v254, 14
	v_readlane_b32 s86, v254, 15
	v_readlane_b32 s87, v254, 16
	s_waitcnt vmcnt(23) lgkmcnt(0)
	v_mov_b32_e32 v102, v204
	v_mov_b32_e32 v103, v205
	v_mov_b32_e32 v104, v206
	v_mov_b32_e32 v105, v207
	v_pk_fma_f32 v[100:101], v[2:3], v[108:109], v[104:105]
	v_pk_fma_f32 v[102:103], v[0:1], v[106:107], v[102:103]
	v_mul_f32_e32 v105, v101, v101
	v_mul_f32_e32 v104, v103, v103
	v_fmac_f32_e32 v104, v102, v102
	v_fmac_f32_e32 v105, v100, v100
	v_add_f32_e32 v104, v104, v105
	s_nop 1
	v_mov_b32_dpp v105, v104 quad_perm:[1,0,3,2] row_mask:0xf bank_mask:0xf
	v_lshl_add_u64 v[106:107], v[110:111], 1, s[64:65]
	v_cvt_pk_bf16_f32 v108, v102, v103
	v_cvt_pk_bf16_f32 v109, v100, v101
	global_store_dwordx2 v[106:107], v[108:109], off
	s_waitcnt lgkmcnt(0)
	v_add_f32_e32 v104, v104, v105
	s_nop 1
	v_mov_b32_dpp v105, v104 quad_perm:[2,3,0,1] row_mask:0xf bank_mask:0xf
	s_waitcnt lgkmcnt(0)
	v_add_f32_e32 v104, v104, v105
	s_nop 1
	v_mov_b32_dpp v105, v104 row_ror:12 row_mask:0xf bank_mask:0xf
	s_waitcnt lgkmcnt(0)
	v_add_f32_e32 v104, v104, v105
	s_nop 1
	v_mov_b32_dpp v105, v104 row_ror:8 row_mask:0xf bank_mask:0xf
	s_waitcnt lgkmcnt(0)
	v_add_f32_e32 v104, v104, v105
	v_mov_b32_e32 v105, v104
	s_nop 1
	v_permlane16_swap_b32_e32 v104, v105
	s_waitcnt lgkmcnt(0)
	v_add_f32_e32 v104, v104, v105
	v_mov_b32_e32 v105, v104
	s_nop 1
	v_permlane32_swap_b32_e32 v104, v105
	s_and_saveexec_b64 s[4:5], vcc
	s_cbranch_execz .LBB0_1640
	s_lshl_b64 s[2:3], s[2:3], 5
	s_add_u32 s2, s6, s2
	s_addc_u32 s3, s7, s3
	v_mov_b32_e32 v106, 0
	s_waitcnt lgkmcnt(0)
	v_add_f32_e32 v104, v104, v105
	global_store_dword v106, v104, s[2:3] sc1
; #define LAS __attribute__((address_space(3)))
; __device__ __forceinline__ f32x4 ld_bf4(const bf16_t* p) { u32x2 w = *(const u32x2*)p; return (f32x4){__uint_as_float(w.x << 16), __uint_as_float(w.x & 0xffff0000u), __uint_as_float(w.y << 16), __uint_as_float(w.y & 0xffff0000u)}; }
; __device__ __forceinline__ void st_bf4(bf16_t* p, f32x4 v) { u32x2 w; w.x = pk2(v[0], v[1]); w.y = pk2(v[2], v[3]); *(u32x2*)p = w; }
; __device__ __forceinline__ float wave_sum(float v) {
; #pragma unroll
;     for (int o = 1; o < 64; o <<= 1) v += __shfl_xor(v, o);
;     return v;
; template <int MODOFF, int STORE  , bool BASE_BF16>
; __device__ __forceinline__ void epi_rows_part1(LAS unsigned char* lds, const f32x4 (&acc)[2][2][4][2], const Unit& u, const float* base, const float* mod, float* outp, float* slots, f32x4 (&xr)[2][16]) {
;     ...
;         for (int j = 0; j < 16; ++j) { const int rl = wid * 16 + j, row = u.pm * BM + ai * HALF + rl; const size_t o = (size_t)row * DM + colg;
;             const f32x4 v = *(const LAS f32x4*)(T + rl * 256 + ((lane ^ j) << 2));
;             const f32x4 bs = BASE_BF16 ? ld_bf4((const bf16_t*)base + o) : *(const f32x4*)(base + o);
;             const f32x4 x1 = bs + gt * v; xr[ai][j] = x1; if (STORE == 2) st_bf4((bf16_t*)outp + o, x1);
;             const float sq = wave_sum((x1[0] * x1[0] + x1[1] * x1[1]) + (x1[2] * x1[2] + x1[3] * x1[3]));
;             if (lane == 0) __hip_atomic_store((unsigned*)slots + (size_t)row * 8 + u.pn, __float_as_uint(sq), __ATOMIC_RELAXED, __HIP_MEMORY_SCOPE_AGENT); }
.LBB0_1640:
	s_or_b64 exec, exec, s[4:5]
	s_or_b32 s17, s8, 9
	s_add_i32 s2, s17, s49
	s_ashr_i32 s3, s2, 31
	s_lshl_b64 s[4:5], s[2:3], 11
	v_readlane_b32 s72, v254, 1
	v_lshl_add_u64 v[114:115], s[4:5], 0, v[132:133]
	v_readlane_b32 s73, v254, 2
	s_lshl_b32 s4, s17, 10
	s_add_i32 s4, s4, 0
	s_waitcnt lgkmcnt(0)
	v_lshl_add_u64 v[104:105], v[114:115], 2, s[72:73]
	v_xor_b32_e32 v104, 0x90, v128
	v_add_u32_e32 v147, s4, v104
	ds_read_b128 v[110:113], v147
	v_readlane_b32 s74, v254, 3
	v_readlane_b32 s75, v254, 4
	v_readlane_b32 s76, v254, 5
	v_readlane_b32 s77, v254, 6
	v_readlane_b32 s78, v254, 7
	v_readlane_b32 s79, v254, 8
	v_readlane_b32 s80, v254, 9
	v_readlane_b32 s81, v254, 10
	v_readlane_b32 s82, v254, 11
	v_readlane_b32 s83, v254, 12
	v_readlane_b32 s84, v254, 13
	v_readlane_b32 s85, v254, 14
	v_readlane_b32 s86, v254, 15
	v_readlane_b32 s87, v254, 16
	s_waitcnt vmcnt(24) lgkmcnt(0)
	v_mov_b32_e32 v106, v208
	v_mov_b32_e32 v107, v209
	v_mov_b32_e32 v108, v210
	v_mov_b32_e32 v109, v211
	v_pk_fma_f32 v[104:105], v[2:3], v[112:113], v[108:109]
	v_pk_fma_f32 v[106:107], v[0:1], v[110:111], v[106:107]
	v_mul_f32_e32 v109, v105, v105
	v_mul_f32_e32 v108, v107, v107
	v_fmac_f32_e32 v108, v106, v106
	v_fmac_f32_e32 v109, v104, v104
	v_add_f32_e32 v108, v108, v109
	s_nop 1
	v_mov_b32_dpp v109, v108 quad_perm:[1,0,3,2] row_mask:0xf bank_mask:0xf
	v_lshl_add_u64 v[110:111], v[114:115], 1, s[64:65]
	v_cvt_pk_bf16_f32 v112, v106, v107
	v_cvt_pk_bf16_f32 v113, v104, v105
	global_store_dwordx2 v[110:111], v[112:113], off
	s_waitcnt lgkmcnt(0)
	v_add_f32_e32 v108, v108, v109
	s_nop 1
	v_mov_b32_dpp v109, v108 quad_perm:[2,3,0,1] row_mask:0xf bank_mask:0xf
	s_waitcnt lgkmcnt(0)
	v_add_f32_e32 v108, v108, v109
	s_nop 1
	v_mov_b32_dpp v109, v108 row_ror:12 row_mask:0xf bank_mask:0xf
	s_waitcnt lgkmcnt(0)
	v_add_f32_e32 v108, v108, v109
	s_nop 1
	v_mov_b32_dpp v109, v108 row_ror:8 row_mask:0xf bank_mask:0xf
	s_waitcnt lgkmcnt(0)
	v_add_f32_e32 v108, v108, v109
	v_mov_b32_e32 v109, v108
	s_nop 1
	v_permlane16_swap_b32_e32 v108, v109
	s_waitcnt lgkmcnt(0)
	v_add_f32_e32 v108, v108, v109
	v_mov_b32_e32 v109, v108
	s_nop 1
	v_permlane32_swap_b32_e32 v108, v109
	s_and_saveexec_b64 s[4:5], vcc
	s_cbranch_execz .LBB0_1642
	s_lshl_b64 s[2:3], s[2:3], 5
	s_add_u32 s2, s6, s2
	s_addc_u32 s3, s7, s3
	v_mov_b32_e32 v110, 0
	s_waitcnt lgkmcnt(0)
	v_add_f32_e32 v108, v108, v109
	global_store_dword v110, v108, s[2:3] sc1
.LBB0_1642:
	s_or_b64 exec, exec, s[4:5]
	s_or_b32 s18, s8, 10
	s_add_i32 s2, s18, s49
	s_ashr_i32 s3, s2, 31
	s_lshl_b64 s[4:5], s[2:3], 11
	v_readlane_b32 s72, v254, 1
	v_lshl_add_u64 v[118:119], s[4:5], 0, v[132:133]
	v_readlane_b32 s73, v254, 2
	s_lshl_b32 s4, s18, 10
	s_add_i32 s4, s4, 0
	s_waitcnt lgkmcnt(0)
	v_lshl_add_u64 v[108:109], v[118:119], 2, s[72:73]
	v_xor_b32_e32 v108, 0xa0, v128
	v_add_u32_e32 v148, s4, v108
	ds_read_b128 v[114:117], v148
	v_readlane_b32 s74, v254, 3
	v_readlane_b32 s75, v254, 4
	v_readlane_b32 s76, v254, 5
	v_readlane_b32 s77, v254, 6
	v_readlane_b32 s78, v254, 7
	v_readlane_b32 s79, v254, 8
	v_readlane_b32 s80, v254, 9
	v_readlane_b32 s81, v254, 10
	v_readlane_b32 s82, v254, 11
	v_readlane_b32 s83, v254, 12
	v_readlane_b32 s84, v254, 13
	v_readlane_b32 s85, v254, 14
	v_readlane_b32 s86, v254, 15
	v_readlane_b32 s87, v254, 16
	s_waitcnt vmcnt(25) lgkmcnt(0)
	v_mov_b32_e32 v110, v212
	v_mov_b32_e32 v111, v213
	v_mov_b32_e32 v112, v214
	v_mov_b32_e32 v113, v215
	v_pk_fma_f32 v[108:109], v[2:3], v[116:117], v[112:113]
	v_pk_fma_f32 v[110:111], v[0:1], v[114:115], v[110:111]
	v_mul_f32_e32 v113, v109, v109
	v_mul_f32_e32 v112, v111, v111
	v_fmac_f32_e32 v112, v110, v110
	v_fmac_f32_e32 v113, v108, v108
	v_add_f32_e32 v112, v112, v113
	s_nop 1
	v_mov_b32_dpp v113, v112 quad_perm:[1,0,3,2] row_mask:0xf bank_mask:0xf
	v_lshl_add_u64 v[114:115], v[118:119], 1, s[64:65]
	v_cvt_pk_bf16_f32 v116, v110, v111
	v_cvt_pk_bf16_f32 v117, v108, v109
	global_store_dwordx2 v[114:115], v[116:117], off
	s_waitcnt lgkmcnt(0)
	v_add_f32_e32 v112, v112, v113
	s_nop 1
	v_mov_b32_dpp v113, v112 quad_perm:[2,3,0,1] row_mask:0xf bank_mask:0xf
	s_waitcnt lgkmcnt(0)
	v_add_f32_e32 v112, v112, v113
	s_nop 1
	v_mov_b32_dpp v113, v112 row_ror:12 row_mask:0xf bank_mask:0xf
	s_waitcnt lgkmcnt(0)
	v_add_f32_e32 v112, v112, v113
	s_nop 1
	v_mov_b32_dpp v113, v112 row_ror:8 row_mask:0xf bank_mask:0xf
	s_waitcnt lgkmcnt(0)
	v_add_f32_e32 v112, v112, v113
	v_mov_b32_e32 v113, v112
	s_nop 1
	v_permlane16_swap_b32_e32 v112, v113
	s_waitcnt lgkmcnt(0)
	v_add_f32_e32 v112, v112, v113
	v_mov_b32_e32 v113, v112
	s_nop 1
	v_permlane32_swap_b32_e32 v112, v113
	s_and_saveexec_b64 s[4:5], vcc
	s_cbranch_execz .LBB0_1644
	s_lshl_b64 s[2:3], s[2:3], 5
	s_add_u32 s2, s6, s2
	s_addc_u32 s3, s7, s3
	v_mov_b32_e32 v114, 0
	s_waitcnt lgkmcnt(0)
	v_add_f32_e32 v112, v112, v113
	global_store_dword v114, v112, s[2:3] sc1
; #define LAS __attribute__((address_space(3)))
; __device__ __forceinline__ f32x4 ld_bf4(const bf16_t* p) { u32x2 w = *(const u32x2*)p; return (f32x4){__uint_as_float(w.x << 16), __uint_as_float(w.x & 0xffff0000u), __uint_as_float(w.y << 16), __uint_as_float(w.y & 0xffff0000u)}; }
; __device__ __forceinline__ void st_bf4(bf16_t* p, f32x4 v) { u32x2 w; w.x = pk2(v[0], v[1]); w.y = pk2(v[2], v[3]); *(u32x2*)p = w; }
; __device__ __forceinline__ float wave_sum(float v) {
; #pragma unroll
;     for (int o = 1; o < 64; o <<= 1) v += __shfl_xor(v, o);
;     return v;
; template <int MODOFF, int STORE  , bool BASE_BF16>
; __device__ __forceinline__ void epi_rows_part1(LAS unsigned char* lds, const f32x4 (&acc)[2][2][4][2], const Unit& u, const float* base, const float* mod, float* outp, float* slots, f32x4 (&xr)[2][16]) {
;     ...
;         for (int j = 0; j < 16; ++j) { const int rl = wid * 16 + j, row = u.pm * BM + ai * HALF + rl; const size_t o = (size_t)row * DM + colg;
;             const f32x4 v = *(const LAS f32x4*)(T + rl * 256 + ((lane ^ j) << 2));
;             const f32x4 bs = BASE_BF16 ? ld_bf4((const bf16_t*)base + o) : *(const f32x4*)(base + o);
;             const f32x4 x1 = bs + gt * v; xr[ai][j] = x1; if (STORE == 2) st_bf4((bf16_t*)outp + o, x1);
;             const float sq = wave_sum((x1[0] * x1[0] + x1[1] * x1[1]) + (x1[2] * x1[2] + x1[3] * x1[3]));
;             if (lane == 0) __hip_atomic_store((unsigned*)slots + (size_t)row * 8 + u.pn, __float_as_uint(sq), __ATOMIC_RELAXED, __HIP_MEMORY_SCOPE_AGENT); }
.LBB0_1644:
	s_or_b64 exec, exec, s[4:5]
	s_or_b32 s19, s8, 11
	s_add_i32 s2, s19, s49
	s_ashr_i32 s3, s2, 31
	s_lshl_b64 s[4:5], s[2:3], 11
	v_readlane_b32 s72, v254, 1
	v_lshl_add_u64 v[122:123], s[4:5], 0, v[132:133]
	v_readlane_b32 s73, v254, 2
	s_lshl_b32 s4, s19, 10
	s_add_i32 s4, s4, 0
	s_waitcnt lgkmcnt(0)
	v_lshl_add_u64 v[112:113], v[122:123], 2, s[72:73]
	v_xor_b32_e32 v112, 0xb0, v128
	v_add_u32_e32 v149, s4, v112
	ds_read_b128 v[118:121], v149
	v_readlane_b32 s74, v254, 3
	v_readlane_b32 s75, v254, 4
	v_readlane_b32 s76, v254, 5
	v_readlane_b32 s77, v254, 6
	v_readlane_b32 s78, v254, 7
	v_readlane_b32 s79, v254, 8
	v_readlane_b32 s80, v254, 9
	v_readlane_b32 s81, v254, 10
	v_readlane_b32 s82, v254, 11
	v_readlane_b32 s83, v254, 12
	v_readlane_b32 s84, v254, 13
	v_readlane_b32 s85, v254, 14
	v_readlane_b32 s86, v254, 15
	v_readlane_b32 s87, v254, 16
	s_waitcnt vmcnt(26) lgkmcnt(0)
	v_mov_b32_e32 v114, v216
	v_mov_b32_e32 v115, v217
	v_mov_b32_e32 v116, v218
	v_mov_b32_e32 v117, v219
	v_pk_fma_f32 v[112:113], v[2:3], v[120:121], v[116:117]
	v_pk_fma_f32 v[114:115], v[0:1], v[118:119], v[114:115]
	v_mul_f32_e32 v117, v113, v113
	v_mul_f32_e32 v116, v115, v115
	v_fmac_f32_e32 v116, v114, v114
	v_fmac_f32_e32 v117, v112, v112
	v_add_f32_e32 v116, v116, v117
	s_nop 1
	v_mov_b32_dpp v117, v116 quad_perm:[1,0,3,2] row_mask:0xf bank_mask:0xf
	v_lshl_add_u64 v[118:119], v[122:123], 1, s[64:65]
	v_cvt_pk_bf16_f32 v120, v114, v115
	v_cvt_pk_bf16_f32 v121, v112, v113
	global_store_dwordx2 v[118:119], v[120:121], off
	s_waitcnt lgkmcnt(0)
	v_add_f32_e32 v116, v116, v117
	s_nop 1
	v_mov_b32_dpp v117, v116 quad_perm:[2,3,0,1] row_mask:0xf bank_mask:0xf
	s_waitcnt lgkmcnt(0)
	v_add_f32_e32 v116, v116, v117
	s_nop 1
	v_mov_b32_dpp v117, v116 row_ror:12 row_mask:0xf bank_mask:0xf
	s_waitcnt lgkmcnt(0)
	v_add_f32_e32 v116, v116, v117
	s_nop 1
	v_mov_b32_dpp v117, v116 row_ror:8 row_mask:0xf bank_mask:0xf
	s_waitcnt lgkmcnt(0)
	v_add_f32_e32 v116, v116, v117
	v_mov_b32_e32 v117, v116
	s_nop 1
	v_permlane16_swap_b32_e32 v116, v117
	s_waitcnt lgkmcnt(0)
	v_add_f32_e32 v116, v116, v117
	v_mov_b32_e32 v117, v116
	s_nop 1
	v_permlane32_swap_b32_e32 v116, v117
	s_and_saveexec_b64 s[4:5], vcc
	s_cbranch_execz .LBB0_1646
	s_lshl_b64 s[2:3], s[2:3], 5
	s_add_u32 s2, s6, s2
	s_addc_u32 s3, s7, s3
	v_mov_b32_e32 v118, 0
	s_waitcnt lgkmcnt(0)
	v_add_f32_e32 v116, v116, v117
	global_store_dword v118, v116, s[2:3] sc1
.LBB0_1646:
	s_or_b64 exec, exec, s[4:5]
	s_or_b32 s20, s8, 12
	s_add_i32 s2, s20, s49
	s_ashr_i32 s3, s2, 31
	s_lshl_b64 s[4:5], s[2:3], 11
	v_readlane_b32 s72, v254, 1
	v_lshl_add_u64 v[126:127], s[4:5], 0, v[132:133]
	v_readlane_b32 s73, v254, 2
	s_lshl_b32 s4, s20, 10
	s_add_i32 s4, s4, 0
	s_waitcnt lgkmcnt(0)
	v_lshl_add_u64 v[116:117], v[126:127], 2, s[72:73]
	v_xor_b32_e32 v116, 0xc0, v128
	v_add_u32_e32 v150, s4, v116
	ds_read_b128 v[122:125], v150
	v_readlane_b32 s74, v254, 3
	v_readlane_b32 s75, v254, 4
	v_readlane_b32 s76, v254, 5
	v_readlane_b32 s77, v254, 6
	v_readlane_b32 s78, v254, 7
	v_readlane_b32 s79, v254, 8
	v_readlane_b32 s80, v254, 9
	v_readlane_b32 s81, v254, 10
	v_readlane_b32 s82, v254, 11
	v_readlane_b32 s83, v254, 12
	v_readlane_b32 s84, v254, 13
	v_readlane_b32 s85, v254, 14
	v_readlane_b32 s86, v254, 15
	v_readlane_b32 s87, v254, 16
	s_waitcnt vmcnt(27) lgkmcnt(0)
	v_mov_b32_e32 v118, v220
	v_mov_b32_e32 v119, v221
	v_mov_b32_e32 v120, v222
	v_mov_b32_e32 v121, v223
	v_pk_fma_f32 v[116:117], v[2:3], v[124:125], v[120:121]
	v_pk_fma_f32 v[118:119], v[0:1], v[122:123], v[118:119]
	v_mul_f32_e32 v121, v117, v117
	v_mul_f32_e32 v120, v119, v119
	v_fmac_f32_e32 v120, v118, v118
	v_fmac_f32_e32 v121, v116, v116
	v_add_f32_e32 v120, v120, v121
	s_nop 1
	v_mov_b32_dpp v121, v120 quad_perm:[1,0,3,2] row_mask:0xf bank_mask:0xf
	v_lshl_add_u64 v[122:123], v[126:127], 1, s[64:65]
	v_cvt_pk_bf16_f32 v124, v118, v119
	v_cvt_pk_bf16_f32 v125, v116, v117
	global_store_dwordx2 v[122:123], v[124:125], off
	s_waitcnt lgkmcnt(0)
	v_add_f32_e32 v120, v120, v121
	s_nop 1
	v_mov_b32_dpp v121, v120 quad_perm:[2,3,0,1] row_mask:0xf bank_mask:0xf
	s_waitcnt lgkmcnt(0)
	v_add_f32_e32 v120, v120, v121
	s_nop 1
	v_mov_b32_dpp v121, v120 row_ror:12 row_mask:0xf bank_mask:0xf
	s_waitcnt lgkmcnt(0)
	v_add_f32_e32 v120, v120, v121
	s_nop 1
	v_mov_b32_dpp v121, v120 row_ror:8 row_mask:0xf bank_mask:0xf
	s_waitcnt lgkmcnt(0)
	v_add_f32_e32 v120, v120, v121
	v_mov_b32_e32 v121, v120
	s_nop 1
	v_permlane16_swap_b32_e32 v120, v121
	s_waitcnt lgkmcnt(0)
	v_add_f32_e32 v120, v120, v121
	v_mov_b32_e32 v121, v120
	s_nop 1
	v_permlane32_swap_b32_e32 v120, v121
	s_and_saveexec_b64 s[4:5], vcc
	s_cbranch_execz .LBB0_1648
	s_lshl_b64 s[2:3], s[2:3], 5
	s_add_u32 s2, s6, s2
	s_addc_u32 s3, s7, s3
	v_mov_b32_e32 v122, 0
	s_waitcnt lgkmcnt(0)
	v_add_f32_e32 v120, v120, v121
	global_store_dword v122, v120, s[2:3] sc1
; #define LAS __attribute__((address_space(3)))
; __device__ __forceinline__ f32x4 ld_bf4(const bf16_t* p) { u32x2 w = *(const u32x2*)p; return (f32x4){__uint_as_float(w.x << 16), __uint_as_float(w.x & 0xffff0000u), __uint_as_float(w.y << 16), __uint_as_float(w.y & 0xffff0000u)}; }
; __device__ __forceinline__ void st_bf4(bf16_t* p, f32x4 v) { u32x2 w; w.x = pk2(v[0], v[1]); w.y = pk2(v[2], v[3]); *(u32x2*)p = w; }
; __device__ __forceinline__ float wave_sum(float v) {
; #pragma unroll
;     for (int o = 1; o < 64; o <<= 1) v += __shfl_xor(v, o);
;     return v;
; template <int MODOFF, int STORE  , bool BASE_BF16>
; __device__ __forceinline__ void epi_rows_part1(LAS unsigned char* lds, const f32x4 (&acc)[2][2][4][2], const Unit& u, const float* base, const float* mod, float* outp, float* slots, f32x4 (&xr)[2][16]) {
;     ...
;         for (int j = 0; j < 16; ++j) { const int rl = wid * 16 + j, row = u.pm * BM + ai * HALF + rl; const size_t o = (size_t)row * DM + colg;
;             const f32x4 v = *(const LAS f32x4*)(T + rl * 256 + ((lane ^ j) << 2));
;             const f32x4 bs = BASE_BF16 ? ld_bf4((const bf16_t*)base + o) : *(const f32x4*)(base + o);
;             const f32x4 x1 = bs + gt * v; xr[ai][j] = x1; if (STORE == 2) st_bf4((bf16_t*)outp + o, x1);
;             const float sq = wave_sum((x1[0] * x1[0] + x1[1] * x1[1]) + (x1[2] * x1[2] + x1[3] * x1[3]));
;             if (lane == 0) __hip_atomic_store((unsigned*)slots + (size_t)row * 8 + u.pn, __float_as_uint(sq), __ATOMIC_RELAXED, __HIP_MEMORY_SCOPE_AGENT); }
.LBB0_1648:
	s_or_b64 exec, exec, s[4:5]
	s_or_b32 s21, s8, 13
	s_add_i32 s2, s21, s49
	s_ashr_i32 s3, s2, 31
	s_lshl_b64 s[4:5], s[2:3], 11
	v_readlane_b32 s72, v254, 1
	v_lshl_add_u64 v[126:127], s[4:5], 0, v[132:133]
	v_readlane_b32 s73, v254, 2
	s_lshl_b32 s4, s21, 10
	s_add_i32 s4, s4, 0
	s_waitcnt lgkmcnt(0)
	v_lshl_add_u64 v[120:121], v[126:127], 2, s[72:73]
	v_xor_b32_e32 v120, 0xd0, v128
	v_add_u32_e32 v151, s4, v120
	ds_read_b128 v[152:155], v151
	v_lshl_add_u64 v[126:127], v[126:127], 1, s[64:65]
	v_readlane_b32 s74, v254, 3
	v_readlane_b32 s75, v254, 4
	v_readlane_b32 s76, v254, 5
	v_readlane_b32 s77, v254, 6
	v_readlane_b32 s78, v254, 7
	v_readlane_b32 s79, v254, 8
	v_readlane_b32 s80, v254, 9
	v_readlane_b32 s81, v254, 10
	v_readlane_b32 s82, v254, 11
	v_readlane_b32 s83, v254, 12
	v_readlane_b32 s84, v254, 13
	v_readlane_b32 s85, v254, 14
	v_readlane_b32 s86, v254, 15
	v_readlane_b32 s87, v254, 16
	s_waitcnt vmcnt(28) lgkmcnt(0)
	v_mov_b32_e32 v122, v224
	v_mov_b32_e32 v123, v225
	v_mov_b32_e32 v124, v226
	v_mov_b32_e32 v125, v227
	v_pk_fma_f32 v[120:121], v[2:3], v[154:155], v[124:125]
	v_pk_fma_f32 v[122:123], v[0:1], v[152:153], v[122:123]
	v_mul_f32_e32 v125, v121, v121
	v_mul_f32_e32 v124, v123, v123
	v_fmac_f32_e32 v124, v122, v122
	v_fmac_f32_e32 v125, v120, v120
	v_add_f32_e32 v124, v124, v125
	s_nop 1
	v_mov_b32_dpp v125, v124 quad_perm:[1,0,3,2] row_mask:0xf bank_mask:0xf
	v_cvt_pk_bf16_f32 v130, v122, v123
	v_cvt_pk_bf16_f32 v131, v120, v121
	global_store_dwordx2 v[126:127], v[130:131], off
	s_waitcnt lgkmcnt(0)
	v_add_f32_e32 v124, v124, v125
	s_nop 1
	v_mov_b32_dpp v125, v124 quad_perm:[2,3,0,1] row_mask:0xf bank_mask:0xf
	s_waitcnt lgkmcnt(0)
	v_add_f32_e32 v124, v124, v125
	s_nop 1
	v_mov_b32_dpp v125, v124 row_ror:12 row_mask:0xf bank_mask:0xf
	s_waitcnt lgkmcnt(0)
	v_add_f32_e32 v124, v124, v125
	s_nop 1
	v_mov_b32_dpp v125, v124 row_ror:8 row_mask:0xf bank_mask:0xf
	s_waitcnt lgkmcnt(0)
	v_add_f32_e32 v124, v124, v125
	v_mov_b32_e32 v125, v124
	s_nop 1
	v_permlane16_swap_b32_e32 v124, v125
	s_waitcnt lgkmcnt(0)
	v_add_f32_e32 v124, v124, v125
	v_mov_b32_e32 v125, v124
	s_nop 1
	v_permlane32_swap_b32_e32 v124, v125
	s_and_saveexec_b64 s[4:5], vcc
	s_cbranch_execz .LBB0_1650
	s_lshl_b64 s[2:3], s[2:3], 5
	s_add_u32 s2, s6, s2
	s_addc_u32 s3, s7, s3
	v_mov_b32_e32 v126, 0
	s_waitcnt lgkmcnt(0)
	v_add_f32_e32 v124, v124, v125
	global_store_dword v126, v124, s[2:3] sc1
.LBB0_1650:
	s_or_b64 exec, exec, s[4:5]
	s_or_b32 s22, s8, 14
	s_add_i32 s2, s22, s49
	s_ashr_i32 s3, s2, 31
	s_lshl_b64 s[4:5], s[2:3], 11
	v_readlane_b32 s72, v254, 1
	v_lshl_add_u64 v[162:163], s[4:5], 0, v[132:133]
	v_readlane_b32 s73, v254, 2
	s_lshl_b32 s4, s22, 10
	s_add_i32 s4, s4, 0
	s_waitcnt lgkmcnt(0)
	v_lshl_add_u64 v[124:125], v[162:163], 2, s[72:73]
	v_xor_b32_e32 v124, 0xe0, v128
	v_add_u32_e32 v152, s4, v124
	ds_read_b128 v[158:161], v152
	v_readlane_b32 s74, v254, 3
	v_readlane_b32 s75, v254, 4
	v_readlane_b32 s76, v254, 5
	v_readlane_b32 s77, v254, 6
	v_readlane_b32 s78, v254, 7
	v_readlane_b32 s79, v254, 8
	v_readlane_b32 s80, v254, 9
	v_readlane_b32 s81, v254, 10
	v_readlane_b32 s82, v254, 11
	v_readlane_b32 s83, v254, 12
	v_readlane_b32 s84, v254, 13
	v_readlane_b32 s85, v254, 14
	v_readlane_b32 s86, v254, 15
	v_readlane_b32 s87, v254, 16
	s_waitcnt vmcnt(29) lgkmcnt(0)
	v_mov_b32_e32 v154, v228
	v_mov_b32_e32 v155, v229
	v_mov_b32_e32 v156, v230
	v_mov_b32_e32 v157, v231
	v_pk_fma_f32 v[124:125], v[2:3], v[160:161], v[156:157]
	v_pk_fma_f32 v[126:127], v[0:1], v[158:159], v[154:155]
	v_mul_f32_e32 v130, v125, v125
	v_mul_f32_e32 v129, v127, v127
	v_fmac_f32_e32 v129, v126, v126
	v_fmac_f32_e32 v130, v124, v124
	v_add_f32_e32 v129, v129, v130
	s_nop 1
	v_mov_b32_dpp v130, v129 quad_perm:[1,0,3,2] row_mask:0xf bank_mask:0xf
	v_lshl_add_u64 v[154:155], v[162:163], 1, s[64:65]
	v_cvt_pk_bf16_f32 v156, v126, v127
	v_cvt_pk_bf16_f32 v157, v124, v125
	global_store_dwordx2 v[154:155], v[156:157], off
	s_waitcnt lgkmcnt(0)
	v_add_f32_e32 v129, v129, v130
	s_nop 1
	v_mov_b32_dpp v130, v129 quad_perm:[2,3,0,1] row_mask:0xf bank_mask:0xf
	s_waitcnt lgkmcnt(0)
	v_add_f32_e32 v129, v129, v130
	s_nop 1
	v_mov_b32_dpp v130, v129 row_ror:12 row_mask:0xf bank_mask:0xf
	s_waitcnt lgkmcnt(0)
	v_add_f32_e32 v129, v129, v130
	s_nop 1
	v_mov_b32_dpp v130, v129 row_ror:8 row_mask:0xf bank_mask:0xf
	s_waitcnt lgkmcnt(0)
	v_add_f32_e32 v129, v129, v130
	v_mov_b32_e32 v130, v129
	s_nop 1
	v_permlane16_swap_b32_e32 v129, v130
	s_waitcnt lgkmcnt(0)
	v_add_f32_e32 v129, v129, v130
	v_mov_b32_e32 v130, v129
	s_nop 1
	v_permlane32_swap_b32_e32 v129, v130
	s_and_saveexec_b64 s[4:5], vcc
	s_cbranch_execz .LBB0_1652
	s_lshl_b64 s[2:3], s[2:3], 5
	s_add_u32 s2, s6, s2
	s_addc_u32 s3, s7, s3
	v_mov_b32_e32 v131, 0
	s_waitcnt lgkmcnt(0)
	v_add_f32_e32 v129, v129, v130
	global_store_dword v131, v129, s[2:3] sc1
; #define LAS __attribute__((address_space(3)))
; __device__ __forceinline__ f32x4 ld_bf4(const bf16_t* p) { u32x2 w = *(const u32x2*)p; return (f32x4){__uint_as_float(w.x << 16), __uint_as_float(w.x & 0xffff0000u), __uint_as_float(w.y << 16), __uint_as_float(w.y & 0xffff0000u)}; }
; __device__ __forceinline__ void st_bf4(bf16_t* p, f32x4 v) { u32x2 w; w.x = pk2(v[0], v[1]); w.y = pk2(v[2], v[3]); *(u32x2*)p = w; }
; #define LBAR() do { asm volatile("s_waitcnt lgkmcnt(0)" ::: "memory"); __builtin_amdgcn_s_barrier(); asm volatile("" ::: "memory"); } while (0)
; template <int MODOFF, int STORE  , bool BASE_BF16>
; __device__ __forceinline__ void epi_rows_part1(LAS unsigned char* lds, const f32x4 (&acc)[2][2][4][2], const Unit& u, const float* base, const float* mod, float* outp, float* slots, f32x4 (&xr)[2][16]) {
;     ...
;     for (int ai = 0; ai < 2; ++ai) {
;         if (ai) LBAR();
; #pragma unroll
;         for (int m = 0; m < 4; ++m)
; #pragma unroll
;             for (int bj = 0; bj < 2; ++bj)
; #pragma unroll
;                 for (int n = 0; n < 2; ++n) { const int rl = wr * 64 + m * 16 + fr, c4 = (bj * HALF + wc * 32 + n * 16 + 4 * fq) >> 2;
;                     *(LAS f32x4*)(T + rl * 256 + ((c4 ^ (rl & 15)) << 2)) = acc[ai][bj][m][n]; }
;         LBAR();
; #pragma unroll
;         for (int j = 0; j < 16; ++j) { const int rl = wid * 16 + j, row = u.pm * BM + ai * HALF + rl; const size_t o = (size_t)row * DM + colg;
;             const f32x4 v = *(const LAS f32x4*)(T + rl * 256 + ((lane ^ j) << 2));
;             const f32x4 bs = BASE_BF16 ? ld_bf4((const bf16_t*)base + o) : *(const f32x4*)(base + o);
;             const f32x4 x1 = bs + gt * v; xr[ai][j] = x1; if (STORE == 2) st_bf4((bf16_t*)outp + o, x1);
;             const float sq = wave_sum((x1[0] * x1[0] + x1[1] * x1[1]) + (x1[2] * x1[2] + x1[3] * x1[3]));
;             if (lane == 0) __hip_atomic_store((unsigned*)slots + (size_t)row * 8 + u.pn, __float_as_uint(sq), __ATOMIC_RELAXED, __HIP_MEMORY_SCOPE_AGENT); }
.LBB0_1652:
	s_or_b64 exec, exec, s[4:5]
	s_or_b32 s23, s8, 15
	s_add_i32 s2, s23, s49
	s_ashr_i32 s3, s2, 31
	s_lshl_b64 s[4:5], s[2:3], 11
	v_readlane_b32 s72, v254, 1
	v_lshl_add_u64 v[162:163], s[4:5], 0, v[132:133]
	v_readlane_b32 s73, v254, 2
	s_lshl_b32 s4, s23, 10
	v_xor_b32_e32 v128, 0xf0, v128
	s_waitcnt lgkmcnt(0)
	v_lshl_add_u64 v[130:131], v[162:163], 2, s[72:73]
	s_add_i32 s4, s4, 0
	v_add_u32_e32 v153, s4, v128
	ds_read_b128 v[158:161], v153
	v_readlane_b32 s74, v254, 3
	v_readlane_b32 s75, v254, 4
	v_readlane_b32 s76, v254, 5
	v_readlane_b32 s77, v254, 6
	v_readlane_b32 s78, v254, 7
	v_readlane_b32 s79, v254, 8
	v_readlane_b32 s80, v254, 9
	v_readlane_b32 s81, v254, 10
	v_readlane_b32 s82, v254, 11
	v_readlane_b32 s83, v254, 12
	v_readlane_b32 s84, v254, 13
	v_readlane_b32 s85, v254, 14
	v_readlane_b32 s86, v254, 15
	v_readlane_b32 s87, v254, 16
	s_waitcnt vmcnt(30) lgkmcnt(0)
	v_mov_b32_e32 v154, v232
	v_mov_b32_e32 v155, v233
	v_mov_b32_e32 v156, v234
	v_mov_b32_e32 v157, v235
	v_pk_fma_f32 v[128:129], v[2:3], v[160:161], v[156:157]
	v_pk_fma_f32 v[130:131], v[0:1], v[158:159], v[154:155]
	v_mul_f32_e32 v155, v129, v129
	v_mul_f32_e32 v154, v131, v131
	v_fmac_f32_e32 v154, v130, v130
	v_fmac_f32_e32 v155, v128, v128
	v_add_f32_e32 v154, v154, v155
	s_nop 1
	v_mov_b32_dpp v155, v154 quad_perm:[1,0,3,2] row_mask:0xf bank_mask:0xf
	v_lshl_add_u64 v[156:157], v[162:163], 1, s[64:65]
	v_cvt_pk_bf16_f32 v158, v130, v131
	v_cvt_pk_bf16_f32 v159, v128, v129
	global_store_dwordx2 v[156:157], v[158:159], off
	s_waitcnt lgkmcnt(0)
	v_add_f32_e32 v154, v154, v155
	s_nop 1
	v_mov_b32_dpp v155, v154 quad_perm:[2,3,0,1] row_mask:0xf bank_mask:0xf
	s_waitcnt lgkmcnt(0)
	v_add_f32_e32 v154, v154, v155
	s_nop 1
	v_mov_b32_dpp v155, v154 row_ror:12 row_mask:0xf bank_mask:0xf
	s_waitcnt lgkmcnt(0)
	v_add_f32_e32 v154, v154, v155
	s_nop 1
	v_mov_b32_dpp v155, v154 row_ror:8 row_mask:0xf bank_mask:0xf
	s_waitcnt lgkmcnt(0)
	v_add_f32_e32 v154, v154, v155
	v_mov_b32_e32 v155, v154
	s_nop 1
	v_permlane16_swap_b32_e32 v154, v155
	s_waitcnt lgkmcnt(0)
	v_add_f32_e32 v154, v154, v155
	v_mov_b32_e32 v155, v154
	s_nop 1
	v_permlane32_swap_b32_e32 v154, v155
	s_and_saveexec_b64 s[4:5], vcc
	s_cbranch_execz .LBB0_1654
	s_lshl_b64 s[2:3], s[2:3], 5
	s_add_u32 s2, s6, s2
	s_addc_u32 s3, s7, s3
	v_mov_b32_e32 v156, 0
	s_waitcnt lgkmcnt(0)
	v_add_f32_e32 v154, v154, v155
	global_store_dword v156, v154, s[2:3] sc1
.LBB0_1654:
	s_or_b64 exec, exec, s[4:5]
	s_or_b32 s24, s49, 0x80
	s_add_i32 s2, s8, s24
	s_ashr_i32 s3, s2, 31
	s_lshl_b64 s[4:5], s[2:3], 11
	v_readlane_b32 s72, v254, 1
	s_waitcnt lgkmcnt(0)
	s_barrier
	ds_write_b128 v134, v[64:67]
	ds_write_b128 v135, v[60:63]
	ds_write_b128 v136, v[56:59]
	ds_write_b128 v137, v[52:55]
	ds_write_b128 v134, v[48:51] offset:16384
	ds_write_b128 v135, v[44:47] offset:16384
	ds_write_b128 v136, v[40:43] offset:16384
	ds_write_b128 v137, v[36:39] offset:16384
	ds_write_b128 v134, v[32:35] offset:32768
	ds_write_b128 v135, v[28:31] offset:32768
	ds_write_b128 v136, v[24:27] offset:32768
	ds_write_b128 v137, v[20:23] offset:32768
	ds_write_b128 v134, v[16:19] offset:49152
	ds_write_b128 v135, v[12:15] offset:49152
	ds_write_b128 v136, v[8:11] offset:49152
	ds_write_b128 v137, v[4:7] offset:49152
	v_lshl_add_u64 v[14:15], s[4:5], 0, v[132:133]
	v_readlane_b32 s73, v254, 2
	s_waitcnt lgkmcnt(0)
	s_barrier
	ds_read_b128 v[10:13], v138
	v_lshl_add_u64 v[4:5], v[14:15], 2, s[72:73]
	s_mov_b64 s[98:99], 0x2000
	global_load_dwordx4 v[164:167], v[4:5], off
	v_lshl_add_u64 v[252:253], v[4:5], 0, s[98:99]
	global_load_dwordx4 v[168:171], v[252:253], off
	v_lshl_add_u64 v[252:253], v[252:253], 0, s[98:99]
	global_load_dwordx4 v[172:175], v[252:253], off
	v_lshl_add_u64 v[252:253], v[252:253], 0, s[98:99]
	global_load_dwordx4 v[176:179], v[252:253], off
	v_lshl_add_u64 v[252:253], v[252:253], 0, s[98:99]
	global_load_dwordx4 v[180:183], v[252:253], off
	v_lshl_add_u64 v[252:253], v[252:253], 0, s[98:99]
	global_load_dwordx4 v[184:187], v[252:253], off
	v_lshl_add_u64 v[252:253], v[252:253], 0, s[98:99]
	global_load_dwordx4 v[196:199], v[252:253], off
	v_lshl_add_u64 v[252:253], v[252:253], 0, s[98:99]
	global_load_dwordx4 v[200:203], v[252:253], off
	v_lshl_add_u64 v[252:253], v[252:253], 0, s[98:99]
	global_load_dwordx4 v[204:207], v[252:253], off
	v_lshl_add_u64 v[252:253], v[252:253], 0, s[98:99]
	global_load_dwordx4 v[208:211], v[252:253], off
	v_lshl_add_u64 v[252:253], v[252:253], 0, s[98:99]
	global_load_dwordx4 v[212:215], v[252:253], off
	v_lshl_add_u64 v[252:253], v[252:253], 0, s[98:99]
	global_load_dwordx4 v[216:219], v[252:253], off
	v_lshl_add_u64 v[252:253], v[252:253], 0, s[98:99]
	global_load_dwordx4 v[220:223], v[252:253], off
	v_lshl_add_u64 v[252:253], v[252:253], 0, s[98:99]
	global_load_dwordx4 v[224:227], v[252:253], off
	v_lshl_add_u64 v[252:253], v[252:253], 0, s[98:99]
	global_load_dwordx4 v[228:231], v[252:253], off
	v_lshl_add_u64 v[252:253], v[252:253], 0, s[98:99]
	global_load_dwordx4 v[232:235], v[252:253], off
	v_readlane_b32 s74, v254, 3
	v_readlane_b32 s75, v254, 4
	v_readlane_b32 s76, v254, 5
	v_readlane_b32 s77, v254, 6
	v_readlane_b32 s78, v254, 7
	v_readlane_b32 s79, v254, 8
	v_readlane_b32 s80, v254, 9
	v_readlane_b32 s81, v254, 10
	v_readlane_b32 s82, v254, 11
	v_readlane_b32 s83, v254, 12
	v_readlane_b32 s84, v254, 13
	v_readlane_b32 s85, v254, 14
	v_readlane_b32 s86, v254, 15
	v_readlane_b32 s87, v254, 16
	s_waitcnt vmcnt(15) lgkmcnt(0)
	v_mov_b32_e32 v4, v164
	v_mov_b32_e32 v5, v165
	v_mov_b32_e32 v6, v166
	v_mov_b32_e32 v7, v167
	v_pk_fma_f32 v[8:9], v[2:3], v[12:13], v[6:7]
	v_pk_fma_f32 v[10:11], v[0:1], v[10:11], v[4:5]
	v_mul_f32_e32 v5, v9, v9
	v_mul_f32_e32 v4, v11, v11
	v_fmac_f32_e32 v4, v10, v10
	v_fmac_f32_e32 v5, v8, v8
	v_add_f32_e32 v4, v4, v5
	s_nop 1
	v_mov_b32_dpp v5, v4 quad_perm:[1,0,3,2] row_mask:0xf bank_mask:0xf
	v_lshl_add_u64 v[6:7], v[14:15], 1, s[64:65]
	v_cvt_pk_bf16_f32 v12, v10, v11
	v_cvt_pk_bf16_f32 v13, v8, v9
	global_store_dwordx2 v[6:7], v[12:13], off
	s_waitcnt lgkmcnt(0)
	v_add_f32_e32 v4, v4, v5
	s_nop 1
	v_mov_b32_dpp v5, v4 quad_perm:[2,3,0,1] row_mask:0xf bank_mask:0xf
	s_waitcnt lgkmcnt(0)
	v_add_f32_e32 v4, v4, v5
	s_nop 1
	v_mov_b32_dpp v5, v4 row_ror:12 row_mask:0xf bank_mask:0xf
	s_waitcnt lgkmcnt(0)
	v_add_f32_e32 v4, v4, v5
	s_nop 1
	v_mov_b32_dpp v5, v4 row_ror:8 row_mask:0xf bank_mask:0xf
	s_waitcnt lgkmcnt(0)
	v_add_f32_e32 v4, v4, v5
	v_mov_b32_e32 v5, v4
	s_nop 1
	v_permlane16_swap_b32_e32 v4, v5
	s_waitcnt lgkmcnt(0)
	v_add_f32_e32 v4, v4, v5
	v_mov_b32_e32 v5, v4
	s_nop 1
	v_permlane32_swap_b32_e32 v4, v5
	s_and_saveexec_b64 s[4:5], vcc
	s_cbranch_execz .LBB0_1656
	s_lshl_b64 s[2:3], s[2:3], 5
	s_add_u32 s2, s6, s2
	s_addc_u32 s3, s7, s3
	v_mov_b32_e32 v6, 0
	s_waitcnt lgkmcnt(0)
	v_add_f32_e32 v4, v4, v5
	global_store_dword v6, v4, s[2:3] sc1
; #define LAS __attribute__((address_space(3)))
; __device__ __forceinline__ f32x4 ld_bf4(const bf16_t* p) { u32x2 w = *(const u32x2*)p; return (f32x4){__uint_as_float(w.x << 16), __uint_as_float(w.x & 0xffff0000u), __uint_as_float(w.y << 16), __uint_as_float(w.y & 0xffff0000u)}; }
; __device__ __forceinline__ void st_bf4(bf16_t* p, f32x4 v) { u32x2 w; w.x = pk2(v[0], v[1]); w.y = pk2(v[2], v[3]); *(u32x2*)p = w; }
; __device__ __forceinline__ float wave_sum(float v) {
; #pragma unroll
;     for (int o = 1; o < 64; o <<= 1) v += __shfl_xor(v, o);
;     return v;
; template <int MODOFF, int STORE  , bool BASE_BF16>
; __device__ __forceinline__ void epi_rows_part1(LAS unsigned char* lds, const f32x4 (&acc)[2][2][4][2], const Unit& u, const float* base, const float* mod, float* outp, float* slots, f32x4 (&xr)[2][16]) {
;     ...
;         for (int j = 0; j < 16; ++j) { const int rl = wid * 16 + j, row = u.pm * BM + ai * HALF + rl; const size_t o = (size_t)row * DM + colg;
;             const f32x4 v = *(const LAS f32x4*)(T + rl * 256 + ((lane ^ j) << 2));
;             const f32x4 bs = BASE_BF16 ? ld_bf4((const bf16_t*)base + o) : *(const f32x4*)(base + o);
;             const f32x4 x1 = bs + gt * v; xr[ai][j] = x1; if (STORE == 2) st_bf4((bf16_t*)outp + o, x1);
;             const float sq = wave_sum((x1[0] * x1[0] + x1[1] * x1[1]) + (x1[2] * x1[2] + x1[3] * x1[3]));
;             if (lane == 0) __hip_atomic_store((unsigned*)slots + (size_t)row * 8 + u.pn, __float_as_uint(sq), __ATOMIC_RELAXED, __HIP_MEMORY_SCOPE_AGENT); }
.LBB0_1656:
	s_or_b64 exec, exec, s[4:5]
	s_add_i32 s2, s9, s24
	s_ashr_i32 s3, s2, 31
	s_lshl_b64 s[4:5], s[2:3], 11
	v_readlane_b32 s72, v254, 1
	v_lshl_add_u64 v[18:19], s[4:5], 0, v[132:133]
	v_readlane_b32 s73, v254, 2
	ds_read_b128 v[14:17], v139
	v_readlane_b32 s74, v254, 3
	s_waitcnt lgkmcnt(1)
	v_lshl_add_u64 v[4:5], v[18:19], 2, s[72:73]
	v_readlane_b32 s75, v254, 4
	v_readlane_b32 s76, v254, 5
	v_readlane_b32 s77, v254, 6
	v_readlane_b32 s78, v254, 7
	v_readlane_b32 s79, v254, 8
	v_readlane_b32 s80, v254, 9
	v_readlane_b32 s81, v254, 10
	v_readlane_b32 s82, v254, 11
	v_readlane_b32 s83, v254, 12
	v_readlane_b32 s84, v254, 13
	v_readlane_b32 s85, v254, 14
	v_readlane_b32 s86, v254, 15
	v_readlane_b32 s87, v254, 16
	s_waitcnt vmcnt(16) lgkmcnt(0)
	v_mov_b32_e32 v4, v168
	v_mov_b32_e32 v5, v169
	v_mov_b32_e32 v6, v170
	v_mov_b32_e32 v7, v171
	v_pk_fma_f32 v[12:13], v[2:3], v[16:17], v[6:7]
	v_pk_fma_f32 v[14:15], v[0:1], v[14:15], v[4:5]
	v_mul_f32_e32 v5, v13, v13
	v_mul_f32_e32 v4, v15, v15
	v_fmac_f32_e32 v4, v14, v14
	v_fmac_f32_e32 v5, v12, v12
	v_add_f32_e32 v4, v4, v5
	s_nop 1
	v_mov_b32_dpp v5, v4 quad_perm:[1,0,3,2] row_mask:0xf bank_mask:0xf
	v_lshl_add_u64 v[6:7], v[18:19], 1, s[64:65]
	v_cvt_pk_bf16_f32 v16, v14, v15
	v_cvt_pk_bf16_f32 v17, v12, v13
	global_store_dwordx2 v[6:7], v[16:17], off
	s_waitcnt lgkmcnt(0)
	v_add_f32_e32 v4, v4, v5
	s_nop 1
	v_mov_b32_dpp v5, v4 quad_perm:[2,3,0,1] row_mask:0xf bank_mask:0xf
	s_waitcnt lgkmcnt(0)
	v_add_f32_e32 v4, v4, v5
	s_nop 1
	v_mov_b32_dpp v5, v4 row_ror:12 row_mask:0xf bank_mask:0xf
	s_waitcnt lgkmcnt(0)
	v_add_f32_e32 v4, v4, v5
	s_nop 1
	v_mov_b32_dpp v5, v4 row_ror:8 row_mask:0xf bank_mask:0xf
	s_waitcnt lgkmcnt(0)
	v_add_f32_e32 v4, v4, v5
	v_mov_b32_e32 v5, v4
	s_nop 1
	v_permlane16_swap_b32_e32 v4, v5
	s_waitcnt lgkmcnt(0)
	v_add_f32_e32 v4, v4, v5
	v_mov_b32_e32 v5, v4
	s_nop 1
	v_permlane32_swap_b32_e32 v4, v5
	s_and_saveexec_b64 s[4:5], vcc
	s_cbranch_execz .LBB0_1658
	s_lshl_b64 s[2:3], s[2:3], 5
	s_add_u32 s2, s6, s2
	s_addc_u32 s3, s7, s3
	v_mov_b32_e32 v6, 0
	s_waitcnt lgkmcnt(0)
	v_add_f32_e32 v4, v4, v5
	global_store_dword v6, v4, s[2:3] sc1
.LBB0_1658:
	s_or_b64 exec, exec, s[4:5]
	s_add_i32 s2, s10, s24
	s_ashr_i32 s3, s2, 31
	s_lshl_b64 s[4:5], s[2:3], 11
	v_readlane_b32 s72, v254, 1
	v_lshl_add_u64 v[22:23], s[4:5], 0, v[132:133]
	v_readlane_b32 s73, v254, 2
	ds_read_b128 v[18:21], v140
	v_readlane_b32 s74, v254, 3
	s_waitcnt lgkmcnt(1)
	v_lshl_add_u64 v[4:5], v[22:23], 2, s[72:73]
	v_readlane_b32 s75, v254, 4
	v_readlane_b32 s76, v254, 5
	v_readlane_b32 s77, v254, 6
	v_readlane_b32 s78, v254, 7
	v_readlane_b32 s79, v254, 8
	v_readlane_b32 s80, v254, 9
	v_readlane_b32 s81, v254, 10
	v_readlane_b32 s82, v254, 11
	v_readlane_b32 s83, v254, 12
	v_readlane_b32 s84, v254, 13
	v_readlane_b32 s85, v254, 14
	v_readlane_b32 s86, v254, 15
	v_readlane_b32 s87, v254, 16
	s_waitcnt vmcnt(17) lgkmcnt(0)
	v_mov_b32_e32 v4, v172
	v_mov_b32_e32 v5, v173
	v_mov_b32_e32 v6, v174
	v_mov_b32_e32 v7, v175
	v_pk_fma_f32 v[16:17], v[2:3], v[20:21], v[6:7]
	v_pk_fma_f32 v[18:19], v[0:1], v[18:19], v[4:5]
	v_mul_f32_e32 v5, v17, v17
	v_mul_f32_e32 v4, v19, v19
	v_fmac_f32_e32 v4, v18, v18
	v_fmac_f32_e32 v5, v16, v16
	v_add_f32_e32 v4, v4, v5
	s_nop 1
	v_mov_b32_dpp v5, v4 quad_perm:[1,0,3,2] row_mask:0xf bank_mask:0xf
	v_lshl_add_u64 v[6:7], v[22:23], 1, s[64:65]
	v_cvt_pk_bf16_f32 v20, v18, v19
	v_cvt_pk_bf16_f32 v21, v16, v17
	global_store_dwordx2 v[6:7], v[20:21], off
	s_waitcnt lgkmcnt(0)
	v_add_f32_e32 v4, v4, v5
	s_nop 1
	v_mov_b32_dpp v5, v4 quad_perm:[2,3,0,1] row_mask:0xf bank_mask:0xf
	s_waitcnt lgkmcnt(0)
	v_add_f32_e32 v4, v4, v5
	s_nop 1
	v_mov_b32_dpp v5, v4 row_ror:12 row_mask:0xf bank_mask:0xf
	s_waitcnt lgkmcnt(0)
	v_add_f32_e32 v4, v4, v5
	s_nop 1
	v_mov_b32_dpp v5, v4 row_ror:8 row_mask:0xf bank_mask:0xf
	s_waitcnt lgkmcnt(0)
	v_add_f32_e32 v4, v4, v5
	v_mov_b32_e32 v5, v4
	s_nop 1
	v_permlane16_swap_b32_e32 v4, v5
	s_waitcnt lgkmcnt(0)
	v_add_f32_e32 v4, v4, v5
	v_mov_b32_e32 v5, v4
	s_nop 1
	v_permlane32_swap_b32_e32 v4, v5
	s_and_saveexec_b64 s[4:5], vcc
	s_cbranch_execz .LBB0_1660
	s_lshl_b64 s[2:3], s[2:3], 5
	s_add_u32 s2, s6, s2
	s_addc_u32 s3, s7, s3
	v_mov_b32_e32 v6, 0
	s_waitcnt lgkmcnt(0)
	v_add_f32_e32 v4, v4, v5
	global_store_dword v6, v4, s[2:3] sc1
.LBB0_1660:
	s_or_b64 exec, exec, s[4:5]
	s_add_i32 s2, s11, s24
	s_ashr_i32 s3, s2, 31
	s_lshl_b64 s[4:5], s[2:3], 11
	v_readlane_b32 s72, v254, 1
	v_lshl_add_u64 v[26:27], s[4:5], 0, v[132:133]
	v_readlane_b32 s73, v254, 2
	ds_read_b128 v[22:25], v141
	v_readlane_b32 s74, v254, 3
	s_waitcnt lgkmcnt(1)
	v_lshl_add_u64 v[4:5], v[26:27], 2, s[72:73]
	v_readlane_b32 s75, v254, 4
	v_readlane_b32 s76, v254, 5
	v_readlane_b32 s77, v254, 6
	v_readlane_b32 s78, v254, 7
	v_readlane_b32 s79, v254, 8
	v_readlane_b32 s80, v254, 9
	v_readlane_b32 s81, v254, 10
	v_readlane_b32 s82, v254, 11
	v_readlane_b32 s83, v254, 12
	v_readlane_b32 s84, v254, 13
	v_readlane_b32 s85, v254, 14
	v_readlane_b32 s86, v254, 15
	v_readlane_b32 s87, v254, 16
	s_waitcnt vmcnt(18) lgkmcnt(0)
	v_mov_b32_e32 v4, v176
	v_mov_b32_e32 v5, v177
	v_mov_b32_e32 v6, v178
	v_mov_b32_e32 v7, v179
	v_pk_fma_f32 v[20:21], v[2:3], v[24:25], v[6:7]
	v_pk_fma_f32 v[22:23], v[0:1], v[22:23], v[4:5]
	v_mul_f32_e32 v5, v21, v21
	v_mul_f32_e32 v4, v23, v23
	v_fmac_f32_e32 v4, v22, v22
	v_fmac_f32_e32 v5, v20, v20
	v_add_f32_e32 v4, v4, v5
	s_nop 1
	v_mov_b32_dpp v5, v4 quad_perm:[1,0,3,2] row_mask:0xf bank_mask:0xf
	v_lshl_add_u64 v[6:7], v[26:27], 1, s[64:65]
	v_cvt_pk_bf16_f32 v24, v22, v23
	v_cvt_pk_bf16_f32 v25, v20, v21
	global_store_dwordx2 v[6:7], v[24:25], off
	s_waitcnt lgkmcnt(0)
	v_add_f32_e32 v4, v4, v5
	s_nop 1
	v_mov_b32_dpp v5, v4 quad_perm:[2,3,0,1] row_mask:0xf bank_mask:0xf
	s_waitcnt lgkmcnt(0)
	v_add_f32_e32 v4, v4, v5
	s_nop 1
	v_mov_b32_dpp v5, v4 row_ror:12 row_mask:0xf bank_mask:0xf
	s_waitcnt lgkmcnt(0)
	v_add_f32_e32 v4, v4, v5
	s_nop 1
	v_mov_b32_dpp v5, v4 row_ror:8 row_mask:0xf bank_mask:0xf
	s_waitcnt lgkmcnt(0)
	v_add_f32_e32 v4, v4, v5
	v_mov_b32_e32 v5, v4
	s_nop 1
	v_permlane16_swap_b32_e32 v4, v5
	s_waitcnt lgkmcnt(0)
	v_add_f32_e32 v4, v4, v5
	v_mov_b32_e32 v5, v4
	s_nop 1
	v_permlane32_swap_b32_e32 v4, v5
	s_and_saveexec_b64 s[4:5], vcc
	s_cbranch_execz .LBB0_1662
	s_lshl_b64 s[2:3], s[2:3], 5
	s_add_u32 s2, s6, s2
	s_addc_u32 s3, s7, s3
	v_mov_b32_e32 v6, 0
	s_waitcnt lgkmcnt(0)
	v_add_f32_e32 v4, v4, v5
	global_store_dword v6, v4, s[2:3] sc1
; #define LAS __attribute__((address_space(3)))
; __device__ __forceinline__ f32x4 ld_bf4(const bf16_t* p) { u32x2 w = *(const u32x2*)p; return (f32x4){__uint_as_float(w.x << 16), __uint_as_float(w.x & 0xffff0000u), __uint_as_float(w.y << 16), __uint_as_float(w.y & 0xffff0000u)}; }
; __device__ __forceinline__ void st_bf4(bf16_t* p, f32x4 v) { u32x2 w; w.x = pk2(v[0], v[1]); w.y = pk2(v[2], v[3]); *(u32x2*)p = w; }
; __device__ __forceinline__ float wave_sum(float v) {
; #pragma unroll
;     for (int o = 1; o < 64; o <<= 1) v += __shfl_xor(v, o);
;     return v;
; template <int MODOFF, int STORE  , bool BASE_BF16>
; __device__ __forceinline__ void epi_rows_part1(LAS unsigned char* lds, const f32x4 (&acc)[2][2][4][2], const Unit& u, const float* base, const float* mod, float* outp, float* slots, f32x4 (&xr)[2][16]) {
;     ...
;         for (int j = 0; j < 16; ++j) { const int rl = wid * 16 + j, row = u.pm * BM + ai * HALF + rl; const size_t o = (size_t)row * DM + colg;
;             const f32x4 v = *(const LAS f32x4*)(T + rl * 256 + ((lane ^ j) << 2));
;             const f32x4 bs = BASE_BF16 ? ld_bf4((const bf16_t*)base + o) : *(const f32x4*)(base + o);
;             const f32x4 x1 = bs + gt * v; xr[ai][j] = x1; if (STORE == 2) st_bf4((bf16_t*)outp + o, x1);
;             const float sq = wave_sum((x1[0] * x1[0] + x1[1] * x1[1]) + (x1[2] * x1[2] + x1[3] * x1[3]));
;             if (lane == 0) __hip_atomic_store((unsigned*)slots + (size_t)row * 8 + u.pn, __float_as_uint(sq), __ATOMIC_RELAXED, __HIP_MEMORY_SCOPE_AGENT); }
.LBB0_1662:
	s_or_b64 exec, exec, s[4:5]
	s_add_i32 s2, s12, s24
	s_ashr_i32 s3, s2, 31
	s_lshl_b64 s[4:5], s[2:3], 11
	v_readlane_b32 s72, v254, 1
	v_lshl_add_u64 v[30:31], s[4:5], 0, v[132:133]
	v_readlane_b32 s73, v254, 2
	ds_read_b128 v[26:29], v142
	v_readlane_b32 s74, v254, 3
	s_waitcnt lgkmcnt(1)
	v_lshl_add_u64 v[4:5], v[30:31], 2, s[72:73]
	v_readlane_b32 s75, v254, 4
	v_readlane_b32 s76, v254, 5
	v_readlane_b32 s77, v254, 6
	v_readlane_b32 s78, v254, 7
	v_readlane_b32 s79, v254, 8
	v_readlane_b32 s80, v254, 9
	v_readlane_b32 s81, v254, 10
	v_readlane_b32 s82, v254, 11
	v_readlane_b32 s83, v254, 12
	v_readlane_b32 s84, v254, 13
	v_readlane_b32 s85, v254, 14
	v_readlane_b32 s86, v254, 15
	v_readlane_b32 s87, v254, 16
	s_waitcnt vmcnt(19) lgkmcnt(0)
	v_mov_b32_e32 v4, v180
	v_mov_b32_e32 v5, v181
	v_mov_b32_e32 v6, v182
	v_mov_b32_e32 v7, v183
	v_pk_fma_f32 v[24:25], v[2:3], v[28:29], v[6:7]
	v_pk_fma_f32 v[26:27], v[0:1], v[26:27], v[4:5]
	v_mul_f32_e32 v5, v25, v25
	v_mul_f32_e32 v4, v27, v27
	v_fmac_f32_e32 v4, v26, v26
	v_fmac_f32_e32 v5, v24, v24
	v_add_f32_e32 v4, v4, v5
	s_nop 1
	v_mov_b32_dpp v5, v4 quad_perm:[1,0,3,2] row_mask:0xf bank_mask:0xf
	v_lshl_add_u64 v[6:7], v[30:31], 1, s[64:65]
	v_cvt_pk_bf16_f32 v28, v26, v27
	v_cvt_pk_bf16_f32 v29, v24, v25
	global_store_dwordx2 v[6:7], v[28:29], off
	s_waitcnt lgkmcnt(0)
	v_add_f32_e32 v4, v4, v5
	s_nop 1
	v_mov_b32_dpp v5, v4 quad_perm:[2,3,0,1] row_mask:0xf bank_mask:0xf
	s_waitcnt lgkmcnt(0)
	v_add_f32_e32 v4, v4, v5
	s_nop 1
	v_mov_b32_dpp v5, v4 row_ror:12 row_mask:0xf bank_mask:0xf
	s_waitcnt lgkmcnt(0)
	v_add_f32_e32 v4, v4, v5
	s_nop 1
	v_mov_b32_dpp v5, v4 row_ror:8 row_mask:0xf bank_mask:0xf
	s_waitcnt lgkmcnt(0)
	v_add_f32_e32 v4, v4, v5
	v_mov_b32_e32 v5, v4
	s_nop 1
	v_permlane16_swap_b32_e32 v4, v5
	s_waitcnt lgkmcnt(0)
	v_add_f32_e32 v4, v4, v5
	v_mov_b32_e32 v5, v4
	s_nop 1
	v_permlane32_swap_b32_e32 v4, v5
	s_and_saveexec_b64 s[4:5], vcc
	s_cbranch_execz .LBB0_1664
	s_lshl_b64 s[2:3], s[2:3], 5
	s_add_u32 s2, s6, s2
	s_addc_u32 s3, s7, s3
	v_mov_b32_e32 v6, 0
	s_waitcnt lgkmcnt(0)
	v_add_f32_e32 v4, v4, v5
	global_store_dword v6, v4, s[2:3] sc1
.LBB0_1664:
	s_or_b64 exec, exec, s[4:5]
	s_add_i32 s2, s13, s24
	s_ashr_i32 s3, s2, 31
	s_lshl_b64 s[4:5], s[2:3], 11
	v_readlane_b32 s72, v254, 1
	v_lshl_add_u64 v[34:35], s[4:5], 0, v[132:133]
	v_readlane_b32 s73, v254, 2
	ds_read_b128 v[30:33], v143
	v_readlane_b32 s74, v254, 3
	s_waitcnt lgkmcnt(1)
	v_lshl_add_u64 v[4:5], v[34:35], 2, s[72:73]
	v_readlane_b32 s75, v254, 4
	v_readlane_b32 s76, v254, 5
	v_readlane_b32 s77, v254, 6
	v_readlane_b32 s78, v254, 7
	v_readlane_b32 s79, v254, 8
	v_readlane_b32 s80, v254, 9
	v_readlane_b32 s81, v254, 10
	v_readlane_b32 s82, v254, 11
	v_readlane_b32 s83, v254, 12
	v_readlane_b32 s84, v254, 13
	v_readlane_b32 s85, v254, 14
	v_readlane_b32 s86, v254, 15
	v_readlane_b32 s87, v254, 16
	s_waitcnt vmcnt(20) lgkmcnt(0)
	v_mov_b32_e32 v4, v184
	v_mov_b32_e32 v5, v185
	v_mov_b32_e32 v6, v186
	v_mov_b32_e32 v7, v187
	v_pk_fma_f32 v[28:29], v[2:3], v[32:33], v[6:7]
	v_pk_fma_f32 v[30:31], v[0:1], v[30:31], v[4:5]
	v_mul_f32_e32 v5, v29, v29
	v_mul_f32_e32 v4, v31, v31
	v_fmac_f32_e32 v4, v30, v30
	v_fmac_f32_e32 v5, v28, v28
	v_add_f32_e32 v4, v4, v5
	s_nop 1
	v_mov_b32_dpp v5, v4 quad_perm:[1,0,3,2] row_mask:0xf bank_mask:0xf
	v_lshl_add_u64 v[6:7], v[34:35], 1, s[64:65]
	v_cvt_pk_bf16_f32 v32, v30, v31
	v_cvt_pk_bf16_f32 v33, v28, v29
	global_store_dwordx2 v[6:7], v[32:33], off
	s_waitcnt lgkmcnt(0)
	v_add_f32_e32 v4, v4, v5
	s_nop 1
	v_mov_b32_dpp v5, v4 quad_perm:[2,3,0,1] row_mask:0xf bank_mask:0xf
	s_waitcnt lgkmcnt(0)
	v_add_f32_e32 v4, v4, v5
	s_nop 1
	v_mov_b32_dpp v5, v4 row_ror:12 row_mask:0xf bank_mask:0xf
	s_waitcnt lgkmcnt(0)
	v_add_f32_e32 v4, v4, v5
	s_nop 1
	v_mov_b32_dpp v5, v4 row_ror:8 row_mask:0xf bank_mask:0xf
	s_waitcnt lgkmcnt(0)
	v_add_f32_e32 v4, v4, v5
	v_mov_b32_e32 v5, v4
	s_nop 1
	v_permlane16_swap_b32_e32 v4, v5
	s_waitcnt lgkmcnt(0)
	v_add_f32_e32 v4, v4, v5
	v_mov_b32_e32 v5, v4
	s_nop 1
	v_permlane32_swap_b32_e32 v4, v5
	s_and_saveexec_b64 s[4:5], vcc
	s_cbranch_execz .LBB0_1666
	s_lshl_b64 s[2:3], s[2:3], 5
	s_add_u32 s2, s6, s2
	s_addc_u32 s3, s7, s3
	v_mov_b32_e32 v6, 0
	s_waitcnt lgkmcnt(0)
	v_add_f32_e32 v4, v4, v5
	global_store_dword v6, v4, s[2:3] sc1
.LBB0_1666:
	s_or_b64 exec, exec, s[4:5]
	s_add_i32 s2, s14, s24
	s_ashr_i32 s3, s2, 31
	s_lshl_b64 s[4:5], s[2:3], 11
	v_readlane_b32 s72, v254, 1
	v_lshl_add_u64 v[38:39], s[4:5], 0, v[132:133]
	v_readlane_b32 s73, v254, 2
	ds_read_b128 v[34:37], v144
	v_readlane_b32 s74, v254, 3
	s_waitcnt lgkmcnt(1)
	v_lshl_add_u64 v[4:5], v[38:39], 2, s[72:73]
	v_readlane_b32 s75, v254, 4
	v_readlane_b32 s76, v254, 5
	v_readlane_b32 s77, v254, 6
	v_readlane_b32 s78, v254, 7
	v_readlane_b32 s79, v254, 8
	v_readlane_b32 s80, v254, 9
	v_readlane_b32 s81, v254, 10
	v_readlane_b32 s82, v254, 11
	v_readlane_b32 s83, v254, 12
	v_readlane_b32 s84, v254, 13
	v_readlane_b32 s85, v254, 14
	v_readlane_b32 s86, v254, 15
	v_readlane_b32 s87, v254, 16
	s_waitcnt vmcnt(21) lgkmcnt(0)
	v_mov_b32_e32 v4, v196
	v_mov_b32_e32 v5, v197
	v_mov_b32_e32 v6, v198
	v_mov_b32_e32 v7, v199
	v_pk_fma_f32 v[32:33], v[2:3], v[36:37], v[6:7]
	v_pk_fma_f32 v[34:35], v[0:1], v[34:35], v[4:5]
	v_mul_f32_e32 v5, v33, v33
	v_mul_f32_e32 v4, v35, v35
	v_fmac_f32_e32 v4, v34, v34
	v_fmac_f32_e32 v5, v32, v32
	v_add_f32_e32 v4, v4, v5
	s_nop 1
	v_mov_b32_dpp v5, v4 quad_perm:[1,0,3,2] row_mask:0xf bank_mask:0xf
	v_lshl_add_u64 v[6:7], v[38:39], 1, s[64:65]
	v_cvt_pk_bf16_f32 v36, v34, v35
	v_cvt_pk_bf16_f32 v37, v32, v33
	global_store_dwordx2 v[6:7], v[36:37], off
	s_waitcnt lgkmcnt(0)
	v_add_f32_e32 v4, v4, v5
	s_nop 1
	v_mov_b32_dpp v5, v4 quad_perm:[2,3,0,1] row_mask:0xf bank_mask:0xf
	s_waitcnt lgkmcnt(0)
	v_add_f32_e32 v4, v4, v5
	s_nop 1
	v_mov_b32_dpp v5, v4 row_ror:12 row_mask:0xf bank_mask:0xf
	s_waitcnt lgkmcnt(0)
	v_add_f32_e32 v4, v4, v5
	s_nop 1
	v_mov_b32_dpp v5, v4 row_ror:8 row_mask:0xf bank_mask:0xf
	s_waitcnt lgkmcnt(0)
	v_add_f32_e32 v4, v4, v5
	v_mov_b32_e32 v5, v4
	s_nop 1
	v_permlane16_swap_b32_e32 v4, v5
	s_waitcnt lgkmcnt(0)
	v_add_f32_e32 v4, v4, v5
	v_mov_b32_e32 v5, v4
	s_nop 1
	v_permlane32_swap_b32_e32 v4, v5
	s_and_saveexec_b64 s[4:5], vcc
	s_cbranch_execz .LBB0_1668
	s_lshl_b64 s[2:3], s[2:3], 5
	s_add_u32 s2, s6, s2
	s_addc_u32 s3, s7, s3
	v_mov_b32_e32 v6, 0
	s_waitcnt lgkmcnt(0)
	v_add_f32_e32 v4, v4, v5
	global_store_dword v6, v4, s[2:3] sc1
; #define LAS __attribute__((address_space(3)))
; __device__ __forceinline__ f32x4 ld_bf4(const bf16_t* p) { u32x2 w = *(const u32x2*)p; return (f32x4){__uint_as_float(w.x << 16), __uint_as_float(w.x & 0xffff0000u), __uint_as_float(w.y << 16), __uint_as_float(w.y & 0xffff0000u)}; }
; __device__ __forceinline__ void st_bf4(bf16_t* p, f32x4 v) { u32x2 w; w.x = pk2(v[0], v[1]); w.y = pk2(v[2], v[3]); *(u32x2*)p = w; }
; __device__ __forceinline__ float wave_sum(float v) {
; #pragma unroll
;     for (int o = 1; o < 64; o <<= 1) v += __shfl_xor(v, o);
;     return v;
; template <int MODOFF, int STORE  , bool BASE_BF16>
; __device__ __forceinline__ void epi_rows_part1(LAS unsigned char* lds, const f32x4 (&acc)[2][2][4][2], const Unit& u, const float* base, const float* mod, float* outp, float* slots, f32x4 (&xr)[2][16]) {
;     ...
;         for (int j = 0; j < 16; ++j) { const int rl = wid * 16 + j, row = u.pm * BM + ai * HALF + rl; const size_t o = (size_t)row * DM + colg;
;             const f32x4 v = *(const LAS f32x4*)(T + rl * 256 + ((lane ^ j) << 2));
;             const f32x4 bs = BASE_BF16 ? ld_bf4((const bf16_t*)base + o) : *(const f32x4*)(base + o);
;             const f32x4 x1 = bs + gt * v; xr[ai][j] = x1; if (STORE == 2) st_bf4((bf16_t*)outp + o, x1);
;             const float sq = wave_sum((x1[0] * x1[0] + x1[1] * x1[1]) + (x1[2] * x1[2] + x1[3] * x1[3]));
;             if (lane == 0) __hip_atomic_store((unsigned*)slots + (size_t)row * 8 + u.pn, __float_as_uint(sq), __ATOMIC_RELAXED, __HIP_MEMORY_SCOPE_AGENT); }
.LBB0_1668:
	s_or_b64 exec, exec, s[4:5]
	s_add_i32 s2, s15, s24
	s_ashr_i32 s3, s2, 31
	s_lshl_b64 s[4:5], s[2:3], 11
	v_readlane_b32 s72, v254, 1
	v_lshl_add_u64 v[42:43], s[4:5], 0, v[132:133]
	v_readlane_b32 s73, v254, 2
	ds_read_b128 v[38:41], v145
	v_readlane_b32 s74, v254, 3
	s_waitcnt lgkmcnt(1)
	v_lshl_add_u64 v[4:5], v[42:43], 2, s[72:73]
	v_readlane_b32 s75, v254, 4
	v_readlane_b32 s76, v254, 5
	v_readlane_b32 s77, v254, 6
	v_readlane_b32 s78, v254, 7
	v_readlane_b32 s79, v254, 8
	v_readlane_b32 s80, v254, 9
	v_readlane_b32 s81, v254, 10
	v_readlane_b32 s82, v254, 11
	v_readlane_b32 s83, v254, 12
	v_readlane_b32 s84, v254, 13
	v_readlane_b32 s85, v254, 14
	v_readlane_b32 s86, v254, 15
	v_readlane_b32 s87, v254, 16
	s_waitcnt vmcnt(22) lgkmcnt(0)
	v_mov_b32_e32 v4, v200
	v_mov_b32_e32 v5, v201
	v_mov_b32_e32 v6, v202
	v_mov_b32_e32 v7, v203
	v_pk_fma_f32 v[36:37], v[2:3], v[40:41], v[6:7]
	v_pk_fma_f32 v[38:39], v[0:1], v[38:39], v[4:5]
	v_mul_f32_e32 v5, v37, v37
	v_mul_f32_e32 v4, v39, v39
	v_fmac_f32_e32 v4, v38, v38
	v_fmac_f32_e32 v5, v36, v36
	v_add_f32_e32 v4, v4, v5
	s_nop 1
	v_mov_b32_dpp v5, v4 quad_perm:[1,0,3,2] row_mask:0xf bank_mask:0xf
	v_lshl_add_u64 v[6:7], v[42:43], 1, s[64:65]
	v_cvt_pk_bf16_f32 v40, v38, v39
	v_cvt_pk_bf16_f32 v41, v36, v37
	global_store_dwordx2 v[6:7], v[40:41], off
	s_waitcnt lgkmcnt(0)
	v_add_f32_e32 v4, v4, v5
	s_nop 1
	v_mov_b32_dpp v5, v4 quad_perm:[2,3,0,1] row_mask:0xf bank_mask:0xf
	s_waitcnt lgkmcnt(0)
	v_add_f32_e32 v4, v4, v5
	s_nop 1
	v_mov_b32_dpp v5, v4 row_ror:12 row_mask:0xf bank_mask:0xf
	s_waitcnt lgkmcnt(0)
	v_add_f32_e32 v4, v4, v5
	s_nop 1
	v_mov_b32_dpp v5, v4 row_ror:8 row_mask:0xf bank_mask:0xf
	s_waitcnt lgkmcnt(0)
	v_add_f32_e32 v4, v4, v5
	v_mov_b32_e32 v5, v4
	s_nop 1
	v_permlane16_swap_b32_e32 v4, v5
	s_waitcnt lgkmcnt(0)
	v_add_f32_e32 v4, v4, v5
	v_mov_b32_e32 v5, v4
	s_nop 1
	v_permlane32_swap_b32_e32 v4, v5
	s_and_saveexec_b64 s[4:5], vcc
	s_cbranch_execz .LBB0_1670
	s_lshl_b64 s[2:3], s[2:3], 5
	s_add_u32 s2, s6, s2
	s_addc_u32 s3, s7, s3
	v_mov_b32_e32 v6, 0
	s_waitcnt lgkmcnt(0)
	v_add_f32_e32 v4, v4, v5
	global_store_dword v6, v4, s[2:3] sc1
.LBB0_1670:
	s_or_b64 exec, exec, s[4:5]
	s_add_i32 s2, s16, s24
	s_ashr_i32 s3, s2, 31
	s_lshl_b64 s[4:5], s[2:3], 11
	v_readlane_b32 s72, v254, 1
	v_lshl_add_u64 v[46:47], s[4:5], 0, v[132:133]
	v_readlane_b32 s73, v254, 2
	ds_read_b128 v[42:45], v146
	v_readlane_b32 s74, v254, 3
	s_waitcnt lgkmcnt(1)
	v_lshl_add_u64 v[4:5], v[46:47], 2, s[72:73]
	v_readlane_b32 s75, v254, 4
	v_readlane_b32 s76, v254, 5
	v_readlane_b32 s77, v254, 6
	v_readlane_b32 s78, v254, 7
	v_readlane_b32 s79, v254, 8
	v_readlane_b32 s80, v254, 9
	v_readlane_b32 s81, v254, 10
	v_readlane_b32 s82, v254, 11
	v_readlane_b32 s83, v254, 12
	v_readlane_b32 s84, v254, 13
	v_readlane_b32 s85, v254, 14
	v_readlane_b32 s86, v254, 15
	v_readlane_b32 s87, v254, 16
	s_waitcnt vmcnt(23) lgkmcnt(0)
	v_mov_b32_e32 v4, v204
	v_mov_b32_e32 v5, v205
	v_mov_b32_e32 v6, v206
	v_mov_b32_e32 v7, v207
	v_pk_fma_f32 v[40:41], v[2:3], v[44:45], v[6:7]
	v_pk_fma_f32 v[42:43], v[0:1], v[42:43], v[4:5]
	v_mul_f32_e32 v5, v41, v41
	v_mul_f32_e32 v4, v43, v43
	v_fmac_f32_e32 v4, v42, v42
	v_fmac_f32_e32 v5, v40, v40
	v_add_f32_e32 v4, v4, v5
	s_nop 1
	v_mov_b32_dpp v5, v4 quad_perm:[1,0,3,2] row_mask:0xf bank_mask:0xf
	v_lshl_add_u64 v[6:7], v[46:47], 1, s[64:65]
	v_cvt_pk_bf16_f32 v44, v42, v43
	v_cvt_pk_bf16_f32 v45, v40, v41
	global_store_dwordx2 v[6:7], v[44:45], off
	s_waitcnt lgkmcnt(0)
	v_add_f32_e32 v4, v4, v5
	s_nop 1
	v_mov_b32_dpp v5, v4 quad_perm:[2,3,0,1] row_mask:0xf bank_mask:0xf
	s_waitcnt lgkmcnt(0)
	v_add_f32_e32 v4, v4, v5
	s_nop 1
	v_mov_b32_dpp v5, v4 row_ror:12 row_mask:0xf bank_mask:0xf
	s_waitcnt lgkmcnt(0)
	v_add_f32_e32 v4, v4, v5
	s_nop 1
	v_mov_b32_dpp v5, v4 row_ror:8 row_mask:0xf bank_mask:0xf
	s_waitcnt lgkmcnt(0)
	v_add_f32_e32 v4, v4, v5
	v_mov_b32_e32 v5, v4
	s_nop 1
	v_permlane16_swap_b32_e32 v4, v5
	s_waitcnt lgkmcnt(0)
	v_add_f32_e32 v4, v4, v5
	v_mov_b32_e32 v5, v4
	s_nop 1
	v_permlane32_swap_b32_e32 v4, v5
	s_and_saveexec_b64 s[4:5], vcc
	s_cbranch_execz .LBB0_1672
	s_lshl_b64 s[2:3], s[2:3], 5
	s_add_u32 s2, s6, s2
	s_addc_u32 s3, s7, s3
	v_mov_b32_e32 v6, 0
	s_waitcnt lgkmcnt(0)
	v_add_f32_e32 v4, v4, v5
	global_store_dword v6, v4, s[2:3] sc1
.LBB0_1672:
	s_or_b64 exec, exec, s[4:5]
	s_add_i32 s2, s17, s24
	s_ashr_i32 s3, s2, 31
	s_lshl_b64 s[4:5], s[2:3], 11
	v_readlane_b32 s72, v254, 1
	v_lshl_add_u64 v[50:51], s[4:5], 0, v[132:133]
	v_readlane_b32 s73, v254, 2
	ds_read_b128 v[46:49], v147
	v_readlane_b32 s74, v254, 3
	s_waitcnt lgkmcnt(1)
	v_lshl_add_u64 v[4:5], v[50:51], 2, s[72:73]
	v_readlane_b32 s75, v254, 4
	v_readlane_b32 s76, v254, 5
	v_readlane_b32 s77, v254, 6
	v_readlane_b32 s78, v254, 7
	v_readlane_b32 s79, v254, 8
	v_readlane_b32 s80, v254, 9
	v_readlane_b32 s81, v254, 10
	v_readlane_b32 s82, v254, 11
	v_readlane_b32 s83, v254, 12
	v_readlane_b32 s84, v254, 13
	v_readlane_b32 s85, v254, 14
	v_readlane_b32 s86, v254, 15
	v_readlane_b32 s87, v254, 16
	s_waitcnt vmcnt(24) lgkmcnt(0)
	v_mov_b32_e32 v4, v208
	v_mov_b32_e32 v5, v209
	v_mov_b32_e32 v6, v210
	v_mov_b32_e32 v7, v211
	v_pk_fma_f32 v[44:45], v[2:3], v[48:49], v[6:7]
	v_pk_fma_f32 v[46:47], v[0:1], v[46:47], v[4:5]
	v_mul_f32_e32 v5, v45, v45
	v_mul_f32_e32 v4, v47, v47
	v_fmac_f32_e32 v4, v46, v46
	v_fmac_f32_e32 v5, v44, v44
	v_add_f32_e32 v4, v4, v5
	s_nop 1
	v_mov_b32_dpp v5, v4 quad_perm:[1,0,3,2] row_mask:0xf bank_mask:0xf
	v_lshl_add_u64 v[6:7], v[50:51], 1, s[64:65]
	v_cvt_pk_bf16_f32 v48, v46, v47
	v_cvt_pk_bf16_f32 v49, v44, v45
	global_store_dwordx2 v[6:7], v[48:49], off
	s_waitcnt lgkmcnt(0)
	v_add_f32_e32 v4, v4, v5
	s_nop 1
	v_mov_b32_dpp v5, v4 quad_perm:[2,3,0,1] row_mask:0xf bank_mask:0xf
	s_waitcnt lgkmcnt(0)
	v_add_f32_e32 v4, v4, v5
	s_nop 1
	v_mov_b32_dpp v5, v4 row_ror:12 row_mask:0xf bank_mask:0xf
	s_waitcnt lgkmcnt(0)
	v_add_f32_e32 v4, v4, v5
	s_nop 1
	v_mov_b32_dpp v5, v4 row_ror:8 row_mask:0xf bank_mask:0xf
	s_waitcnt lgkmcnt(0)
	v_add_f32_e32 v4, v4, v5
	v_mov_b32_e32 v5, v4
	s_nop 1
	v_permlane16_swap_b32_e32 v4, v5
	s_waitcnt lgkmcnt(0)
	v_add_f32_e32 v4, v4, v5
	v_mov_b32_e32 v5, v4
	s_nop 1
	v_permlane32_swap_b32_e32 v4, v5
	s_and_saveexec_b64 s[4:5], vcc
	s_cbranch_execz .LBB0_1674
	s_lshl_b64 s[2:3], s[2:3], 5
	s_add_u32 s2, s6, s2
	s_addc_u32 s3, s7, s3
	v_mov_b32_e32 v6, 0
	s_waitcnt lgkmcnt(0)
	v_add_f32_e32 v4, v4, v5
	global_store_dword v6, v4, s[2:3] sc1
; #define LAS __attribute__((address_space(3)))
; __device__ __forceinline__ f32x4 ld_bf4(const bf16_t* p) { u32x2 w = *(const u32x2*)p; return (f32x4){__uint_as_float(w.x << 16), __uint_as_float(w.x & 0xffff0000u), __uint_as_float(w.y << 16), __uint_as_float(w.y & 0xffff0000u)}; }
; __device__ __forceinline__ void st_bf4(bf16_t* p, f32x4 v) { u32x2 w; w.x = pk2(v[0], v[1]); w.y = pk2(v[2], v[3]); *(u32x2*)p = w; }
; __device__ __forceinline__ float wave_sum(float v) {
; #pragma unroll
;     for (int o = 1; o < 64; o <<= 1) v += __shfl_xor(v, o);
;     return v;
; template <int MODOFF, int STORE  , bool BASE_BF16>
; __device__ __forceinline__ void epi_rows_part1(LAS unsigned char* lds, const f32x4 (&acc)[2][2][4][2], const Unit& u, const float* base, const float* mod, float* outp, float* slots, f32x4 (&xr)[2][16]) {
;     ...
;         for (int j = 0; j < 16; ++j) { const int rl = wid * 16 + j, row = u.pm * BM + ai * HALF + rl; const size_t o = (size_t)row * DM + colg;
;             const f32x4 v = *(const LAS f32x4*)(T + rl * 256 + ((lane ^ j) << 2));
;             const f32x4 bs = BASE_BF16 ? ld_bf4((const bf16_t*)base + o) : *(const f32x4*)(base + o);
;             const f32x4 x1 = bs + gt * v; xr[ai][j] = x1; if (STORE == 2) st_bf4((bf16_t*)outp + o, x1);
;             const float sq = wave_sum((x1[0] * x1[0] + x1[1] * x1[1]) + (x1[2] * x1[2] + x1[3] * x1[3]));
;             if (lane == 0) __hip_atomic_store((unsigned*)slots + (size_t)row * 8 + u.pn, __float_as_uint(sq), __ATOMIC_RELAXED, __HIP_MEMORY_SCOPE_AGENT); }
.LBB0_1674:
	s_or_b64 exec, exec, s[4:5]
	s_add_i32 s2, s18, s24
	s_ashr_i32 s3, s2, 31
	s_lshl_b64 s[4:5], s[2:3], 11
	v_readlane_b32 s72, v254, 1
	v_lshl_add_u64 v[54:55], s[4:5], 0, v[132:133]
	v_readlane_b32 s73, v254, 2
	ds_read_b128 v[50:53], v148
	v_readlane_b32 s74, v254, 3
	s_waitcnt lgkmcnt(1)
	v_lshl_add_u64 v[4:5], v[54:55], 2, s[72:73]
	v_readlane_b32 s75, v254, 4
	v_readlane_b32 s76, v254, 5
	v_readlane_b32 s77, v254, 6
	v_readlane_b32 s78, v254, 7
	v_readlane_b32 s79, v254, 8
	v_readlane_b32 s80, v254, 9
	v_readlane_b32 s81, v254, 10
	v_readlane_b32 s82, v254, 11
	v_readlane_b32 s83, v254, 12
	v_readlane_b32 s84, v254, 13
	v_readlane_b32 s85, v254, 14
	v_readlane_b32 s86, v254, 15
	v_readlane_b32 s87, v254, 16
	s_waitcnt vmcnt(25) lgkmcnt(0)
	v_mov_b32_e32 v4, v212
	v_mov_b32_e32 v5, v213
	v_mov_b32_e32 v6, v214
	v_mov_b32_e32 v7, v215
	v_pk_fma_f32 v[48:49], v[2:3], v[52:53], v[6:7]
	v_pk_fma_f32 v[50:51], v[0:1], v[50:51], v[4:5]
	v_mul_f32_e32 v5, v49, v49
	v_mul_f32_e32 v4, v51, v51
	v_fmac_f32_e32 v4, v50, v50
	v_fmac_f32_e32 v5, v48, v48
	v_add_f32_e32 v4, v4, v5
	s_nop 1
	v_mov_b32_dpp v5, v4 quad_perm:[1,0,3,2] row_mask:0xf bank_mask:0xf
	v_lshl_add_u64 v[6:7], v[54:55], 1, s[64:65]
	v_cvt_pk_bf16_f32 v52, v50, v51
	v_cvt_pk_bf16_f32 v53, v48, v49
	global_store_dwordx2 v[6:7], v[52:53], off
	s_waitcnt lgkmcnt(0)
	v_add_f32_e32 v4, v4, v5
	s_nop 1
	v_mov_b32_dpp v5, v4 quad_perm:[2,3,0,1] row_mask:0xf bank_mask:0xf
	s_waitcnt lgkmcnt(0)
	v_add_f32_e32 v4, v4, v5
	s_nop 1
	v_mov_b32_dpp v5, v4 row_ror:12 row_mask:0xf bank_mask:0xf
	s_waitcnt lgkmcnt(0)
	v_add_f32_e32 v4, v4, v5
	s_nop 1
	v_mov_b32_dpp v5, v4 row_ror:8 row_mask:0xf bank_mask:0xf
	s_waitcnt lgkmcnt(0)
	v_add_f32_e32 v4, v4, v5
	v_mov_b32_e32 v5, v4
	s_nop 1
	v_permlane16_swap_b32_e32 v4, v5
	s_waitcnt lgkmcnt(0)
	v_add_f32_e32 v4, v4, v5
	v_mov_b32_e32 v5, v4
	s_nop 1
	v_permlane32_swap_b32_e32 v4, v5
	s_and_saveexec_b64 s[4:5], vcc
	s_cbranch_execz .LBB0_1676
	s_lshl_b64 s[2:3], s[2:3], 5
	s_add_u32 s2, s6, s2
	s_addc_u32 s3, s7, s3
	v_mov_b32_e32 v6, 0
	s_waitcnt lgkmcnt(0)
	v_add_f32_e32 v4, v4, v5
	global_store_dword v6, v4, s[2:3] sc1
.LBB0_1676:
	s_or_b64 exec, exec, s[4:5]
	s_add_i32 s2, s19, s24
	s_ashr_i32 s3, s2, 31
	s_lshl_b64 s[4:5], s[2:3], 11
	v_readlane_b32 s72, v254, 1
	v_lshl_add_u64 v[58:59], s[4:5], 0, v[132:133]
	v_readlane_b32 s73, v254, 2
	ds_read_b128 v[54:57], v149
	v_readlane_b32 s74, v254, 3
	s_waitcnt lgkmcnt(1)
	v_lshl_add_u64 v[4:5], v[58:59], 2, s[72:73]
	v_readlane_b32 s75, v254, 4
	v_readlane_b32 s76, v254, 5
	v_readlane_b32 s77, v254, 6
	v_readlane_b32 s78, v254, 7
	v_readlane_b32 s79, v254, 8
	v_readlane_b32 s80, v254, 9
	v_readlane_b32 s81, v254, 10
	v_readlane_b32 s82, v254, 11
	v_readlane_b32 s83, v254, 12
	v_readlane_b32 s84, v254, 13
	v_readlane_b32 s85, v254, 14
	v_readlane_b32 s86, v254, 15
	v_readlane_b32 s87, v254, 16
	s_waitcnt vmcnt(26) lgkmcnt(0)
	v_mov_b32_e32 v4, v216
	v_mov_b32_e32 v5, v217
	v_mov_b32_e32 v6, v218
	v_mov_b32_e32 v7, v219
	v_pk_fma_f32 v[52:53], v[2:3], v[56:57], v[6:7]
	v_pk_fma_f32 v[54:55], v[0:1], v[54:55], v[4:5]
	v_mul_f32_e32 v5, v53, v53
	v_mul_f32_e32 v4, v55, v55
	v_fmac_f32_e32 v4, v54, v54
	v_fmac_f32_e32 v5, v52, v52
	v_add_f32_e32 v4, v4, v5
	s_nop 1
	v_mov_b32_dpp v5, v4 quad_perm:[1,0,3,2] row_mask:0xf bank_mask:0xf
	v_lshl_add_u64 v[6:7], v[58:59], 1, s[64:65]
	v_cvt_pk_bf16_f32 v56, v54, v55
	v_cvt_pk_bf16_f32 v57, v52, v53
	global_store_dwordx2 v[6:7], v[56:57], off
	s_waitcnt lgkmcnt(0)
	v_add_f32_e32 v4, v4, v5
	s_nop 1
	v_mov_b32_dpp v5, v4 quad_perm:[2,3,0,1] row_mask:0xf bank_mask:0xf
	s_waitcnt lgkmcnt(0)
	v_add_f32_e32 v4, v4, v5
	s_nop 1
	v_mov_b32_dpp v5, v4 row_ror:12 row_mask:0xf bank_mask:0xf
	s_waitcnt lgkmcnt(0)
	v_add_f32_e32 v4, v4, v5
	s_nop 1
	v_mov_b32_dpp v5, v4 row_ror:8 row_mask:0xf bank_mask:0xf
	s_waitcnt lgkmcnt(0)
	v_add_f32_e32 v4, v4, v5
	v_mov_b32_e32 v5, v4
	s_nop 1
	v_permlane16_swap_b32_e32 v4, v5
	s_waitcnt lgkmcnt(0)
	v_add_f32_e32 v4, v4, v5
	v_mov_b32_e32 v5, v4
	s_nop 1
	v_permlane32_swap_b32_e32 v4, v5
	s_and_saveexec_b64 s[4:5], vcc
	s_cbranch_execz .LBB0_1678
	s_lshl_b64 s[2:3], s[2:3], 5
	s_add_u32 s2, s6, s2
	s_addc_u32 s3, s7, s3
	v_mov_b32_e32 v6, 0
	s_waitcnt lgkmcnt(0)
	v_add_f32_e32 v4, v4, v5
	global_store_dword v6, v4, s[2:3] sc1
.LBB0_1678:
	s_or_b64 exec, exec, s[4:5]
	s_add_i32 s2, s20, s24
	s_ashr_i32 s3, s2, 31
	s_lshl_b64 s[4:5], s[2:3], 11
	v_readlane_b32 s72, v254, 1
	v_lshl_add_u64 v[62:63], s[4:5], 0, v[132:133]
	v_readlane_b32 s73, v254, 2
	ds_read_b128 v[58:61], v150
	v_readlane_b32 s74, v254, 3
	s_waitcnt lgkmcnt(1)
	v_lshl_add_u64 v[4:5], v[62:63], 2, s[72:73]
	v_readlane_b32 s75, v254, 4
	v_readlane_b32 s76, v254, 5
	v_readlane_b32 s77, v254, 6
	v_readlane_b32 s78, v254, 7
	v_readlane_b32 s79, v254, 8
	v_readlane_b32 s80, v254, 9
	v_readlane_b32 s81, v254, 10
	v_readlane_b32 s82, v254, 11
	v_readlane_b32 s83, v254, 12
	v_readlane_b32 s84, v254, 13
	v_readlane_b32 s85, v254, 14
	v_readlane_b32 s86, v254, 15
	v_readlane_b32 s87, v254, 16
	s_waitcnt vmcnt(27) lgkmcnt(0)
	v_mov_b32_e32 v4, v220
	v_mov_b32_e32 v5, v221
	v_mov_b32_e32 v6, v222
	v_mov_b32_e32 v7, v223
	v_pk_fma_f32 v[56:57], v[2:3], v[60:61], v[6:7]
	v_pk_fma_f32 v[58:59], v[0:1], v[58:59], v[4:5]
	v_mul_f32_e32 v5, v57, v57
	v_mul_f32_e32 v4, v59, v59
	v_fmac_f32_e32 v4, v58, v58
	v_fmac_f32_e32 v5, v56, v56
	v_add_f32_e32 v4, v4, v5
	s_nop 1
	v_mov_b32_dpp v5, v4 quad_perm:[1,0,3,2] row_mask:0xf bank_mask:0xf
	v_lshl_add_u64 v[6:7], v[62:63], 1, s[64:65]
	v_cvt_pk_bf16_f32 v60, v58, v59
	v_cvt_pk_bf16_f32 v61, v56, v57
	global_store_dwordx2 v[6:7], v[60:61], off
	s_waitcnt lgkmcnt(0)
	v_add_f32_e32 v4, v4, v5
	s_nop 1
	v_mov_b32_dpp v5, v4 quad_perm:[2,3,0,1] row_mask:0xf bank_mask:0xf
	s_waitcnt lgkmcnt(0)
	v_add_f32_e32 v4, v4, v5
	s_nop 1
	v_mov_b32_dpp v5, v4 row_ror:12 row_mask:0xf bank_mask:0xf
	s_waitcnt lgkmcnt(0)
	v_add_f32_e32 v4, v4, v5
	s_nop 1
	v_mov_b32_dpp v5, v4 row_ror:8 row_mask:0xf bank_mask:0xf
	s_waitcnt lgkmcnt(0)
	v_add_f32_e32 v4, v4, v5
	v_mov_b32_e32 v5, v4
	s_nop 1
	v_permlane16_swap_b32_e32 v4, v5
	s_waitcnt lgkmcnt(0)
	v_add_f32_e32 v4, v4, v5
	v_mov_b32_e32 v5, v4
	s_nop 1
	v_permlane32_swap_b32_e32 v4, v5
	s_and_saveexec_b64 s[4:5], vcc
	s_cbranch_execz .LBB0_1680
	s_lshl_b64 s[2:3], s[2:3], 5
	s_add_u32 s2, s6, s2
	s_addc_u32 s3, s7, s3
	v_mov_b32_e32 v6, 0
	s_waitcnt lgkmcnt(0)
	v_add_f32_e32 v4, v4, v5
	global_store_dword v6, v4, s[2:3] sc1
; #define LAS __attribute__((address_space(3)))
; __device__ __forceinline__ f32x4 ld_bf4(const bf16_t* p) { u32x2 w = *(const u32x2*)p; return (f32x4){__uint_as_float(w.x << 16), __uint_as_float(w.x & 0xffff0000u), __uint_as_float(w.y << 16), __uint_as_float(w.y & 0xffff0000u)}; }
; __device__ __forceinline__ void st_bf4(bf16_t* p, f32x4 v) { u32x2 w; w.x = pk2(v[0], v[1]); w.y = pk2(v[2], v[3]); *(u32x2*)p = w; }
; __device__ __forceinline__ float wave_sum(float v) {
; #pragma unroll
;     for (int o = 1; o < 64; o <<= 1) v += __shfl_xor(v, o);
;     return v;
; template <int MODOFF, int STORE  , bool BASE_BF16>
; __device__ __forceinline__ void epi_rows_part1(LAS unsigned char* lds, const f32x4 (&acc)[2][2][4][2], const Unit& u, const float* base, const float* mod, float* outp, float* slots, f32x4 (&xr)[2][16]) {
;     ...
;         for (int j = 0; j < 16; ++j) { const int rl = wid * 16 + j, row = u.pm * BM + ai * HALF + rl; const size_t o = (size_t)row * DM + colg;
;             const f32x4 v = *(const LAS f32x4*)(T + rl * 256 + ((lane ^ j) << 2));
;             const f32x4 bs = BASE_BF16 ? ld_bf4((const bf16_t*)base + o) : *(const f32x4*)(base + o);
;             const f32x4 x1 = bs + gt * v; xr[ai][j] = x1; if (STORE == 2) st_bf4((bf16_t*)outp + o, x1);
;             const float sq = wave_sum((x1[0] * x1[0] + x1[1] * x1[1]) + (x1[2] * x1[2] + x1[3] * x1[3]));
;             if (lane == 0) __hip_atomic_store((unsigned*)slots + (size_t)row * 8 + u.pn, __float_as_uint(sq), __ATOMIC_RELAXED, __HIP_MEMORY_SCOPE_AGENT); }
.LBB0_1680:
	s_or_b64 exec, exec, s[4:5]
	s_add_i32 s2, s21, s24
	s_ashr_i32 s3, s2, 31
	s_lshl_b64 s[4:5], s[2:3], 11
	v_readlane_b32 s72, v254, 1
	v_lshl_add_u64 v[66:67], s[4:5], 0, v[132:133]
	v_readlane_b32 s73, v254, 2
	ds_read_b128 v[62:65], v151
	v_readlane_b32 s74, v254, 3
	s_waitcnt lgkmcnt(1)
	v_lshl_add_u64 v[4:5], v[66:67], 2, s[72:73]
	v_readlane_b32 s75, v254, 4
	v_readlane_b32 s76, v254, 5
	v_readlane_b32 s77, v254, 6
	v_readlane_b32 s78, v254, 7
	v_readlane_b32 s79, v254, 8
	v_readlane_b32 s80, v254, 9
	v_readlane_b32 s81, v254, 10
	v_readlane_b32 s82, v254, 11
	v_readlane_b32 s83, v254, 12
	v_readlane_b32 s84, v254, 13
	v_readlane_b32 s85, v254, 14
	v_readlane_b32 s86, v254, 15
	v_readlane_b32 s87, v254, 16
	s_waitcnt vmcnt(28) lgkmcnt(0)
	v_mov_b32_e32 v4, v224
	v_mov_b32_e32 v5, v225
	v_mov_b32_e32 v6, v226
	v_mov_b32_e32 v7, v227
	v_pk_fma_f32 v[60:61], v[2:3], v[64:65], v[6:7]
	v_pk_fma_f32 v[62:63], v[0:1], v[62:63], v[4:5]
	v_mul_f32_e32 v5, v61, v61
	v_mul_f32_e32 v4, v63, v63
	v_fmac_f32_e32 v4, v62, v62
	v_fmac_f32_e32 v5, v60, v60
	v_add_f32_e32 v4, v4, v5
	s_nop 1
	v_mov_b32_dpp v5, v4 quad_perm:[1,0,3,2] row_mask:0xf bank_mask:0xf
	v_lshl_add_u64 v[6:7], v[66:67], 1, s[64:65]
	v_cvt_pk_bf16_f32 v64, v62, v63
	v_cvt_pk_bf16_f32 v65, v60, v61
	global_store_dwordx2 v[6:7], v[64:65], off
	s_waitcnt lgkmcnt(0)
	v_add_f32_e32 v4, v4, v5
	s_nop 1
	v_mov_b32_dpp v5, v4 quad_perm:[2,3,0,1] row_mask:0xf bank_mask:0xf
	s_waitcnt lgkmcnt(0)
	v_add_f32_e32 v4, v4, v5
	s_nop 1
	v_mov_b32_dpp v5, v4 row_ror:12 row_mask:0xf bank_mask:0xf
	s_waitcnt lgkmcnt(0)
	v_add_f32_e32 v4, v4, v5
	s_nop 1
	v_mov_b32_dpp v5, v4 row_ror:8 row_mask:0xf bank_mask:0xf
	s_waitcnt lgkmcnt(0)
	v_add_f32_e32 v4, v4, v5
	v_mov_b32_e32 v5, v4
	s_nop 1
	v_permlane16_swap_b32_e32 v4, v5
	s_waitcnt lgkmcnt(0)
	v_add_f32_e32 v4, v4, v5
	v_mov_b32_e32 v5, v4
	s_nop 1
	v_permlane32_swap_b32_e32 v4, v5
	s_and_saveexec_b64 s[4:5], vcc
	s_cbranch_execz .LBB0_1682
	s_lshl_b64 s[2:3], s[2:3], 5
	s_add_u32 s2, s6, s2
	s_addc_u32 s3, s7, s3
	v_mov_b32_e32 v6, 0
	s_waitcnt lgkmcnt(0)
	v_add_f32_e32 v4, v4, v5
	global_store_dword v6, v4, s[2:3] sc1
.LBB0_1682:
	s_or_b64 exec, exec, s[4:5]
	s_add_i32 s2, s22, s24
	s_ashr_i32 s3, s2, 31
	s_lshl_b64 s[4:5], s[2:3], 11
	v_readlane_b32 s72, v254, 1
	v_lshl_add_u64 v[138:139], s[4:5], 0, v[132:133]
	v_readlane_b32 s73, v254, 2
	ds_read_b128 v[134:137], v152
	v_readlane_b32 s74, v254, 3
	s_waitcnt lgkmcnt(1)
	v_lshl_add_u64 v[4:5], v[138:139], 2, s[72:73]
	v_readlane_b32 s75, v254, 4
	v_readlane_b32 s76, v254, 5
	v_readlane_b32 s77, v254, 6
	v_readlane_b32 s78, v254, 7
	v_readlane_b32 s79, v254, 8
	v_readlane_b32 s80, v254, 9
	v_readlane_b32 s81, v254, 10
	v_readlane_b32 s82, v254, 11
	v_readlane_b32 s83, v254, 12
	v_readlane_b32 s84, v254, 13
	v_readlane_b32 s85, v254, 14
	v_readlane_b32 s86, v254, 15
	v_readlane_b32 s87, v254, 16
	s_waitcnt vmcnt(29) lgkmcnt(0)
	v_mov_b32_e32 v4, v228
	v_mov_b32_e32 v5, v229
	v_mov_b32_e32 v6, v230
	v_mov_b32_e32 v7, v231
	v_pk_fma_f32 v[64:65], v[2:3], v[136:137], v[6:7]
	v_pk_fma_f32 v[66:67], v[0:1], v[134:135], v[4:5]
	v_mul_f32_e32 v5, v65, v65
	v_mul_f32_e32 v4, v67, v67
	v_fmac_f32_e32 v4, v66, v66
	v_fmac_f32_e32 v5, v64, v64
	v_add_f32_e32 v4, v4, v5
	s_nop 1
	v_mov_b32_dpp v5, v4 quad_perm:[1,0,3,2] row_mask:0xf bank_mask:0xf
	v_lshl_add_u64 v[6:7], v[138:139], 1, s[64:65]
	v_cvt_pk_bf16_f32 v134, v66, v67
	v_cvt_pk_bf16_f32 v135, v64, v65
	global_store_dwordx2 v[6:7], v[134:135], off
	s_waitcnt lgkmcnt(0)
	v_add_f32_e32 v4, v4, v5
	s_nop 1
	v_mov_b32_dpp v5, v4 quad_perm:[2,3,0,1] row_mask:0xf bank_mask:0xf
	s_waitcnt lgkmcnt(0)
	v_add_f32_e32 v4, v4, v5
	s_nop 1
	v_mov_b32_dpp v5, v4 row_ror:12 row_mask:0xf bank_mask:0xf
	s_waitcnt lgkmcnt(0)
	v_add_f32_e32 v4, v4, v5
	s_nop 1
	v_mov_b32_dpp v5, v4 row_ror:8 row_mask:0xf bank_mask:0xf
	s_waitcnt lgkmcnt(0)
	v_add_f32_e32 v4, v4, v5
	v_mov_b32_e32 v5, v4
	s_nop 1
	v_permlane16_swap_b32_e32 v4, v5
	s_waitcnt lgkmcnt(0)
	v_add_f32_e32 v4, v4, v5
	v_mov_b32_e32 v5, v4
	s_nop 1
	v_permlane32_swap_b32_e32 v4, v5
	s_and_saveexec_b64 s[4:5], vcc
	s_cbranch_execz .LBB0_1684
	s_lshl_b64 s[2:3], s[2:3], 5
	s_add_u32 s2, s6, s2
	s_addc_u32 s3, s7, s3
	v_mov_b32_e32 v6, 0
	s_waitcnt lgkmcnt(0)
	v_add_f32_e32 v4, v4, v5
	global_store_dword v6, v4, s[2:3] sc1
.LBB0_1684:
	s_or_b64 exec, exec, s[4:5]
	s_add_i32 s2, s23, s24
	s_ashr_i32 s3, s2, 31
	s_lshl_b64 s[4:5], s[2:3], 11
	v_readlane_b32 s8, v254, 1
	v_lshl_add_u64 v[138:139], s[4:5], 0, v[132:133]
	v_readlane_b32 s9, v254, 2
	ds_read_b128 v[134:137], v153
	v_readlane_b32 s10, v254, 3
	s_waitcnt lgkmcnt(1)
	v_lshl_add_u64 v[4:5], v[138:139], 2, s[8:9]
	v_readlane_b32 s11, v254, 4
	v_readlane_b32 s12, v254, 5
	v_readlane_b32 s13, v254, 6
	v_readlane_b32 s14, v254, 7
	v_readlane_b32 s15, v254, 8
	v_readlane_b32 s16, v254, 9
	v_readlane_b32 s17, v254, 10
	v_readlane_b32 s18, v254, 11
	v_readlane_b32 s19, v254, 12
	v_readlane_b32 s20, v254, 13
	v_readlane_b32 s21, v254, 14
	v_readlane_b32 s22, v254, 15
	v_readlane_b32 s23, v254, 16
	s_waitcnt vmcnt(30) lgkmcnt(0)
	v_mov_b32_e32 v4, v232
	v_mov_b32_e32 v5, v233
	v_mov_b32_e32 v6, v234
	v_mov_b32_e32 v7, v235
	v_pk_fma_f32 v[132:133], v[2:3], v[136:137], v[6:7]
	v_pk_fma_f32 v[134:135], v[0:1], v[134:135], v[4:5]
	v_mul_f32_e32 v1, v133, v133
	v_mul_f32_e32 v0, v135, v135
	v_fmac_f32_e32 v0, v134, v134
	v_fmac_f32_e32 v1, v132, v132
	v_add_f32_e32 v0, v0, v1
	s_nop 1
	v_mov_b32_dpp v1, v0 quad_perm:[1,0,3,2] row_mask:0xf bank_mask:0xf
	v_lshl_add_u64 v[2:3], v[138:139], 1, s[64:65]
	v_cvt_pk_bf16_f32 v4, v134, v135
	v_cvt_pk_bf16_f32 v5, v132, v133
	global_store_dwordx2 v[2:3], v[4:5], off
	s_waitcnt lgkmcnt(0)
	v_add_f32_e32 v0, v0, v1
	s_nop 1
	v_mov_b32_dpp v1, v0 quad_perm:[2,3,0,1] row_mask:0xf bank_mask:0xf
	s_waitcnt lgkmcnt(0)
	v_add_f32_e32 v0, v0, v1
	s_nop 1
	v_mov_b32_dpp v1, v0 row_ror:12 row_mask:0xf bank_mask:0xf
	s_waitcnt lgkmcnt(0)
	v_add_f32_e32 v0, v0, v1
	s_nop 1
	v_mov_b32_dpp v1, v0 row_ror:8 row_mask:0xf bank_mask:0xf
	s_waitcnt lgkmcnt(0)
	v_add_f32_e32 v0, v0, v1
	v_mov_b32_e32 v1, v0
	s_nop 1
	v_permlane16_swap_b32_e32 v0, v1
	s_waitcnt lgkmcnt(0)
	v_add_f32_e32 v0, v0, v1
	v_mov_b32_e32 v1, v0
	s_nop 1
	v_permlane32_swap_b32_e32 v0, v1
	s_and_saveexec_b64 s[4:5], vcc
	s_cbranch_execz .LBB0_1686
	s_lshl_b64 s[2:3], s[2:3], 5
	s_add_u32 s2, s6, s2
	s_addc_u32 s3, s7, s3
	v_mov_b32_e32 v2, 0
	s_waitcnt lgkmcnt(0)
	v_add_f32_e32 v0, v0, v1
	global_store_dword v2, v0, s[2:3] sc1

; #define LAS __attribute__((address_space(3)))
; __device__ __forceinline__ f32x4 ld_bf4(const bf16_t* p) { u32x2 w = *(const u32x2*)p; return (f32x4){__uint_as_float(w.x << 16), __uint_as_float(w.x & 0xffff0000u), __uint_as_float(w.y << 16), __uint_as_float(w.y & 0xffff0000u)}; }
; __device__ __forceinline__ void st_bf4(bf16_t* p, f32x4 v) { u32x2 w; w.x = pk2(v[0], v[1]); w.y = pk2(v[2], v[3]); *(u32x2*)p = w; }
; #define LBAR() do { asm volatile("s_waitcnt lgkmcnt(0)" ::: "memory"); __builtin_amdgcn_s_barrier(); asm volatile("" ::: "memory"); } while (0)
; __device__ __forceinline__ float wave_sum(float v) {
; #pragma unroll
;     for (int o = 1; o < 64; o <<= 1) v += __shfl_xor(v, o);
;     return v;
; template <int MODOFF, int STORE  , bool BASE_BF16>
; __device__ __forceinline__ void epi_rows_part1(LAS unsigned char* lds, const f32x4 (&acc)[2][2][4][2], const Unit& u, const float* base, const float* mod, float* outp, float* slots, f32x4 (&xr)[2][16]) {
;     ...
;     const int colg = u.pn * BM + 4 * lane;
;     const f32x4 gt = *(const f32x4*)(mod + ((u.pm * BM) >> 11) * MODW + MODOFF * DM + colg);
; #pragma unroll
;     for (int ai = 0; ai < 2; ++ai) {
;         if (ai) LBAR();
; #pragma unroll
;         for (int m = 0; m < 4; ++m)
; #pragma unroll
;             for (int bj = 0; bj < 2; ++bj)
; #pragma unroll
;                 for (int n = 0; n < 2; ++n) { const int rl = wr * 64 + m * 16 + fr, c4 = (bj * HALF + wc * 32 + n * 16 + 4 * fq) >> 2;
;                     *(LAS f32x4*)(T + rl * 256 + ((c4 ^ (rl & 15)) << 2)) = acc[ai][bj][m][n]; }
;         LBAR();
; #pragma unroll
;         for (int j = 0; j < 16; ++j) { const int rl = wid * 16 + j, row = u.pm * BM + ai * HALF + rl; const size_t o = (size_t)row * DM + colg;
;             const f32x4 v = *(const LAS f32x4*)(T + rl * 256 + ((lane ^ j) << 2));
;             const f32x4 bs = BASE_BF16 ? ld_bf4((const bf16_t*)base + o) : *(const f32x4*)(base + o);
;             const f32x4 x1 = bs + gt * v; xr[ai][j] = x1; if (STORE == 2) st_bf4((bf16_t*)outp + o, x1);
;             const float sq = wave_sum((x1[0] * x1[0] + x1[1] * x1[1]) + (x1[2] * x1[2] + x1[3] * x1[3]));
;             if (lane == 0) __hip_atomic_store((unsigned*)slots + (size_t)row * 8 + u.pn, __float_as_uint(sq), __ATOMIC_RELAXED, __HIP_MEMORY_SCOPE_AGENT); }
.LBB0_1893:
	s_add_u32 s33, s66, 0x90000
	s_addc_u32 s44, s67, 0
	s_lshr_b32 s0, s7, 3
	v_mov_b32_e32 v134, v189
	s_mulk_i32 s0, 0x3000
	s_ashr_i32 s1, s0, 31
	v_readfirstlane_b32 s2, v134
	s_ashr_i32 s9, s2, 6
	v_and_b32_e32 v139, 63, v134
	s_lshl_b32 s45, s6, 8
	s_lshl_b64 s[0:1], s[0:1], 2
	v_lshl_or_b32 v132, v139, 2, s45
	s_add_u32 s0, s92, s0
	s_addc_u32 s1, s93, s1
	v_ashrrev_i32_e32 v133, 31, v132
	v_lshl_add_u64 v[64:65], v[132:133], 2, s[0:1]
	s_mov_b32 s0, 0xa000
	v_add_co_u32_e32 v64, vcc, s0, v64
	s_lshr_b32 s0, s2, 2
	v_and_b32_e32 v135, 15, v134
	s_and_b32 s0, s0, 0x3fffc0
	v_or_b32_e32 v138, s0, v135
	s_lshl_b32 s0, s9, 5
	v_lshrrev_b32_e32 v134, 2, v134
	s_and_b32 s2, s0, 0x60
	v_and_b32_e32 v134, 12, v134
	v_lshlrev_b32_e32 v135, 2, v135
	v_lshl_add_u64 v[136:137], v[132:133], 1, s[64:65]
	v_lshl_add_u32 v138, v138, 10, 0
	v_bitop3_b32 v132, s2, v135, v134 bitop3:0x36
	v_or_b32_e32 v140, s2, v134
	s_lshl_b32 s46, s7, 8
	s_ashr_i32 s7, s6, 31
	v_lshl_add_u32 v132, v132, 2, v138
	s_lshl_b32 s8, s9, 4
	s_lshl_b64 s[0:1], s[6:7], 2
	ds_write_b128 v132, v[128:131]
	v_bitop3_b32 v128, v140, v135, 16 bitop3:0x36
	s_add_u32 s4, s33, s0
	v_lshl_add_u32 v133, v128, 2, v138
	s_movk_i32 s0, 0x80
	ds_write_b128 v133, v[124:127]
	v_bitop3_b32 v124, v140, v135, s0 bitop3:0x36
	v_lshl_add_u32 v134, v124, 2, v138
	s_movk_i32 s0, 0x90
	s_addc_u32 s5, s44, s1
	ds_write_b128 v134, v[120:123]
	v_bitop3_b32 v120, v140, v135, s0 bitop3:0x36
	s_add_i32 s0, s8, s46
	v_addc_co_u32_e32 v65, vcc, 0, v65, vcc
	v_lshl_add_u32 v135, v120, 2, v138
	s_ashr_i32 s1, s0, 31
	global_load_dwordx4 v[64:67], v[64:65], off
	ds_write_b128 v135, v[116:119]
	ds_write_b128 v132, v[112:115] offset:16384
	ds_write_b128 v133, v[108:111] offset:16384
	ds_write_b128 v134, v[104:107] offset:16384
	ds_write_b128 v135, v[100:103] offset:16384
	ds_write_b128 v132, v[96:99] offset:32768
	ds_write_b128 v133, v[92:95] offset:32768
	ds_write_b128 v134, v[88:91] offset:32768
	ds_write_b128 v135, v[84:87] offset:32768
	ds_write_b128 v132, v[80:83] offset:49152
	ds_write_b128 v133, v[76:79] offset:49152
	ds_write_b128 v134, v[72:75] offset:49152
	ds_write_b128 v135, v[68:71] offset:49152
	s_lshl_b64 s[2:3], s[0:1], 12
	s_waitcnt lgkmcnt(0)
	s_barrier
	v_lshl_add_u64 v[68:69], v[136:137], 0, s[2:3]
	s_mov_b64 s[98:99], 0x1000
	global_load_dwordx2 v[164:165], v[68:69], off
	v_lshl_add_u64 v[252:253], v[68:69], 0, s[98:99]
	global_load_dwordx2 v[168:169], v[252:253], off
	v_lshl_add_u64 v[252:253], v[252:253], 0, s[98:99]
	global_load_dwordx2 v[172:173], v[252:253], off
	v_lshl_add_u64 v[252:253], v[252:253], 0, s[98:99]
	global_load_dwordx2 v[176:177], v[252:253], off
	v_lshl_add_u64 v[252:253], v[252:253], 0, s[98:99]
	global_load_dwordx2 v[180:181], v[252:253], off
	v_lshl_add_u64 v[252:253], v[252:253], 0, s[98:99]
	global_load_dwordx2 v[184:185], v[252:253], off
	v_lshl_add_u64 v[252:253], v[252:253], 0, s[98:99]
	global_load_dwordx2 v[196:197], v[252:253], off
	v_lshl_add_u64 v[252:253], v[252:253], 0, s[98:99]
	global_load_dwordx2 v[200:201], v[252:253], off
	v_lshl_add_u64 v[252:253], v[252:253], 0, s[98:99]
	global_load_dwordx2 v[204:205], v[252:253], off
	v_lshl_add_u64 v[252:253], v[252:253], 0, s[98:99]
	global_load_dwordx2 v[208:209], v[252:253], off
	v_lshl_add_u64 v[252:253], v[252:253], 0, s[98:99]
	global_load_dwordx2 v[212:213], v[252:253], off
	v_lshl_add_u64 v[252:253], v[252:253], 0, s[98:99]
	global_load_dwordx2 v[216:217], v[252:253], off
	v_lshl_add_u64 v[252:253], v[252:253], 0, s[98:99]
	global_load_dwordx2 v[220:221], v[252:253], off
	v_lshl_add_u64 v[252:253], v[252:253], 0, s[98:99]
	global_load_dwordx2 v[224:225], v[252:253], off
	v_lshl_add_u64 v[252:253], v[252:253], 0, s[98:99]
	global_load_dwordx2 v[228:229], v[252:253], off
	v_lshl_add_u64 v[252:253], v[252:253], 0, s[98:99]
	global_load_dwordx2 v[232:233], v[252:253], off
	s_lshl_b32 s2, s9, 14
	v_lshlrev_b32_e32 v124, 4, v139
	s_add_i32 s2, s2, 0
	v_add_u32_e32 v138, s2, v124
	ds_read_b128 v[70:73], v138
	v_cmp_eq_u32_e32 vcc, 0, v139
	s_waitcnt vmcnt(15)
	v_mov_b32_e32 v68, v164
	v_mov_b32_e32 v69, v165
	v_lshlrev_b32_e32 v74, 16, v68
	v_and_b32_e32 v75, 0xffff0000, v68
	v_lshlrev_b32_e32 v68, 16, v69
	v_and_b32_e32 v69, 0xffff0000, v69
	s_waitcnt lgkmcnt(0)
	v_pk_fma_f32 v[68:69], v[66:67], v[72:73], v[68:69]
	v_pk_fma_f32 v[72:73], v[64:65], v[70:71], v[74:75]
	v_mul_f32_e32 v71, v69, v69
	v_mul_f32_e32 v70, v73, v73
	v_fmac_f32_e32 v70, v72, v72
	v_fmac_f32_e32 v71, v68, v68
	v_add_f32_e32 v70, v70, v71
	s_nop 1
	v_mov_b32_dpp v71, v70 quad_perm:[1,0,3,2] row_mask:0xf bank_mask:0xf
	s_waitcnt lgkmcnt(0)
	v_add_f32_e32 v70, v70, v71
	s_nop 1
	v_mov_b32_dpp v71, v70 quad_perm:[2,3,0,1] row_mask:0xf bank_mask:0xf
	s_waitcnt lgkmcnt(0)
	v_add_f32_e32 v70, v70, v71
	s_nop 1
	v_mov_b32_dpp v71, v70 row_ror:12 row_mask:0xf bank_mask:0xf
	s_waitcnt lgkmcnt(0)
	v_add_f32_e32 v70, v70, v71
	s_nop 1
	v_mov_b32_dpp v71, v70 row_ror:8 row_mask:0xf bank_mask:0xf
	s_waitcnt lgkmcnt(0)
	v_add_f32_e32 v70, v70, v71
	v_mov_b32_e32 v71, v70
	s_nop 1
	v_permlane16_swap_b32_e32 v70, v71
	s_waitcnt lgkmcnt(0)
	v_add_f32_e32 v70, v70, v71
	v_mov_b32_e32 v71, v70
	s_nop 1
	v_permlane32_swap_b32_e32 v70, v71
	s_and_saveexec_b64 s[2:3], vcc
	s_cbranch_execz .LBB0_1895
	s_lshl_b64 s[0:1], s[0:1], 5
	s_add_u32 s0, s4, s0
	s_addc_u32 s1, s5, s1
	v_mov_b32_e32 v74, 0
	s_waitcnt lgkmcnt(0)
	v_add_f32_e32 v70, v70, v71
	global_store_dword v74, v70, s[0:1] sc1
; #define LAS __attribute__((address_space(3)))
; __device__ __forceinline__ f32x4 ld_bf4(const bf16_t* p) { u32x2 w = *(const u32x2*)p; return (f32x4){__uint_as_float(w.x << 16), __uint_as_float(w.x & 0xffff0000u), __uint_as_float(w.y << 16), __uint_as_float(w.y & 0xffff0000u)}; }
; __device__ __forceinline__ void st_bf4(bf16_t* p, f32x4 v) { u32x2 w; w.x = pk2(v[0], v[1]); w.y = pk2(v[2], v[3]); *(u32x2*)p = w; }
; __device__ __forceinline__ float wave_sum(float v) {
; #pragma unroll
;     for (int o = 1; o < 64; o <<= 1) v += __shfl_xor(v, o);
;     return v;
; template <int MODOFF, int STORE  , bool BASE_BF16>
; __device__ __forceinline__ void epi_rows_part1(LAS unsigned char* lds, const f32x4 (&acc)[2][2][4][2], const Unit& u, const float* base, const float* mod, float* outp, float* slots, f32x4 (&xr)[2][16]) {
;     ...
;         for (int j = 0; j < 16; ++j) { const int rl = wid * 16 + j, row = u.pm * BM + ai * HALF + rl; const size_t o = (size_t)row * DM + colg;
;             const f32x4 v = *(const LAS f32x4*)(T + rl * 256 + ((lane ^ j) << 2));
;             const f32x4 bs = BASE_BF16 ? ld_bf4((const bf16_t*)base + o) : *(const f32x4*)(base + o);
;             const f32x4 x1 = bs + gt * v; xr[ai][j] = x1; if (STORE == 2) st_bf4((bf16_t*)outp + o, x1);
;             const float sq = wave_sum((x1[0] * x1[0] + x1[1] * x1[1]) + (x1[2] * x1[2] + x1[3] * x1[3]));
;             if (lane == 0) __hip_atomic_store((unsigned*)slots + (size_t)row * 8 + u.pn, __float_as_uint(sq), __ATOMIC_RELAXED, __HIP_MEMORY_SCOPE_AGENT); }
.LBB0_1895:
	s_or_b64 exec, exec, s[2:3]
	s_or_b32 s6, s8, 1
	s_add_i32 s0, s6, s46
	s_ashr_i32 s1, s0, 31
	s_lshl_b64 s[2:3], s[0:1], 12
	s_waitcnt lgkmcnt(0)
	v_lshl_add_u64 v[70:71], v[136:137], 0, s[2:3]
	s_lshl_b32 s2, s6, 10
	v_xor_b32_e32 v74, 16, v124
	s_add_i32 s2, s2, 0
	v_add_u32_e32 v139, s2, v74
	ds_read_b128 v[74:77], v139
	s_waitcnt vmcnt(15)
	v_mov_b32_e32 v70, v168
	v_mov_b32_e32 v71, v169
	v_lshlrev_b32_e32 v78, 16, v70
	v_and_b32_e32 v79, 0xffff0000, v70
	v_lshlrev_b32_e32 v70, 16, v71
	v_and_b32_e32 v71, 0xffff0000, v71
	s_waitcnt lgkmcnt(0)
	v_pk_fma_f32 v[70:71], v[66:67], v[76:77], v[70:71]
	v_pk_fma_f32 v[76:77], v[64:65], v[74:75], v[78:79]
	v_mul_f32_e32 v75, v71, v71
	v_mul_f32_e32 v74, v77, v77
	v_fmac_f32_e32 v74, v76, v76
	v_fmac_f32_e32 v75, v70, v70
	v_add_f32_e32 v74, v74, v75
	s_nop 1
	v_mov_b32_dpp v75, v74 quad_perm:[1,0,3,2] row_mask:0xf bank_mask:0xf
	s_waitcnt lgkmcnt(0)
	v_add_f32_e32 v74, v74, v75
	s_nop 1
	v_mov_b32_dpp v75, v74 quad_perm:[2,3,0,1] row_mask:0xf bank_mask:0xf
	s_waitcnt lgkmcnt(0)
	v_add_f32_e32 v74, v74, v75
	s_nop 1
	v_mov_b32_dpp v75, v74 row_ror:12 row_mask:0xf bank_mask:0xf
	s_waitcnt lgkmcnt(0)
	v_add_f32_e32 v74, v74, v75
	s_nop 1
	v_mov_b32_dpp v75, v74 row_ror:8 row_mask:0xf bank_mask:0xf
	s_waitcnt lgkmcnt(0)
	v_add_f32_e32 v74, v74, v75
	v_mov_b32_e32 v75, v74
	s_nop 1
	v_permlane16_swap_b32_e32 v74, v75
	s_waitcnt lgkmcnt(0)
	v_add_f32_e32 v74, v74, v75
	v_mov_b32_e32 v75, v74
	s_nop 1
	v_permlane32_swap_b32_e32 v74, v75
	s_and_saveexec_b64 s[2:3], vcc
	s_cbranch_execz .LBB0_1897
	s_lshl_b64 s[0:1], s[0:1], 5
	s_add_u32 s0, s4, s0
	s_addc_u32 s1, s5, s1
	v_mov_b32_e32 v78, 0
	s_waitcnt lgkmcnt(0)
	v_add_f32_e32 v74, v74, v75
	global_store_dword v78, v74, s[0:1] sc1
.LBB0_1897:
	s_or_b64 exec, exec, s[2:3]
	s_or_b32 s7, s8, 2
	s_add_i32 s0, s7, s46
	s_ashr_i32 s1, s0, 31
	s_lshl_b64 s[2:3], s[0:1], 12
	s_waitcnt lgkmcnt(0)
	v_lshl_add_u64 v[74:75], v[136:137], 0, s[2:3]
	s_lshl_b32 s2, s7, 10
	v_xor_b32_e32 v78, 32, v124
	s_add_i32 s2, s2, 0
	v_add_u32_e32 v140, s2, v78
	ds_read_b128 v[78:81], v140
	s_waitcnt vmcnt(15)
	v_mov_b32_e32 v74, v172
	v_mov_b32_e32 v75, v173
	v_lshlrev_b32_e32 v82, 16, v74
	v_and_b32_e32 v83, 0xffff0000, v74
	v_lshlrev_b32_e32 v74, 16, v75
	v_and_b32_e32 v75, 0xffff0000, v75
	s_waitcnt lgkmcnt(0)
	v_pk_fma_f32 v[74:75], v[66:67], v[80:81], v[74:75]
	v_pk_fma_f32 v[80:81], v[64:65], v[78:79], v[82:83]
	v_mul_f32_e32 v79, v75, v75
	v_mul_f32_e32 v78, v81, v81
	v_fmac_f32_e32 v78, v80, v80
	v_fmac_f32_e32 v79, v74, v74
	v_add_f32_e32 v78, v78, v79
	s_nop 1
	v_mov_b32_dpp v79, v78 quad_perm:[1,0,3,2] row_mask:0xf bank_mask:0xf
	s_waitcnt lgkmcnt(0)
	v_add_f32_e32 v78, v78, v79
	s_nop 1
	v_mov_b32_dpp v79, v78 quad_perm:[2,3,0,1] row_mask:0xf bank_mask:0xf
	s_waitcnt lgkmcnt(0)
	v_add_f32_e32 v78, v78, v79
	s_nop 1
	v_mov_b32_dpp v79, v78 row_ror:12 row_mask:0xf bank_mask:0xf
	s_waitcnt lgkmcnt(0)
	v_add_f32_e32 v78, v78, v79
	s_nop 1
	v_mov_b32_dpp v79, v78 row_ror:8 row_mask:0xf bank_mask:0xf
	s_waitcnt lgkmcnt(0)
	v_add_f32_e32 v78, v78, v79
	v_mov_b32_e32 v79, v78
	s_nop 1
	v_permlane16_swap_b32_e32 v78, v79
	s_waitcnt lgkmcnt(0)
	v_add_f32_e32 v78, v78, v79
	v_mov_b32_e32 v79, v78
	s_nop 1
	v_permlane32_swap_b32_e32 v78, v79
	s_and_saveexec_b64 s[2:3], vcc
	s_cbranch_execz .LBB0_1899
	s_lshl_b64 s[0:1], s[0:1], 5
	s_add_u32 s0, s4, s0
	s_addc_u32 s1, s5, s1
	v_mov_b32_e32 v82, 0
	s_waitcnt lgkmcnt(0)
	v_add_f32_e32 v78, v78, v79
	global_store_dword v82, v78, s[0:1] sc1
.LBB0_1899:
	s_or_b64 exec, exec, s[2:3]
	s_or_b32 s9, s8, 3
	s_add_i32 s0, s9, s46
	s_ashr_i32 s1, s0, 31
	s_lshl_b64 s[2:3], s[0:1], 12
	s_waitcnt lgkmcnt(0)
	v_lshl_add_u64 v[78:79], v[136:137], 0, s[2:3]
	s_lshl_b32 s2, s9, 10
	v_xor_b32_e32 v82, 48, v124
	s_add_i32 s2, s2, 0
	v_add_u32_e32 v141, s2, v82
	ds_read_b128 v[82:85], v141
	s_waitcnt vmcnt(15)
	v_mov_b32_e32 v78, v176
	v_mov_b32_e32 v79, v177
	v_lshlrev_b32_e32 v86, 16, v78
	v_and_b32_e32 v87, 0xffff0000, v78
	v_lshlrev_b32_e32 v78, 16, v79
	v_and_b32_e32 v79, 0xffff0000, v79
	s_waitcnt lgkmcnt(0)
	v_pk_fma_f32 v[78:79], v[66:67], v[84:85], v[78:79]
	v_pk_fma_f32 v[86:87], v[64:65], v[82:83], v[86:87]
	v_mul_f32_e32 v83, v79, v79
	v_mul_f32_e32 v82, v87, v87
	v_fmac_f32_e32 v82, v86, v86
	v_fmac_f32_e32 v83, v78, v78
	v_add_f32_e32 v82, v82, v83
	s_nop 1
	v_mov_b32_dpp v83, v82 quad_perm:[1,0,3,2] row_mask:0xf bank_mask:0xf
	s_waitcnt lgkmcnt(0)
	v_add_f32_e32 v82, v82, v83
	s_nop 1
	v_mov_b32_dpp v83, v82 quad_perm:[2,3,0,1] row_mask:0xf bank_mask:0xf
	s_waitcnt lgkmcnt(0)
	v_add_f32_e32 v82, v82, v83
	s_nop 1
	v_mov_b32_dpp v83, v82 row_ror:12 row_mask:0xf bank_mask:0xf
	s_waitcnt lgkmcnt(0)
	v_add_f32_e32 v82, v82, v83
	s_nop 1
	v_mov_b32_dpp v83, v82 row_ror:8 row_mask:0xf bank_mask:0xf
	s_waitcnt lgkmcnt(0)
	v_add_f32_e32 v82, v82, v83
	v_mov_b32_e32 v83, v82
	s_nop 1
	v_permlane16_swap_b32_e32 v82, v83
	s_waitcnt lgkmcnt(0)
	v_add_f32_e32 v82, v82, v83
	v_mov_b32_e32 v83, v82
	s_nop 1
	v_permlane32_swap_b32_e32 v82, v83
	s_and_saveexec_b64 s[2:3], vcc
	s_cbranch_execz .LBB0_1901
	s_lshl_b64 s[0:1], s[0:1], 5
	s_add_u32 s0, s4, s0
	s_addc_u32 s1, s5, s1
	v_mov_b32_e32 v84, 0
	s_waitcnt lgkmcnt(0)
	v_add_f32_e32 v82, v82, v83
	global_store_dword v84, v82, s[0:1] sc1
; #define LAS __attribute__((address_space(3)))
; __device__ __forceinline__ f32x4 ld_bf4(const bf16_t* p) { u32x2 w = *(const u32x2*)p; return (f32x4){__uint_as_float(w.x << 16), __uint_as_float(w.x & 0xffff0000u), __uint_as_float(w.y << 16), __uint_as_float(w.y & 0xffff0000u)}; }
; __device__ __forceinline__ void st_bf4(bf16_t* p, f32x4 v) { u32x2 w; w.x = pk2(v[0], v[1]); w.y = pk2(v[2], v[3]); *(u32x2*)p = w; }
; __device__ __forceinline__ float wave_sum(float v) {
; #pragma unroll
;     for (int o = 1; o < 64; o <<= 1) v += __shfl_xor(v, o);
;     return v;
; template <int MODOFF, int STORE  , bool BASE_BF16>
; __device__ __forceinline__ void epi_rows_part1(LAS unsigned char* lds, const f32x4 (&acc)[2][2][4][2], const Unit& u, const float* base, const float* mod, float* outp, float* slots, f32x4 (&xr)[2][16]) {
;     ...
;         for (int j = 0; j < 16; ++j) { const int rl = wid * 16 + j, row = u.pm * BM + ai * HALF + rl; const size_t o = (size_t)row * DM + colg;
;             const f32x4 v = *(const LAS f32x4*)(T + rl * 256 + ((lane ^ j) << 2));
;             const f32x4 bs = BASE_BF16 ? ld_bf4((const bf16_t*)base + o) : *(const f32x4*)(base + o);
;             const f32x4 x1 = bs + gt * v; xr[ai][j] = x1; if (STORE == 2) st_bf4((bf16_t*)outp + o, x1);
;             const float sq = wave_sum((x1[0] * x1[0] + x1[1] * x1[1]) + (x1[2] * x1[2] + x1[3] * x1[3]));
;             if (lane == 0) __hip_atomic_store((unsigned*)slots + (size_t)row * 8 + u.pn, __float_as_uint(sq), __ATOMIC_RELAXED, __HIP_MEMORY_SCOPE_AGENT); }
.LBB0_1901:
	s_or_b64 exec, exec, s[2:3]
	s_or_b32 s10, s8, 4
	s_add_i32 s0, s10, s46
	s_ashr_i32 s1, s0, 31
	s_lshl_b64 s[2:3], s[0:1], 12
	s_waitcnt lgkmcnt(0)
	v_lshl_add_u64 v[82:83], v[136:137], 0, s[2:3]
	s_lshl_b32 s2, s10, 10
	v_xor_b32_e32 v84, 64, v124
	s_add_i32 s2, s2, 0
	v_add_u32_e32 v142, s2, v84
	ds_read_b128 v[88:91], v142
	s_waitcnt vmcnt(15)
	v_mov_b32_e32 v82, v180
	v_mov_b32_e32 v83, v181
	v_lshlrev_b32_e32 v84, 16, v82
	v_and_b32_e32 v85, 0xffff0000, v82
	v_lshlrev_b32_e32 v82, 16, v83
	v_and_b32_e32 v83, 0xffff0000, v83
	s_waitcnt lgkmcnt(0)
	v_pk_fma_f32 v[82:83], v[66:67], v[90:91], v[82:83]
	v_pk_fma_f32 v[90:91], v[64:65], v[88:89], v[84:85]
	v_mul_f32_e32 v85, v83, v83
	v_mul_f32_e32 v84, v91, v91
	v_fmac_f32_e32 v84, v90, v90
	v_fmac_f32_e32 v85, v82, v82
	v_add_f32_e32 v84, v84, v85
	s_nop 1
	v_mov_b32_dpp v85, v84 quad_perm:[1,0,3,2] row_mask:0xf bank_mask:0xf
	s_waitcnt lgkmcnt(0)
	v_add_f32_e32 v84, v84, v85
	s_nop 1
	v_mov_b32_dpp v85, v84 quad_perm:[2,3,0,1] row_mask:0xf bank_mask:0xf
	s_waitcnt lgkmcnt(0)
	v_add_f32_e32 v84, v84, v85
	s_nop 1
	v_mov_b32_dpp v85, v84 row_ror:12 row_mask:0xf bank_mask:0xf
	s_waitcnt lgkmcnt(0)
	v_add_f32_e32 v84, v84, v85
	s_nop 1
	v_mov_b32_dpp v85, v84 row_ror:8 row_mask:0xf bank_mask:0xf
	s_waitcnt lgkmcnt(0)
	v_add_f32_e32 v84, v84, v85
	v_mov_b32_e32 v85, v84
	s_nop 1
	v_permlane16_swap_b32_e32 v84, v85
	s_waitcnt lgkmcnt(0)
	v_add_f32_e32 v84, v84, v85
	v_mov_b32_e32 v85, v84
	s_nop 1
	v_permlane32_swap_b32_e32 v84, v85
	s_and_saveexec_b64 s[2:3], vcc
	s_cbranch_execz .LBB0_1903
	s_lshl_b64 s[0:1], s[0:1], 5
	s_add_u32 s0, s4, s0
	s_addc_u32 s1, s5, s1
	v_mov_b32_e32 v88, 0
	s_waitcnt lgkmcnt(0)
	v_add_f32_e32 v84, v84, v85
	global_store_dword v88, v84, s[0:1] sc1
.LBB0_1903:
	s_or_b64 exec, exec, s[2:3]
	s_or_b32 s11, s8, 5
	s_add_i32 s0, s11, s46
	s_ashr_i32 s1, s0, 31
	s_lshl_b64 s[2:3], s[0:1], 12
	s_waitcnt lgkmcnt(0)
	v_lshl_add_u64 v[84:85], v[136:137], 0, s[2:3]
	s_lshl_b32 s2, s11, 10
	v_xor_b32_e32 v88, 0x50, v124
	s_add_i32 s2, s2, 0
	v_add_u32_e32 v143, s2, v88
	ds_read_b128 v[92:95], v143
	s_waitcnt vmcnt(15)
	v_mov_b32_e32 v84, v184
	v_mov_b32_e32 v85, v185
	v_lshlrev_b32_e32 v88, 16, v84
	v_and_b32_e32 v89, 0xffff0000, v84
	v_lshlrev_b32_e32 v84, 16, v85
	v_and_b32_e32 v85, 0xffff0000, v85
	s_waitcnt lgkmcnt(0)
	v_pk_fma_f32 v[84:85], v[66:67], v[94:95], v[84:85]
	v_pk_fma_f32 v[94:95], v[64:65], v[92:93], v[88:89]
	v_mul_f32_e32 v89, v85, v85
	v_mul_f32_e32 v88, v95, v95
	v_fmac_f32_e32 v88, v94, v94
	v_fmac_f32_e32 v89, v84, v84
	v_add_f32_e32 v88, v88, v89
	s_nop 1
	v_mov_b32_dpp v89, v88 quad_perm:[1,0,3,2] row_mask:0xf bank_mask:0xf
	s_waitcnt lgkmcnt(0)
	v_add_f32_e32 v88, v88, v89
	s_nop 1
	v_mov_b32_dpp v89, v88 quad_perm:[2,3,0,1] row_mask:0xf bank_mask:0xf
	s_waitcnt lgkmcnt(0)
	v_add_f32_e32 v88, v88, v89
	s_nop 1
	v_mov_b32_dpp v89, v88 row_ror:12 row_mask:0xf bank_mask:0xf
	s_waitcnt lgkmcnt(0)
	v_add_f32_e32 v88, v88, v89
	s_nop 1
	v_mov_b32_dpp v89, v88 row_ror:8 row_mask:0xf bank_mask:0xf
	s_waitcnt lgkmcnt(0)
	v_add_f32_e32 v88, v88, v89
	v_mov_b32_e32 v89, v88
	s_nop 1
	v_permlane16_swap_b32_e32 v88, v89
	s_waitcnt lgkmcnt(0)
	v_add_f32_e32 v88, v88, v89
	v_mov_b32_e32 v89, v88
	s_nop 1
	v_permlane32_swap_b32_e32 v88, v89
	s_and_saveexec_b64 s[2:3], vcc
	s_cbranch_execz .LBB0_1905
	s_lshl_b64 s[0:1], s[0:1], 5
	s_add_u32 s0, s4, s0
	s_addc_u32 s1, s5, s1
	v_mov_b32_e32 v92, 0
	s_waitcnt lgkmcnt(0)
	v_add_f32_e32 v88, v88, v89
	global_store_dword v92, v88, s[0:1] sc1
.LBB0_1905:
	s_or_b64 exec, exec, s[2:3]
	s_or_b32 s12, s8, 6
	s_add_i32 s0, s12, s46
	s_ashr_i32 s1, s0, 31
	s_lshl_b64 s[2:3], s[0:1], 12
	s_waitcnt lgkmcnt(0)
	v_lshl_add_u64 v[88:89], v[136:137], 0, s[2:3]
	s_lshl_b32 s2, s12, 10
	v_xor_b32_e32 v92, 0x60, v124
	s_add_i32 s2, s2, 0
	v_add_u32_e32 v144, s2, v92
	ds_read_b128 v[96:99], v144
	s_waitcnt vmcnt(15)
	v_mov_b32_e32 v88, v196
	v_mov_b32_e32 v89, v197
	v_lshlrev_b32_e32 v92, 16, v88
	v_and_b32_e32 v93, 0xffff0000, v88
	v_lshlrev_b32_e32 v88, 16, v89
	v_and_b32_e32 v89, 0xffff0000, v89
	s_waitcnt lgkmcnt(0)
	v_pk_fma_f32 v[88:89], v[66:67], v[98:99], v[88:89]
	v_pk_fma_f32 v[98:99], v[64:65], v[96:97], v[92:93]
	v_mul_f32_e32 v93, v89, v89
	v_mul_f32_e32 v92, v99, v99
	v_fmac_f32_e32 v92, v98, v98
	v_fmac_f32_e32 v93, v88, v88
	v_add_f32_e32 v92, v92, v93
	s_nop 1
	v_mov_b32_dpp v93, v92 quad_perm:[1,0,3,2] row_mask:0xf bank_mask:0xf
	s_waitcnt lgkmcnt(0)
	v_add_f32_e32 v92, v92, v93
	s_nop 1
	v_mov_b32_dpp v93, v92 quad_perm:[2,3,0,1] row_mask:0xf bank_mask:0xf
	s_waitcnt lgkmcnt(0)
	v_add_f32_e32 v92, v92, v93
	s_nop 1
	v_mov_b32_dpp v93, v92 row_ror:12 row_mask:0xf bank_mask:0xf
	s_waitcnt lgkmcnt(0)
	v_add_f32_e32 v92, v92, v93
	s_nop 1
	v_mov_b32_dpp v93, v92 row_ror:8 row_mask:0xf bank_mask:0xf
	s_waitcnt lgkmcnt(0)
	v_add_f32_e32 v92, v92, v93
	v_mov_b32_e32 v93, v92
	s_nop 1
	v_permlane16_swap_b32_e32 v92, v93
	s_waitcnt lgkmcnt(0)
	v_add_f32_e32 v92, v92, v93
	v_mov_b32_e32 v93, v92
	s_nop 1
	v_permlane32_swap_b32_e32 v92, v93
	s_and_saveexec_b64 s[2:3], vcc
	s_cbranch_execz .LBB0_1907
	s_lshl_b64 s[0:1], s[0:1], 5
	s_add_u32 s0, s4, s0
	s_addc_u32 s1, s5, s1
	v_mov_b32_e32 v96, 0
	s_waitcnt lgkmcnt(0)
	v_add_f32_e32 v92, v92, v93
	global_store_dword v96, v92, s[0:1] sc1
; #define LAS __attribute__((address_space(3)))
; __device__ __forceinline__ f32x4 ld_bf4(const bf16_t* p) { u32x2 w = *(const u32x2*)p; return (f32x4){__uint_as_float(w.x << 16), __uint_as_float(w.x & 0xffff0000u), __uint_as_float(w.y << 16), __uint_as_float(w.y & 0xffff0000u)}; }
; __device__ __forceinline__ void st_bf4(bf16_t* p, f32x4 v) { u32x2 w; w.x = pk2(v[0], v[1]); w.y = pk2(v[2], v[3]); *(u32x2*)p = w; }
; __device__ __forceinline__ float wave_sum(float v) {
; #pragma unroll
;     for (int o = 1; o < 64; o <<= 1) v += __shfl_xor(v, o);
;     return v;
; template <int MODOFF, int STORE  , bool BASE_BF16>
; __device__ __forceinline__ void epi_rows_part1(LAS unsigned char* lds, const f32x4 (&acc)[2][2][4][2], const Unit& u, const float* base, const float* mod, float* outp, float* slots, f32x4 (&xr)[2][16]) {
;     ...
;         for (int j = 0; j < 16; ++j) { const int rl = wid * 16 + j, row = u.pm * BM + ai * HALF + rl; const size_t o = (size_t)row * DM + colg;
;             const f32x4 v = *(const LAS f32x4*)(T + rl * 256 + ((lane ^ j) << 2));
;             const f32x4 bs = BASE_BF16 ? ld_bf4((const bf16_t*)base + o) : *(const f32x4*)(base + o);
;             const f32x4 x1 = bs + gt * v; xr[ai][j] = x1; if (STORE == 2) st_bf4((bf16_t*)outp + o, x1);
;             const float sq = wave_sum((x1[0] * x1[0] + x1[1] * x1[1]) + (x1[2] * x1[2] + x1[3] * x1[3]));
;             if (lane == 0) __hip_atomic_store((unsigned*)slots + (size_t)row * 8 + u.pn, __float_as_uint(sq), __ATOMIC_RELAXED, __HIP_MEMORY_SCOPE_AGENT); }
.LBB0_1907:
	s_or_b64 exec, exec, s[2:3]
	s_or_b32 s13, s8, 7
	s_add_i32 s0, s13, s46
	s_ashr_i32 s1, s0, 31
	s_lshl_b64 s[2:3], s[0:1], 12
	s_waitcnt lgkmcnt(0)
	v_lshl_add_u64 v[92:93], v[136:137], 0, s[2:3]
	s_lshl_b32 s2, s13, 10
	v_xor_b32_e32 v96, 0x70, v124
	s_add_i32 s2, s2, 0
	v_add_u32_e32 v145, s2, v96
	ds_read_b128 v[100:103], v145
	s_waitcnt vmcnt(15)
	v_mov_b32_e32 v92, v200
	v_mov_b32_e32 v93, v201
	v_lshlrev_b32_e32 v96, 16, v92
	v_and_b32_e32 v97, 0xffff0000, v92
	v_lshlrev_b32_e32 v92, 16, v93
	v_and_b32_e32 v93, 0xffff0000, v93
	s_waitcnt lgkmcnt(0)
	v_pk_fma_f32 v[92:93], v[66:67], v[102:103], v[92:93]
	v_pk_fma_f32 v[102:103], v[64:65], v[100:101], v[96:97]
	v_mul_f32_e32 v97, v93, v93
	v_mul_f32_e32 v96, v103, v103
	v_fmac_f32_e32 v96, v102, v102
	v_fmac_f32_e32 v97, v92, v92
	v_add_f32_e32 v96, v96, v97
	s_nop 1
	v_mov_b32_dpp v97, v96 quad_perm:[1,0,3,2] row_mask:0xf bank_mask:0xf
	s_waitcnt lgkmcnt(0)
	v_add_f32_e32 v96, v96, v97
	s_nop 1
	v_mov_b32_dpp v97, v96 quad_perm:[2,3,0,1] row_mask:0xf bank_mask:0xf
	s_waitcnt lgkmcnt(0)
	v_add_f32_e32 v96, v96, v97
	s_nop 1
	v_mov_b32_dpp v97, v96 row_ror:12 row_mask:0xf bank_mask:0xf
	s_waitcnt lgkmcnt(0)
	v_add_f32_e32 v96, v96, v97
	s_nop 1
	v_mov_b32_dpp v97, v96 row_ror:8 row_mask:0xf bank_mask:0xf
	s_waitcnt lgkmcnt(0)
	v_add_f32_e32 v96, v96, v97
	v_mov_b32_e32 v97, v96
	s_nop 1
	v_permlane16_swap_b32_e32 v96, v97
	s_waitcnt lgkmcnt(0)
	v_add_f32_e32 v96, v96, v97
	v_mov_b32_e32 v97, v96
	s_nop 1
	v_permlane32_swap_b32_e32 v96, v97
	s_and_saveexec_b64 s[2:3], vcc
	s_cbranch_execz .LBB0_1909
	s_lshl_b64 s[0:1], s[0:1], 5
	s_add_u32 s0, s4, s0
	s_addc_u32 s1, s5, s1
	v_mov_b32_e32 v100, 0
	s_waitcnt lgkmcnt(0)
	v_add_f32_e32 v96, v96, v97
	global_store_dword v100, v96, s[0:1] sc1
.LBB0_1909:
	s_or_b64 exec, exec, s[2:3]
	s_or_b32 s14, s8, 8
	s_add_i32 s0, s14, s46
	s_ashr_i32 s1, s0, 31
	s_lshl_b64 s[2:3], s[0:1], 12
	s_waitcnt lgkmcnt(0)
	v_lshl_add_u64 v[96:97], v[136:137], 0, s[2:3]
	s_lshl_b32 s2, s14, 10
	v_xor_b32_e32 v100, 0x80, v124
	s_add_i32 s2, s2, 0
	v_add_u32_e32 v146, s2, v100
	ds_read_b128 v[104:107], v146
	s_waitcnt vmcnt(15)
	v_mov_b32_e32 v96, v204
	v_mov_b32_e32 v97, v205
	v_lshlrev_b32_e32 v100, 16, v96
	v_and_b32_e32 v101, 0xffff0000, v96
	v_lshlrev_b32_e32 v96, 16, v97
	v_and_b32_e32 v97, 0xffff0000, v97
	s_waitcnt lgkmcnt(0)
	v_pk_fma_f32 v[96:97], v[66:67], v[106:107], v[96:97]
	v_pk_fma_f32 v[106:107], v[64:65], v[104:105], v[100:101]
	v_mul_f32_e32 v101, v97, v97
	v_mul_f32_e32 v100, v107, v107
	v_fmac_f32_e32 v100, v106, v106
	v_fmac_f32_e32 v101, v96, v96
	v_add_f32_e32 v100, v100, v101
	s_nop 1
	v_mov_b32_dpp v101, v100 quad_perm:[1,0,3,2] row_mask:0xf bank_mask:0xf
	s_waitcnt lgkmcnt(0)
	v_add_f32_e32 v100, v100, v101
	s_nop 1
	v_mov_b32_dpp v101, v100 quad_perm:[2,3,0,1] row_mask:0xf bank_mask:0xf
	s_waitcnt lgkmcnt(0)
	v_add_f32_e32 v100, v100, v101
	s_nop 1
	v_mov_b32_dpp v101, v100 row_ror:12 row_mask:0xf bank_mask:0xf
	s_waitcnt lgkmcnt(0)
	v_add_f32_e32 v100, v100, v101
	s_nop 1
	v_mov_b32_dpp v101, v100 row_ror:8 row_mask:0xf bank_mask:0xf
	s_waitcnt lgkmcnt(0)
	v_add_f32_e32 v100, v100, v101
	v_mov_b32_e32 v101, v100
	s_nop 1
	v_permlane16_swap_b32_e32 v100, v101
	s_waitcnt lgkmcnt(0)
	v_add_f32_e32 v100, v100, v101
	v_mov_b32_e32 v101, v100
	s_nop 1
	v_permlane32_swap_b32_e32 v100, v101
	s_and_saveexec_b64 s[2:3], vcc
	s_cbranch_execz .LBB0_1911
	s_lshl_b64 s[0:1], s[0:1], 5
	s_add_u32 s0, s4, s0
	s_addc_u32 s1, s5, s1
	v_mov_b32_e32 v104, 0
	s_waitcnt lgkmcnt(0)
	v_add_f32_e32 v100, v100, v101
	global_store_dword v104, v100, s[0:1] sc1
.LBB0_1911:
	s_or_b64 exec, exec, s[2:3]
	s_or_b32 s15, s8, 9
	s_add_i32 s0, s15, s46
	s_ashr_i32 s1, s0, 31
	s_lshl_b64 s[2:3], s[0:1], 12
	s_waitcnt lgkmcnt(0)
	v_lshl_add_u64 v[100:101], v[136:137], 0, s[2:3]
	s_lshl_b32 s2, s15, 10
	v_xor_b32_e32 v104, 0x90, v124
	s_add_i32 s2, s2, 0
	v_add_u32_e32 v147, s2, v104
	ds_read_b128 v[108:111], v147
	s_waitcnt vmcnt(15)
	v_mov_b32_e32 v100, v208
	v_mov_b32_e32 v101, v209
	v_lshlrev_b32_e32 v104, 16, v100
	v_and_b32_e32 v105, 0xffff0000, v100
	v_lshlrev_b32_e32 v100, 16, v101
	v_and_b32_e32 v101, 0xffff0000, v101
	s_waitcnt lgkmcnt(0)
	v_pk_fma_f32 v[100:101], v[66:67], v[110:111], v[100:101]
	v_pk_fma_f32 v[110:111], v[64:65], v[108:109], v[104:105]
	v_mul_f32_e32 v105, v101, v101
	v_mul_f32_e32 v104, v111, v111
	v_fmac_f32_e32 v104, v110, v110
	v_fmac_f32_e32 v105, v100, v100
	v_add_f32_e32 v104, v104, v105
	s_nop 1
	v_mov_b32_dpp v105, v104 quad_perm:[1,0,3,2] row_mask:0xf bank_mask:0xf
	s_waitcnt lgkmcnt(0)
	v_add_f32_e32 v104, v104, v105
	s_nop 1
	v_mov_b32_dpp v105, v104 quad_perm:[2,3,0,1] row_mask:0xf bank_mask:0xf
	s_waitcnt lgkmcnt(0)
	v_add_f32_e32 v104, v104, v105
	s_nop 1
	v_mov_b32_dpp v105, v104 row_ror:12 row_mask:0xf bank_mask:0xf
	s_waitcnt lgkmcnt(0)
	v_add_f32_e32 v104, v104, v105
	s_nop 1
	v_mov_b32_dpp v105, v104 row_ror:8 row_mask:0xf bank_mask:0xf
	s_waitcnt lgkmcnt(0)
	v_add_f32_e32 v104, v104, v105
	v_mov_b32_e32 v105, v104
	s_nop 1
	v_permlane16_swap_b32_e32 v104, v105
	s_waitcnt lgkmcnt(0)
	v_add_f32_e32 v104, v104, v105
	v_mov_b32_e32 v105, v104
	s_nop 1
	v_permlane32_swap_b32_e32 v104, v105
	s_and_saveexec_b64 s[2:3], vcc
	s_cbranch_execz .LBB0_1913
	s_lshl_b64 s[0:1], s[0:1], 5
	s_add_u32 s0, s4, s0
	s_addc_u32 s1, s5, s1
	v_mov_b32_e32 v108, 0
	s_waitcnt lgkmcnt(0)
	v_add_f32_e32 v104, v104, v105
	global_store_dword v108, v104, s[0:1] sc1
; #define LAS __attribute__((address_space(3)))
; __device__ __forceinline__ f32x4 ld_bf4(const bf16_t* p) { u32x2 w = *(const u32x2*)p; return (f32x4){__uint_as_float(w.x << 16), __uint_as_float(w.x & 0xffff0000u), __uint_as_float(w.y << 16), __uint_as_float(w.y & 0xffff0000u)}; }
; __device__ __forceinline__ void st_bf4(bf16_t* p, f32x4 v) { u32x2 w; w.x = pk2(v[0], v[1]); w.y = pk2(v[2], v[3]); *(u32x2*)p = w; }
; __device__ __forceinline__ float wave_sum(float v) {
; #pragma unroll
;     for (int o = 1; o < 64; o <<= 1) v += __shfl_xor(v, o);
;     return v;
; template <int MODOFF, int STORE  , bool BASE_BF16>
; __device__ __forceinline__ void epi_rows_part1(LAS unsigned char* lds, const f32x4 (&acc)[2][2][4][2], const Unit& u, const float* base, const float* mod, float* outp, float* slots, f32x4 (&xr)[2][16]) {
;     ...
;         for (int j = 0; j < 16; ++j) { const int rl = wid * 16 + j, row = u.pm * BM + ai * HALF + rl; const size_t o = (size_t)row * DM + colg;
;             const f32x4 v = *(const LAS f32x4*)(T + rl * 256 + ((lane ^ j) << 2));
;             const f32x4 bs = BASE_BF16 ? ld_bf4((const bf16_t*)base + o) : *(const f32x4*)(base + o);
;             const f32x4 x1 = bs + gt * v; xr[ai][j] = x1; if (STORE == 2) st_bf4((bf16_t*)outp + o, x1);
;             const float sq = wave_sum((x1[0] * x1[0] + x1[1] * x1[1]) + (x1[2] * x1[2] + x1[3] * x1[3]));
;             if (lane == 0) __hip_atomic_store((unsigned*)slots + (size_t)row * 8 + u.pn, __float_as_uint(sq), __ATOMIC_RELAXED, __HIP_MEMORY_SCOPE_AGENT); }
.LBB0_1913:
	s_or_b64 exec, exec, s[2:3]
	s_or_b32 s16, s8, 10
	s_add_i32 s0, s16, s46
	s_ashr_i32 s1, s0, 31
	s_lshl_b64 s[2:3], s[0:1], 12
	s_waitcnt lgkmcnt(0)
	v_lshl_add_u64 v[104:105], v[136:137], 0, s[2:3]
	s_lshl_b32 s2, s16, 10
	v_xor_b32_e32 v108, 0xa0, v124
	s_add_i32 s2, s2, 0
	v_add_u32_e32 v148, s2, v108
	ds_read_b128 v[112:115], v148
	s_waitcnt vmcnt(15)
	v_mov_b32_e32 v104, v212
	v_mov_b32_e32 v105, v213
	v_lshlrev_b32_e32 v108, 16, v104
	v_and_b32_e32 v109, 0xffff0000, v104
	v_lshlrev_b32_e32 v104, 16, v105
	v_and_b32_e32 v105, 0xffff0000, v105
	s_waitcnt lgkmcnt(0)
	v_pk_fma_f32 v[104:105], v[66:67], v[114:115], v[104:105]
	v_pk_fma_f32 v[114:115], v[64:65], v[112:113], v[108:109]
	v_mul_f32_e32 v109, v105, v105
	v_mul_f32_e32 v108, v115, v115
	v_fmac_f32_e32 v108, v114, v114
	v_fmac_f32_e32 v109, v104, v104
	v_add_f32_e32 v108, v108, v109
	s_nop 1
	v_mov_b32_dpp v109, v108 quad_perm:[1,0,3,2] row_mask:0xf bank_mask:0xf
	s_waitcnt lgkmcnt(0)
	v_add_f32_e32 v108, v108, v109
	s_nop 1
	v_mov_b32_dpp v109, v108 quad_perm:[2,3,0,1] row_mask:0xf bank_mask:0xf
	s_waitcnt lgkmcnt(0)
	v_add_f32_e32 v108, v108, v109
	s_nop 1
	v_mov_b32_dpp v109, v108 row_ror:12 row_mask:0xf bank_mask:0xf
	s_waitcnt lgkmcnt(0)
	v_add_f32_e32 v108, v108, v109
	s_nop 1
	v_mov_b32_dpp v109, v108 row_ror:8 row_mask:0xf bank_mask:0xf
	s_waitcnt lgkmcnt(0)
	v_add_f32_e32 v108, v108, v109
	v_mov_b32_e32 v109, v108
	s_nop 1
	v_permlane16_swap_b32_e32 v108, v109
	s_waitcnt lgkmcnt(0)
	v_add_f32_e32 v108, v108, v109
	v_mov_b32_e32 v109, v108
	s_nop 1
	v_permlane32_swap_b32_e32 v108, v109
	s_and_saveexec_b64 s[2:3], vcc
	s_cbranch_execz .LBB0_1915
	s_lshl_b64 s[0:1], s[0:1], 5
	s_add_u32 s0, s4, s0
	s_addc_u32 s1, s5, s1
	v_mov_b32_e32 v112, 0
	s_waitcnt lgkmcnt(0)
	v_add_f32_e32 v108, v108, v109
	global_store_dword v112, v108, s[0:1] sc1
.LBB0_1915:
	s_or_b64 exec, exec, s[2:3]
	s_or_b32 s17, s8, 11
	s_add_i32 s0, s17, s46
	s_ashr_i32 s1, s0, 31
	s_lshl_b64 s[2:3], s[0:1], 12
	s_waitcnt lgkmcnt(0)
	v_lshl_add_u64 v[108:109], v[136:137], 0, s[2:3]
	s_lshl_b32 s2, s17, 10
	v_xor_b32_e32 v112, 0xb0, v124
	s_add_i32 s2, s2, 0
	v_add_u32_e32 v149, s2, v112
	ds_read_b128 v[116:119], v149
	s_waitcnt vmcnt(15)
	v_mov_b32_e32 v108, v216
	v_mov_b32_e32 v109, v217
	v_lshlrev_b32_e32 v112, 16, v108
	v_and_b32_e32 v113, 0xffff0000, v108
	v_lshlrev_b32_e32 v108, 16, v109
	v_and_b32_e32 v109, 0xffff0000, v109
	s_waitcnt lgkmcnt(0)
	v_pk_fma_f32 v[108:109], v[66:67], v[118:119], v[108:109]
	v_pk_fma_f32 v[118:119], v[64:65], v[116:117], v[112:113]
	v_mul_f32_e32 v113, v109, v109
	v_mul_f32_e32 v112, v119, v119
	v_fmac_f32_e32 v112, v118, v118
	v_fmac_f32_e32 v113, v108, v108
	v_add_f32_e32 v112, v112, v113
	s_nop 1
	v_mov_b32_dpp v113, v112 quad_perm:[1,0,3,2] row_mask:0xf bank_mask:0xf
	s_waitcnt lgkmcnt(0)
	v_add_f32_e32 v112, v112, v113
	s_nop 1
	v_mov_b32_dpp v113, v112 quad_perm:[2,3,0,1] row_mask:0xf bank_mask:0xf
	s_waitcnt lgkmcnt(0)
	v_add_f32_e32 v112, v112, v113
	s_nop 1
	v_mov_b32_dpp v113, v112 row_ror:12 row_mask:0xf bank_mask:0xf
	s_waitcnt lgkmcnt(0)
	v_add_f32_e32 v112, v112, v113
	s_nop 1
	v_mov_b32_dpp v113, v112 row_ror:8 row_mask:0xf bank_mask:0xf
	s_waitcnt lgkmcnt(0)
	v_add_f32_e32 v112, v112, v113
	v_mov_b32_e32 v113, v112
	s_nop 1
	v_permlane16_swap_b32_e32 v112, v113
	s_waitcnt lgkmcnt(0)
	v_add_f32_e32 v112, v112, v113
	v_mov_b32_e32 v113, v112
	s_nop 1
	v_permlane32_swap_b32_e32 v112, v113
	s_and_saveexec_b64 s[2:3], vcc
	s_cbranch_execz .LBB0_1917
	s_lshl_b64 s[0:1], s[0:1], 5
	s_add_u32 s0, s4, s0
	s_addc_u32 s1, s5, s1
	v_mov_b32_e32 v116, 0
	s_waitcnt lgkmcnt(0)
	v_add_f32_e32 v112, v112, v113
	global_store_dword v116, v112, s[0:1] sc1
.LBB0_1917:
	s_or_b64 exec, exec, s[2:3]
	s_or_b32 s18, s8, 12
	s_add_i32 s0, s18, s46
	s_ashr_i32 s1, s0, 31
	s_lshl_b64 s[2:3], s[0:1], 12
	s_waitcnt lgkmcnt(0)
	v_lshl_add_u64 v[112:113], v[136:137], 0, s[2:3]
	s_lshl_b32 s2, s18, 10
	v_xor_b32_e32 v116, 0xc0, v124
	s_add_i32 s2, s2, 0
	v_add_u32_e32 v150, s2, v116
	ds_read_b128 v[120:123], v150
	s_waitcnt vmcnt(15)
	v_mov_b32_e32 v112, v220
	v_mov_b32_e32 v113, v221
	v_lshlrev_b32_e32 v116, 16, v112
	v_and_b32_e32 v117, 0xffff0000, v112
	v_lshlrev_b32_e32 v112, 16, v113
	v_and_b32_e32 v113, 0xffff0000, v113
	s_waitcnt lgkmcnt(0)
	v_pk_fma_f32 v[112:113], v[66:67], v[122:123], v[112:113]
	v_pk_fma_f32 v[122:123], v[64:65], v[120:121], v[116:117]
	v_mul_f32_e32 v117, v113, v113
	v_mul_f32_e32 v116, v123, v123
	v_fmac_f32_e32 v116, v122, v122
	v_fmac_f32_e32 v117, v112, v112
	v_add_f32_e32 v116, v116, v117
	s_nop 1
	v_mov_b32_dpp v117, v116 quad_perm:[1,0,3,2] row_mask:0xf bank_mask:0xf
	s_waitcnt lgkmcnt(0)
	v_add_f32_e32 v116, v116, v117
	s_nop 1
	v_mov_b32_dpp v117, v116 quad_perm:[2,3,0,1] row_mask:0xf bank_mask:0xf
	s_waitcnt lgkmcnt(0)
	v_add_f32_e32 v116, v116, v117
	s_nop 1
	v_mov_b32_dpp v117, v116 row_ror:12 row_mask:0xf bank_mask:0xf
	s_waitcnt lgkmcnt(0)
	v_add_f32_e32 v116, v116, v117
	s_nop 1
	v_mov_b32_dpp v117, v116 row_ror:8 row_mask:0xf bank_mask:0xf
	s_waitcnt lgkmcnt(0)
	v_add_f32_e32 v116, v116, v117
	v_mov_b32_e32 v117, v116
	s_nop 1
	v_permlane16_swap_b32_e32 v116, v117
	s_waitcnt lgkmcnt(0)
	v_add_f32_e32 v116, v116, v117
	v_mov_b32_e32 v117, v116
	s_nop 1
	v_permlane32_swap_b32_e32 v116, v117
	s_and_saveexec_b64 s[2:3], vcc
	s_cbranch_execz .LBB0_1919
	s_lshl_b64 s[0:1], s[0:1], 5
	s_add_u32 s0, s4, s0
	s_addc_u32 s1, s5, s1
	v_mov_b32_e32 v120, 0
	s_waitcnt lgkmcnt(0)
	v_add_f32_e32 v116, v116, v117
	global_store_dword v120, v116, s[0:1] sc1
; #define LAS __attribute__((address_space(3)))
; __device__ __forceinline__ f32x4 ld_bf4(const bf16_t* p) { u32x2 w = *(const u32x2*)p; return (f32x4){__uint_as_float(w.x << 16), __uint_as_float(w.x & 0xffff0000u), __uint_as_float(w.y << 16), __uint_as_float(w.y & 0xffff0000u)}; }
; __device__ __forceinline__ void st_bf4(bf16_t* p, f32x4 v) { u32x2 w; w.x = pk2(v[0], v[1]); w.y = pk2(v[2], v[3]); *(u32x2*)p = w; }
; __device__ __forceinline__ float wave_sum(float v) {
; #pragma unroll
;     for (int o = 1; o < 64; o <<= 1) v += __shfl_xor(v, o);
;     return v;
; template <int MODOFF, int STORE  , bool BASE_BF16>
; __device__ __forceinline__ void epi_rows_part1(LAS unsigned char* lds, const f32x4 (&acc)[2][2][4][2], const Unit& u, const float* base, const float* mod, float* outp, float* slots, f32x4 (&xr)[2][16]) {
;     ...
;         for (int j = 0; j < 16; ++j) { const int rl = wid * 16 + j, row = u.pm * BM + ai * HALF + rl; const size_t o = (size_t)row * DM + colg;
;             const f32x4 v = *(const LAS f32x4*)(T + rl * 256 + ((lane ^ j) << 2));
;             const f32x4 bs = BASE_BF16 ? ld_bf4((const bf16_t*)base + o) : *(const f32x4*)(base + o);
;             const f32x4 x1 = bs + gt * v; xr[ai][j] = x1; if (STORE == 2) st_bf4((bf16_t*)outp + o, x1);
;             const float sq = wave_sum((x1[0] * x1[0] + x1[1] * x1[1]) + (x1[2] * x1[2] + x1[3] * x1[3]));
;             if (lane == 0) __hip_atomic_store((unsigned*)slots + (size_t)row * 8 + u.pn, __float_as_uint(sq), __ATOMIC_RELAXED, __HIP_MEMORY_SCOPE_AGENT); }
.LBB0_1919:
	s_or_b64 exec, exec, s[2:3]
	s_or_b32 s19, s8, 13
	s_add_i32 s0, s19, s46
	s_ashr_i32 s1, s0, 31
	s_lshl_b64 s[2:3], s[0:1], 12
	s_waitcnt lgkmcnt(0)
	v_lshl_add_u64 v[116:117], v[136:137], 0, s[2:3]
	s_lshl_b32 s2, s19, 10
	v_xor_b32_e32 v120, 0xd0, v124
	s_add_i32 s2, s2, 0
	v_add_u32_e32 v151, s2, v120
	ds_read_b128 v[126:129], v151
	s_waitcnt vmcnt(15)
	v_mov_b32_e32 v116, v224
	v_mov_b32_e32 v117, v225
	v_lshlrev_b32_e32 v120, 16, v116
	v_and_b32_e32 v121, 0xffff0000, v116
	v_lshlrev_b32_e32 v116, 16, v117
	v_and_b32_e32 v117, 0xffff0000, v117
	s_waitcnt lgkmcnt(0)
	v_pk_fma_f32 v[116:117], v[66:67], v[128:129], v[116:117]
	v_pk_fma_f32 v[126:127], v[64:65], v[126:127], v[120:121]
	v_mul_f32_e32 v121, v117, v117
	v_mul_f32_e32 v120, v127, v127
	v_fmac_f32_e32 v120, v126, v126
	v_fmac_f32_e32 v121, v116, v116
	v_add_f32_e32 v120, v120, v121
	s_nop 1
	v_mov_b32_dpp v121, v120 quad_perm:[1,0,3,2] row_mask:0xf bank_mask:0xf
	s_waitcnt lgkmcnt(0)
	v_add_f32_e32 v120, v120, v121
	s_nop 1
	v_mov_b32_dpp v121, v120 quad_perm:[2,3,0,1] row_mask:0xf bank_mask:0xf
	s_waitcnt lgkmcnt(0)
	v_add_f32_e32 v120, v120, v121
	s_nop 1
	v_mov_b32_dpp v121, v120 row_ror:12 row_mask:0xf bank_mask:0xf
	s_waitcnt lgkmcnt(0)
	v_add_f32_e32 v120, v120, v121
	s_nop 1
	v_mov_b32_dpp v121, v120 row_ror:8 row_mask:0xf bank_mask:0xf
	s_waitcnt lgkmcnt(0)
	v_add_f32_e32 v120, v120, v121
	v_mov_b32_e32 v121, v120
	s_nop 1
	v_permlane16_swap_b32_e32 v120, v121
	s_waitcnt lgkmcnt(0)
	v_add_f32_e32 v120, v120, v121
	v_mov_b32_e32 v121, v120
	s_nop 1
	v_permlane32_swap_b32_e32 v120, v121
	s_and_saveexec_b64 s[2:3], vcc
	s_cbranch_execz .LBB0_1921
	s_lshl_b64 s[0:1], s[0:1], 5
	s_add_u32 s0, s4, s0
	s_addc_u32 s1, s5, s1
	v_mov_b32_e32 v125, 0
	s_waitcnt lgkmcnt(0)
	v_add_f32_e32 v120, v120, v121
	global_store_dword v125, v120, s[0:1] sc1
.LBB0_1921:
	s_or_b64 exec, exec, s[2:3]
	s_or_b32 s20, s8, 14
	s_add_i32 s0, s20, s46
	s_ashr_i32 s1, s0, 31
	s_lshl_b64 s[2:3], s[0:1], 12
	s_waitcnt lgkmcnt(0)
	v_lshl_add_u64 v[120:121], v[136:137], 0, s[2:3]
	s_lshl_b32 s2, s20, 10
	v_xor_b32_e32 v125, 0xe0, v124
	s_add_i32 s2, s2, 0
	v_add_u32_e32 v152, s2, v125
	ds_read_b128 v[128:131], v152
	s_waitcnt vmcnt(15)
	v_mov_b32_e32 v120, v228
	v_mov_b32_e32 v121, v229
	v_lshlrev_b32_e32 v154, 16, v120
	v_and_b32_e32 v155, 0xffff0000, v120
	v_lshlrev_b32_e32 v120, 16, v121
	v_and_b32_e32 v121, 0xffff0000, v121
	s_waitcnt lgkmcnt(0)
	v_pk_fma_f32 v[120:121], v[66:67], v[130:131], v[120:121]
	v_pk_fma_f32 v[128:129], v[64:65], v[128:129], v[154:155]
	v_mul_f32_e32 v130, v121, v121
	v_mul_f32_e32 v125, v129, v129
	v_fmac_f32_e32 v125, v128, v128
	v_fmac_f32_e32 v130, v120, v120
	v_add_f32_e32 v125, v125, v130
	s_nop 1
	v_mov_b32_dpp v130, v125 quad_perm:[1,0,3,2] row_mask:0xf bank_mask:0xf
	s_waitcnt lgkmcnt(0)
	v_add_f32_e32 v125, v125, v130
	s_nop 1
	v_mov_b32_dpp v130, v125 quad_perm:[2,3,0,1] row_mask:0xf bank_mask:0xf
	s_waitcnt lgkmcnt(0)
	v_add_f32_e32 v125, v125, v130
	s_nop 1
	v_mov_b32_dpp v130, v125 row_ror:12 row_mask:0xf bank_mask:0xf
	s_waitcnt lgkmcnt(0)
	v_add_f32_e32 v125, v125, v130
	s_nop 1
	v_mov_b32_dpp v130, v125 row_ror:8 row_mask:0xf bank_mask:0xf
	s_waitcnt lgkmcnt(0)
	v_add_f32_e32 v125, v125, v130
	v_mov_b32_e32 v130, v125
	s_nop 1
	v_permlane16_swap_b32_e32 v125, v130
	s_waitcnt lgkmcnt(0)
	v_add_f32_e32 v125, v125, v130
	v_mov_b32_e32 v130, v125
	s_nop 1
	v_permlane32_swap_b32_e32 v125, v130
	s_and_saveexec_b64 s[2:3], vcc
	s_cbranch_execz .LBB0_1923
	s_lshl_b64 s[0:1], s[0:1], 5
	s_add_u32 s0, s4, s0
	s_addc_u32 s1, s5, s1
	v_mov_b32_e32 v131, 0
	s_waitcnt lgkmcnt(0)
	v_add_f32_e32 v125, v125, v130
	global_store_dword v131, v125, s[0:1] sc1
.LBB0_1923:
	s_or_b64 exec, exec, s[2:3]
	s_or_b32 s21, s8, 15
	s_add_i32 s0, s21, s46
	s_ashr_i32 s1, s0, 31
	s_lshl_b64 s[2:3], s[0:1], 12
	s_waitcnt lgkmcnt(0)
	v_lshl_add_u64 v[130:131], v[136:137], 0, s[2:3]
	s_lshl_b32 s2, s21, 10
	v_xor_b32_e32 v124, 0xf0, v124
	s_add_i32 s2, s2, 0
	v_add_u32_e32 v153, s2, v124
	ds_read_b128 v[154:157], v153
	s_waitcnt vmcnt(15)
	v_mov_b32_e32 v130, v232
	v_mov_b32_e32 v131, v233
	v_lshlrev_b32_e32 v158, 16, v130
	v_and_b32_e32 v159, 0xffff0000, v130
	v_lshlrev_b32_e32 v124, 16, v131
	v_and_b32_e32 v125, 0xffff0000, v131
	s_waitcnt lgkmcnt(0)
	v_pk_fma_f32 v[124:125], v[66:67], v[156:157], v[124:125]
	v_pk_fma_f32 v[130:131], v[64:65], v[154:155], v[158:159]
	v_mul_f32_e32 v155, v125, v125
	v_mul_f32_e32 v154, v131, v131
	v_fmac_f32_e32 v154, v130, v130
	v_fmac_f32_e32 v155, v124, v124
	v_add_f32_e32 v154, v154, v155
	s_nop 1
	v_mov_b32_dpp v155, v154 quad_perm:[1,0,3,2] row_mask:0xf bank_mask:0xf
	s_waitcnt lgkmcnt(0)
	v_add_f32_e32 v154, v154, v155
	s_nop 1
	v_mov_b32_dpp v155, v154 quad_perm:[2,3,0,1] row_mask:0xf bank_mask:0xf
	s_waitcnt lgkmcnt(0)
	v_add_f32_e32 v154, v154, v155
	s_nop 1
	v_mov_b32_dpp v155, v154 row_ror:12 row_mask:0xf bank_mask:0xf
	s_waitcnt lgkmcnt(0)
	v_add_f32_e32 v154, v154, v155
	s_nop 1
	v_mov_b32_dpp v155, v154 row_ror:8 row_mask:0xf bank_mask:0xf
	s_waitcnt lgkmcnt(0)
	v_add_f32_e32 v154, v154, v155
	v_mov_b32_e32 v155, v154
	s_nop 1
	v_permlane16_swap_b32_e32 v154, v155
	s_waitcnt lgkmcnt(0)
	v_add_f32_e32 v154, v154, v155
	v_mov_b32_e32 v155, v154
	s_nop 1
	v_permlane32_swap_b32_e32 v154, v155
	s_and_saveexec_b64 s[2:3], vcc
	s_cbranch_execz .LBB0_1925
	s_lshl_b64 s[0:1], s[0:1], 5
	s_add_u32 s0, s4, s0
	s_addc_u32 s1, s5, s1
	v_mov_b32_e32 v156, 0
	s_waitcnt lgkmcnt(0)
	v_add_f32_e32 v154, v154, v155
	global_store_dword v156, v154, s[0:1] sc1
; #define LAS __attribute__((address_space(3)))
; __device__ __forceinline__ f32x4 ld_bf4(const bf16_t* p) { u32x2 w = *(const u32x2*)p; return (f32x4){__uint_as_float(w.x << 16), __uint_as_float(w.x & 0xffff0000u), __uint_as_float(w.y << 16), __uint_as_float(w.y & 0xffff0000u)}; }
; __device__ __forceinline__ void st_bf4(bf16_t* p, f32x4 v) { u32x2 w; w.x = pk2(v[0], v[1]); w.y = pk2(v[2], v[3]); *(u32x2*)p = w; }
; #define LBAR() do { asm volatile("s_waitcnt lgkmcnt(0)" ::: "memory"); __builtin_amdgcn_s_barrier(); asm volatile("" ::: "memory"); } while (0)
; template <int MODOFF, int STORE  , bool BASE_BF16>
; __device__ __forceinline__ void epi_rows_part1(LAS unsigned char* lds, const f32x4 (&acc)[2][2][4][2], const Unit& u, const float* base, const float* mod, float* outp, float* slots, f32x4 (&xr)[2][16]) {
;     ...
;     for (int ai = 0; ai < 2; ++ai) {
;         if (ai) LBAR();
; #pragma unroll
;         for (int m = 0; m < 4; ++m)
; #pragma unroll
;             for (int bj = 0; bj < 2; ++bj)
; #pragma unroll
;                 for (int n = 0; n < 2; ++n) { const int rl = wr * 64 + m * 16 + fr, c4 = (bj * HALF + wc * 32 + n * 16 + 4 * fq) >> 2;
;                     *(LAS f32x4*)(T + rl * 256 + ((c4 ^ (rl & 15)) << 2)) = acc[ai][bj][m][n]; }
;         LBAR();
; #pragma unroll
;         for (int j = 0; j < 16; ++j) { const int rl = wid * 16 + j, row = u.pm * BM + ai * HALF + rl; const size_t o = (size_t)row * DM + colg;
;             const f32x4 v = *(const LAS f32x4*)(T + rl * 256 + ((lane ^ j) << 2));
;             const f32x4 bs = BASE_BF16 ? ld_bf4((const bf16_t*)base + o) : *(const f32x4*)(base + o);
;             const f32x4 x1 = bs + gt * v; xr[ai][j] = x1; if (STORE == 2) st_bf4((bf16_t*)outp + o, x1);
;             const float sq = wave_sum((x1[0] * x1[0] + x1[1] * x1[1]) + (x1[2] * x1[2] + x1[3] * x1[3]));
;             if (lane == 0) __hip_atomic_store((unsigned*)slots + (size_t)row * 8 + u.pn, __float_as_uint(sq), __ATOMIC_RELAXED, __HIP_MEMORY_SCOPE_AGENT); }
.LBB0_1925:
	s_or_b64 exec, exec, s[2:3]
	s_or_b32 s22, s46, 0x80
	s_add_i32 s0, s8, s22
	s_ashr_i32 s1, s0, 31
	s_waitcnt lgkmcnt(0)
	s_barrier
	ds_write_b128 v132, v[60:63]
	ds_write_b128 v133, v[56:59]
	ds_write_b128 v134, v[52:55]
	ds_write_b128 v135, v[48:51]
	ds_write_b128 v132, v[44:47] offset:16384
	ds_write_b128 v133, v[40:43] offset:16384
	ds_write_b128 v134, v[36:39] offset:16384
	ds_write_b128 v135, v[32:35] offset:16384
	ds_write_b128 v132, v[28:31] offset:32768
	ds_write_b128 v133, v[24:27] offset:32768
	ds_write_b128 v134, v[20:23] offset:32768
	ds_write_b128 v135, v[16:19] offset:32768
	ds_write_b128 v132, v[12:15] offset:49152
	ds_write_b128 v133, v[8:11] offset:49152
	ds_write_b128 v134, v[4:7] offset:49152
	ds_write_b128 v135, v[0:3] offset:49152
	s_lshl_b64 s[2:3], s[0:1], 12
	s_waitcnt lgkmcnt(0)
	s_barrier
	v_lshl_add_u64 v[0:1], v[136:137], 0, s[2:3]
	s_mov_b64 s[98:99], 0x1000
	global_load_dwordx2 v[164:165], v[0:1], off
	v_lshl_add_u64 v[252:253], v[0:1], 0, s[98:99]
	global_load_dwordx2 v[168:169], v[252:253], off
	v_lshl_add_u64 v[252:253], v[252:253], 0, s[98:99]
	global_load_dwordx2 v[172:173], v[252:253], off
	v_lshl_add_u64 v[252:253], v[252:253], 0, s[98:99]
	global_load_dwordx2 v[176:177], v[252:253], off
	v_lshl_add_u64 v[252:253], v[252:253], 0, s[98:99]
	global_load_dwordx2 v[180:181], v[252:253], off
	v_lshl_add_u64 v[252:253], v[252:253], 0, s[98:99]
	global_load_dwordx2 v[184:185], v[252:253], off
	v_lshl_add_u64 v[252:253], v[252:253], 0, s[98:99]
	global_load_dwordx2 v[196:197], v[252:253], off
	v_lshl_add_u64 v[252:253], v[252:253], 0, s[98:99]
	global_load_dwordx2 v[200:201], v[252:253], off
	v_lshl_add_u64 v[252:253], v[252:253], 0, s[98:99]
	global_load_dwordx2 v[204:205], v[252:253], off
	v_lshl_add_u64 v[252:253], v[252:253], 0, s[98:99]
	global_load_dwordx2 v[208:209], v[252:253], off
	v_lshl_add_u64 v[252:253], v[252:253], 0, s[98:99]
	global_load_dwordx2 v[212:213], v[252:253], off
	v_lshl_add_u64 v[252:253], v[252:253], 0, s[98:99]
	global_load_dwordx2 v[216:217], v[252:253], off
	v_lshl_add_u64 v[252:253], v[252:253], 0, s[98:99]
	global_load_dwordx2 v[220:221], v[252:253], off
	v_lshl_add_u64 v[252:253], v[252:253], 0, s[98:99]
	global_load_dwordx2 v[224:225], v[252:253], off
	v_lshl_add_u64 v[252:253], v[252:253], 0, s[98:99]
	global_load_dwordx2 v[228:229], v[252:253], off
	v_lshl_add_u64 v[252:253], v[252:253], 0, s[98:99]
	global_load_dwordx2 v[232:233], v[252:253], off
	ds_read_b128 v[0:3], v138
	s_waitcnt vmcnt(15)
	v_mov_b32_e32 v4, v164
	v_mov_b32_e32 v5, v165
	v_lshlrev_b32_e32 v6, 16, v4
	v_and_b32_e32 v7, 0xffff0000, v4
	v_lshlrev_b32_e32 v4, 16, v5
	v_and_b32_e32 v5, 0xffff0000, v5
	s_waitcnt lgkmcnt(0)
	v_pk_fma_f32 v[132:133], v[66:67], v[2:3], v[4:5]
	v_pk_fma_f32 v[134:135], v[64:65], v[0:1], v[6:7]
	v_mul_f32_e32 v1, v133, v133
	v_mul_f32_e32 v0, v135, v135
	v_fmac_f32_e32 v0, v134, v134
	v_fmac_f32_e32 v1, v132, v132
	v_add_f32_e32 v0, v0, v1
	s_nop 1
	v_mov_b32_dpp v1, v0 quad_perm:[1,0,3,2] row_mask:0xf bank_mask:0xf
	s_waitcnt lgkmcnt(0)
	v_add_f32_e32 v0, v0, v1
	s_nop 1
	v_mov_b32_dpp v1, v0 quad_perm:[2,3,0,1] row_mask:0xf bank_mask:0xf
	s_waitcnt lgkmcnt(0)
	v_add_f32_e32 v0, v0, v1
	s_nop 1
	v_mov_b32_dpp v1, v0 row_ror:12 row_mask:0xf bank_mask:0xf
	s_waitcnt lgkmcnt(0)
	v_add_f32_e32 v0, v0, v1
	s_nop 1
	v_mov_b32_dpp v1, v0 row_ror:8 row_mask:0xf bank_mask:0xf
	s_waitcnt lgkmcnt(0)
	v_add_f32_e32 v0, v0, v1
	v_mov_b32_e32 v1, v0
	s_nop 1
	v_permlane16_swap_b32_e32 v0, v1
	s_waitcnt lgkmcnt(0)
	v_add_f32_e32 v0, v0, v1
	v_mov_b32_e32 v1, v0
	s_nop 1
	v_permlane32_swap_b32_e32 v0, v1
	s_and_saveexec_b64 s[2:3], vcc
	s_cbranch_execz .LBB0_1927
	s_lshl_b64 s[0:1], s[0:1], 5
	s_add_u32 s0, s4, s0
	s_addc_u32 s1, s5, s1
	v_mov_b32_e32 v2, 0
	s_waitcnt lgkmcnt(0)
	v_add_f32_e32 v0, v0, v1
	global_store_dword v2, v0, s[0:1] sc1
.LBB0_1927:
	s_or_b64 exec, exec, s[2:3]
	s_add_i32 s0, s6, s22
	s_ashr_i32 s1, s0, 31
	s_lshl_b64 s[2:3], s[0:1], 12
	s_waitcnt lgkmcnt(0)
	v_lshl_add_u64 v[0:1], v[136:137], 0, s[2:3]
	ds_read_b128 v[0:3], v139
	s_waitcnt vmcnt(15)
	v_mov_b32_e32 v4, v168
	v_mov_b32_e32 v5, v169
	v_lshlrev_b32_e32 v6, 16, v4
	v_and_b32_e32 v7, 0xffff0000, v4
	v_lshlrev_b32_e32 v4, 16, v5
	v_and_b32_e32 v5, 0xffff0000, v5
	s_waitcnt lgkmcnt(0)
	v_pk_fma_f32 v[60:61], v[66:67], v[2:3], v[4:5]
	v_pk_fma_f32 v[62:63], v[64:65], v[0:1], v[6:7]
	v_mul_f32_e32 v1, v61, v61
	v_mul_f32_e32 v0, v63, v63
	v_fmac_f32_e32 v0, v62, v62
	v_fmac_f32_e32 v1, v60, v60
	v_add_f32_e32 v0, v0, v1
	s_nop 1
	v_mov_b32_dpp v1, v0 quad_perm:[1,0,3,2] row_mask:0xf bank_mask:0xf
	s_waitcnt lgkmcnt(0)
	v_add_f32_e32 v0, v0, v1
	s_nop 1
	v_mov_b32_dpp v1, v0 quad_perm:[2,3,0,1] row_mask:0xf bank_mask:0xf
	s_waitcnt lgkmcnt(0)
	v_add_f32_e32 v0, v0, v1
	s_nop 1
	v_mov_b32_dpp v1, v0 row_ror:12 row_mask:0xf bank_mask:0xf
	s_waitcnt lgkmcnt(0)
	v_add_f32_e32 v0, v0, v1
	s_nop 1
	v_mov_b32_dpp v1, v0 row_ror:8 row_mask:0xf bank_mask:0xf
	s_waitcnt lgkmcnt(0)
	v_add_f32_e32 v0, v0, v1
	v_mov_b32_e32 v1, v0
	s_nop 1
	v_permlane16_swap_b32_e32 v0, v1
	s_waitcnt lgkmcnt(0)
	v_add_f32_e32 v0, v0, v1
	v_mov_b32_e32 v1, v0
	s_nop 1
	v_permlane32_swap_b32_e32 v0, v1
	s_and_saveexec_b64 s[2:3], vcc
	s_cbranch_execz .LBB0_1929
	s_lshl_b64 s[0:1], s[0:1], 5
	s_add_u32 s0, s4, s0
	s_addc_u32 s1, s5, s1
	v_mov_b32_e32 v2, 0
	s_waitcnt lgkmcnt(0)
	v_add_f32_e32 v0, v0, v1
	global_store_dword v2, v0, s[0:1] sc1
; #define LAS __attribute__((address_space(3)))
; __device__ __forceinline__ f32x4 ld_bf4(const bf16_t* p) { u32x2 w = *(const u32x2*)p; return (f32x4){__uint_as_float(w.x << 16), __uint_as_float(w.x & 0xffff0000u), __uint_as_float(w.y << 16), __uint_as_float(w.y & 0xffff0000u)}; }
; __device__ __forceinline__ void st_bf4(bf16_t* p, f32x4 v) { u32x2 w; w.x = pk2(v[0], v[1]); w.y = pk2(v[2], v[3]); *(u32x2*)p = w; }
; __device__ __forceinline__ float wave_sum(float v) {
; #pragma unroll
;     for (int o = 1; o < 64; o <<= 1) v += __shfl_xor(v, o);
;     return v;
; template <int MODOFF, int STORE  , bool BASE_BF16>
; __device__ __forceinline__ void epi_rows_part1(LAS unsigned char* lds, const f32x4 (&acc)[2][2][4][2], const Unit& u, const float* base, const float* mod, float* outp, float* slots, f32x4 (&xr)[2][16]) {
;     ...
;         for (int j = 0; j < 16; ++j) { const int rl = wid * 16 + j, row = u.pm * BM + ai * HALF + rl; const size_t o = (size_t)row * DM + colg;
;             const f32x4 v = *(const LAS f32x4*)(T + rl * 256 + ((lane ^ j) << 2));
;             const f32x4 bs = BASE_BF16 ? ld_bf4((const bf16_t*)base + o) : *(const f32x4*)(base + o);
;             const f32x4 x1 = bs + gt * v; xr[ai][j] = x1; if (STORE == 2) st_bf4((bf16_t*)outp + o, x1);
;             const float sq = wave_sum((x1[0] * x1[0] + x1[1] * x1[1]) + (x1[2] * x1[2] + x1[3] * x1[3]));
;             if (lane == 0) __hip_atomic_store((unsigned*)slots + (size_t)row * 8 + u.pn, __float_as_uint(sq), __ATOMIC_RELAXED, __HIP_MEMORY_SCOPE_AGENT); }
.LBB0_1929:
	s_or_b64 exec, exec, s[2:3]
	s_add_i32 s0, s7, s22
	s_ashr_i32 s1, s0, 31
	s_lshl_b64 s[2:3], s[0:1], 12
	s_waitcnt lgkmcnt(0)
	v_lshl_add_u64 v[0:1], v[136:137], 0, s[2:3]
	ds_read_b128 v[0:3], v140
	s_waitcnt vmcnt(15)
	v_mov_b32_e32 v4, v172
	v_mov_b32_e32 v5, v173
	v_lshlrev_b32_e32 v6, 16, v4
	v_and_b32_e32 v7, 0xffff0000, v4
	v_lshlrev_b32_e32 v4, 16, v5
	v_and_b32_e32 v5, 0xffff0000, v5
	s_waitcnt lgkmcnt(0)
	v_pk_fma_f32 v[56:57], v[66:67], v[2:3], v[4:5]
	v_pk_fma_f32 v[58:59], v[64:65], v[0:1], v[6:7]
	v_mul_f32_e32 v1, v57, v57
	v_mul_f32_e32 v0, v59, v59
	v_fmac_f32_e32 v0, v58, v58
	v_fmac_f32_e32 v1, v56, v56
	v_add_f32_e32 v0, v0, v1
	s_nop 1
	v_mov_b32_dpp v1, v0 quad_perm:[1,0,3,2] row_mask:0xf bank_mask:0xf
	s_waitcnt lgkmcnt(0)
	v_add_f32_e32 v0, v0, v1
	s_nop 1
	v_mov_b32_dpp v1, v0 quad_perm:[2,3,0,1] row_mask:0xf bank_mask:0xf
	s_waitcnt lgkmcnt(0)
	v_add_f32_e32 v0, v0, v1
	s_nop 1
	v_mov_b32_dpp v1, v0 row_ror:12 row_mask:0xf bank_mask:0xf
	s_waitcnt lgkmcnt(0)
	v_add_f32_e32 v0, v0, v1
	s_nop 1
	v_mov_b32_dpp v1, v0 row_ror:8 row_mask:0xf bank_mask:0xf
	s_waitcnt lgkmcnt(0)
	v_add_f32_e32 v0, v0, v1
	v_mov_b32_e32 v1, v0
	s_nop 1
	v_permlane16_swap_b32_e32 v0, v1
	s_waitcnt lgkmcnt(0)
	v_add_f32_e32 v0, v0, v1
	v_mov_b32_e32 v1, v0
	s_nop 1
	v_permlane32_swap_b32_e32 v0, v1
	s_and_saveexec_b64 s[2:3], vcc
	s_cbranch_execz .LBB0_1931
	s_lshl_b64 s[0:1], s[0:1], 5
	s_add_u32 s0, s4, s0
	s_addc_u32 s1, s5, s1
	v_mov_b32_e32 v2, 0
	s_waitcnt lgkmcnt(0)
	v_add_f32_e32 v0, v0, v1
	global_store_dword v2, v0, s[0:1] sc1
.LBB0_1931:
	s_or_b64 exec, exec, s[2:3]
	s_add_i32 s0, s9, s22
	s_ashr_i32 s1, s0, 31
	s_lshl_b64 s[2:3], s[0:1], 12
	s_waitcnt lgkmcnt(0)
	v_lshl_add_u64 v[0:1], v[136:137], 0, s[2:3]
	ds_read_b128 v[0:3], v141
	s_waitcnt vmcnt(15)
	v_mov_b32_e32 v4, v176
	v_mov_b32_e32 v5, v177
	v_lshlrev_b32_e32 v6, 16, v4
	v_and_b32_e32 v7, 0xffff0000, v4
	v_lshlrev_b32_e32 v4, 16, v5
	v_and_b32_e32 v5, 0xffff0000, v5
	s_waitcnt lgkmcnt(0)
	v_pk_fma_f32 v[52:53], v[66:67], v[2:3], v[4:5]
	v_pk_fma_f32 v[54:55], v[64:65], v[0:1], v[6:7]
	v_mul_f32_e32 v1, v53, v53
	v_mul_f32_e32 v0, v55, v55
	v_fmac_f32_e32 v0, v54, v54
	v_fmac_f32_e32 v1, v52, v52
	v_add_f32_e32 v0, v0, v1
	s_nop 1
	v_mov_b32_dpp v1, v0 quad_perm:[1,0,3,2] row_mask:0xf bank_mask:0xf
	s_waitcnt lgkmcnt(0)
	v_add_f32_e32 v0, v0, v1
	s_nop 1
	v_mov_b32_dpp v1, v0 quad_perm:[2,3,0,1] row_mask:0xf bank_mask:0xf
	s_waitcnt lgkmcnt(0)
	v_add_f32_e32 v0, v0, v1
	s_nop 1
	v_mov_b32_dpp v1, v0 row_ror:12 row_mask:0xf bank_mask:0xf
	s_waitcnt lgkmcnt(0)
	v_add_f32_e32 v0, v0, v1
	s_nop 1
	v_mov_b32_dpp v1, v0 row_ror:8 row_mask:0xf bank_mask:0xf
	s_waitcnt lgkmcnt(0)
	v_add_f32_e32 v0, v0, v1
	v_mov_b32_e32 v1, v0
	s_nop 1
	v_permlane16_swap_b32_e32 v0, v1
	s_waitcnt lgkmcnt(0)
	v_add_f32_e32 v0, v0, v1
	v_mov_b32_e32 v1, v0
	s_nop 1
	v_permlane32_swap_b32_e32 v0, v1
	s_and_saveexec_b64 s[2:3], vcc
	s_cbranch_execz .LBB0_1933
	s_lshl_b64 s[0:1], s[0:1], 5
	s_add_u32 s0, s4, s0
	s_addc_u32 s1, s5, s1
	v_mov_b32_e32 v2, 0
	s_waitcnt lgkmcnt(0)
	v_add_f32_e32 v0, v0, v1
	global_store_dword v2, v0, s[0:1] sc1
.LBB0_1933:
	s_or_b64 exec, exec, s[2:3]
	s_add_i32 s0, s10, s22
	s_ashr_i32 s1, s0, 31
	s_lshl_b64 s[2:3], s[0:1], 12
	s_waitcnt lgkmcnt(0)
	v_lshl_add_u64 v[0:1], v[136:137], 0, s[2:3]
	ds_read_b128 v[0:3], v142
	s_waitcnt vmcnt(15)
	v_mov_b32_e32 v4, v180
	v_mov_b32_e32 v5, v181
	v_lshlrev_b32_e32 v6, 16, v4
	v_and_b32_e32 v7, 0xffff0000, v4
	v_lshlrev_b32_e32 v4, 16, v5
	v_and_b32_e32 v5, 0xffff0000, v5
	s_waitcnt lgkmcnt(0)
	v_pk_fma_f32 v[48:49], v[66:67], v[2:3], v[4:5]
	v_pk_fma_f32 v[50:51], v[64:65], v[0:1], v[6:7]
	v_mul_f32_e32 v1, v49, v49
	v_mul_f32_e32 v0, v51, v51
	v_fmac_f32_e32 v0, v50, v50
	v_fmac_f32_e32 v1, v48, v48
	v_add_f32_e32 v0, v0, v1
	s_nop 1
	v_mov_b32_dpp v1, v0 quad_perm:[1,0,3,2] row_mask:0xf bank_mask:0xf
	s_waitcnt lgkmcnt(0)
	v_add_f32_e32 v0, v0, v1
	s_nop 1
	v_mov_b32_dpp v1, v0 quad_perm:[2,3,0,1] row_mask:0xf bank_mask:0xf
	s_waitcnt lgkmcnt(0)
	v_add_f32_e32 v0, v0, v1
	s_nop 1
	v_mov_b32_dpp v1, v0 row_ror:12 row_mask:0xf bank_mask:0xf
	s_waitcnt lgkmcnt(0)
	v_add_f32_e32 v0, v0, v1
	s_nop 1
	v_mov_b32_dpp v1, v0 row_ror:8 row_mask:0xf bank_mask:0xf
	s_waitcnt lgkmcnt(0)
	v_add_f32_e32 v0, v0, v1
	v_mov_b32_e32 v1, v0
	s_nop 1
	v_permlane16_swap_b32_e32 v0, v1
	s_waitcnt lgkmcnt(0)
	v_add_f32_e32 v0, v0, v1
	v_mov_b32_e32 v1, v0
	s_nop 1
	v_permlane32_swap_b32_e32 v0, v1
	s_and_saveexec_b64 s[2:3], vcc
	s_cbranch_execz .LBB0_1935
	s_lshl_b64 s[0:1], s[0:1], 5
	s_add_u32 s0, s4, s0
	s_addc_u32 s1, s5, s1
	v_mov_b32_e32 v2, 0
	s_waitcnt lgkmcnt(0)
	v_add_f32_e32 v0, v0, v1
	global_store_dword v2, v0, s[0:1] sc1
.LBB0_1935:
	s_or_b64 exec, exec, s[2:3]
	s_add_i32 s0, s11, s22
	s_ashr_i32 s1, s0, 31
	s_lshl_b64 s[2:3], s[0:1], 12
	s_waitcnt lgkmcnt(0)
	v_lshl_add_u64 v[0:1], v[136:137], 0, s[2:3]
	ds_read_b128 v[0:3], v143
	s_waitcnt vmcnt(15)
	v_mov_b32_e32 v4, v184
	v_mov_b32_e32 v5, v185
	v_lshlrev_b32_e32 v6, 16, v4
	v_and_b32_e32 v7, 0xffff0000, v4
	v_lshlrev_b32_e32 v4, 16, v5
	v_and_b32_e32 v5, 0xffff0000, v5
	s_waitcnt lgkmcnt(0)
	v_pk_fma_f32 v[44:45], v[66:67], v[2:3], v[4:5]
	v_pk_fma_f32 v[46:47], v[64:65], v[0:1], v[6:7]
	v_mul_f32_e32 v1, v45, v45
	v_mul_f32_e32 v0, v47, v47
	v_fmac_f32_e32 v0, v46, v46
	v_fmac_f32_e32 v1, v44, v44
	v_add_f32_e32 v0, v0, v1
	s_nop 1
	v_mov_b32_dpp v1, v0 quad_perm:[1,0,3,2] row_mask:0xf bank_mask:0xf
	s_waitcnt lgkmcnt(0)
	v_add_f32_e32 v0, v0, v1
	s_nop 1
	v_mov_b32_dpp v1, v0 quad_perm:[2,3,0,1] row_mask:0xf bank_mask:0xf
	s_waitcnt lgkmcnt(0)
	v_add_f32_e32 v0, v0, v1
	s_nop 1
	v_mov_b32_dpp v1, v0 row_ror:12 row_mask:0xf bank_mask:0xf
	s_waitcnt lgkmcnt(0)
	v_add_f32_e32 v0, v0, v1
	s_nop 1
	v_mov_b32_dpp v1, v0 row_ror:8 row_mask:0xf bank_mask:0xf
	s_waitcnt lgkmcnt(0)
	v_add_f32_e32 v0, v0, v1
	v_mov_b32_e32 v1, v0
	s_nop 1
	v_permlane16_swap_b32_e32 v0, v1
	s_waitcnt lgkmcnt(0)
	v_add_f32_e32 v0, v0, v1
	v_mov_b32_e32 v1, v0
	s_nop 1
	v_permlane32_swap_b32_e32 v0, v1
	s_and_saveexec_b64 s[2:3], vcc
	s_cbranch_execz .LBB0_1937
	s_lshl_b64 s[0:1], s[0:1], 5
	s_add_u32 s0, s4, s0
	s_addc_u32 s1, s5, s1
	v_mov_b32_e32 v2, 0
	s_waitcnt lgkmcnt(0)
	v_add_f32_e32 v0, v0, v1
	global_store_dword v2, v0, s[0:1] sc1
; #define LAS __attribute__((address_space(3)))
; __device__ __forceinline__ f32x4 ld_bf4(const bf16_t* p) { u32x2 w = *(const u32x2*)p; return (f32x4){__uint_as_float(w.x << 16), __uint_as_float(w.x & 0xffff0000u), __uint_as_float(w.y << 16), __uint_as_float(w.y & 0xffff0000u)}; }
; __device__ __forceinline__ void st_bf4(bf16_t* p, f32x4 v) { u32x2 w; w.x = pk2(v[0], v[1]); w.y = pk2(v[2], v[3]); *(u32x2*)p = w; }
; __device__ __forceinline__ float wave_sum(float v) {
; #pragma unroll
;     for (int o = 1; o < 64; o <<= 1) v += __shfl_xor(v, o);
;     return v;
; template <int MODOFF, int STORE  , bool BASE_BF16>
; __device__ __forceinline__ void epi_rows_part1(LAS unsigned char* lds, const f32x4 (&acc)[2][2][4][2], const Unit& u, const float* base, const float* mod, float* outp, float* slots, f32x4 (&xr)[2][16]) {
;     ...
;         for (int j = 0; j < 16; ++j) { const int rl = wid * 16 + j, row = u.pm * BM + ai * HALF + rl; const size_t o = (size_t)row * DM + colg;
;             const f32x4 v = *(const LAS f32x4*)(T + rl * 256 + ((lane ^ j) << 2));
;             const f32x4 bs = BASE_BF16 ? ld_bf4((const bf16_t*)base + o) : *(const f32x4*)(base + o);
;             const f32x4 x1 = bs + gt * v; xr[ai][j] = x1; if (STORE == 2) st_bf4((bf16_t*)outp + o, x1);
;             const float sq = wave_sum((x1[0] * x1[0] + x1[1] * x1[1]) + (x1[2] * x1[2] + x1[3] * x1[3]));
;             if (lane == 0) __hip_atomic_store((unsigned*)slots + (size_t)row * 8 + u.pn, __float_as_uint(sq), __ATOMIC_RELAXED, __HIP_MEMORY_SCOPE_AGENT); }
.LBB0_1937:
	s_or_b64 exec, exec, s[2:3]
	s_add_i32 s0, s12, s22
	s_ashr_i32 s1, s0, 31
	s_lshl_b64 s[2:3], s[0:1], 12
	s_waitcnt lgkmcnt(0)
	v_lshl_add_u64 v[0:1], v[136:137], 0, s[2:3]
	ds_read_b128 v[0:3], v144
	s_waitcnt vmcnt(15)
	v_mov_b32_e32 v4, v196
	v_mov_b32_e32 v5, v197
	v_lshlrev_b32_e32 v6, 16, v4
	v_and_b32_e32 v7, 0xffff0000, v4
	v_lshlrev_b32_e32 v4, 16, v5
	v_and_b32_e32 v5, 0xffff0000, v5
	s_waitcnt lgkmcnt(0)
	v_pk_fma_f32 v[40:41], v[66:67], v[2:3], v[4:5]
	v_pk_fma_f32 v[42:43], v[64:65], v[0:1], v[6:7]
	v_mul_f32_e32 v1, v41, v41
	v_mul_f32_e32 v0, v43, v43
	v_fmac_f32_e32 v0, v42, v42
	v_fmac_f32_e32 v1, v40, v40
	v_add_f32_e32 v0, v0, v1
	s_nop 1
	v_mov_b32_dpp v1, v0 quad_perm:[1,0,3,2] row_mask:0xf bank_mask:0xf
	s_waitcnt lgkmcnt(0)
	v_add_f32_e32 v0, v0, v1
	s_nop 1
	v_mov_b32_dpp v1, v0 quad_perm:[2,3,0,1] row_mask:0xf bank_mask:0xf
	s_waitcnt lgkmcnt(0)
	v_add_f32_e32 v0, v0, v1
	s_nop 1
	v_mov_b32_dpp v1, v0 row_ror:12 row_mask:0xf bank_mask:0xf
	s_waitcnt lgkmcnt(0)
	v_add_f32_e32 v0, v0, v1
	s_nop 1
	v_mov_b32_dpp v1, v0 row_ror:8 row_mask:0xf bank_mask:0xf
	s_waitcnt lgkmcnt(0)
	v_add_f32_e32 v0, v0, v1
	v_mov_b32_e32 v1, v0
	s_nop 1
	v_permlane16_swap_b32_e32 v0, v1
	s_waitcnt lgkmcnt(0)
	v_add_f32_e32 v0, v0, v1
	v_mov_b32_e32 v1, v0
	s_nop 1
	v_permlane32_swap_b32_e32 v0, v1
	s_and_saveexec_b64 s[2:3], vcc
	s_cbranch_execz .LBB0_1939
	s_lshl_b64 s[0:1], s[0:1], 5
	s_add_u32 s0, s4, s0
	s_addc_u32 s1, s5, s1
	v_mov_b32_e32 v2, 0
	s_waitcnt lgkmcnt(0)
	v_add_f32_e32 v0, v0, v1
	global_store_dword v2, v0, s[0:1] sc1
.LBB0_1939:
	s_or_b64 exec, exec, s[2:3]
	s_add_i32 s0, s13, s22
	s_ashr_i32 s1, s0, 31
	s_lshl_b64 s[2:3], s[0:1], 12
	s_waitcnt lgkmcnt(0)
	v_lshl_add_u64 v[0:1], v[136:137], 0, s[2:3]
	ds_read_b128 v[0:3], v145
	s_waitcnt vmcnt(15)
	v_mov_b32_e32 v4, v200
	v_mov_b32_e32 v5, v201
	v_lshlrev_b32_e32 v6, 16, v4
	v_and_b32_e32 v7, 0xffff0000, v4
	v_lshlrev_b32_e32 v4, 16, v5
	v_and_b32_e32 v5, 0xffff0000, v5
	s_waitcnt lgkmcnt(0)
	v_pk_fma_f32 v[36:37], v[66:67], v[2:3], v[4:5]
	v_pk_fma_f32 v[38:39], v[64:65], v[0:1], v[6:7]
	v_mul_f32_e32 v1, v37, v37
	v_mul_f32_e32 v0, v39, v39
	v_fmac_f32_e32 v0, v38, v38
	v_fmac_f32_e32 v1, v36, v36
	v_add_f32_e32 v0, v0, v1
	s_nop 1
	v_mov_b32_dpp v1, v0 quad_perm:[1,0,3,2] row_mask:0xf bank_mask:0xf
	s_waitcnt lgkmcnt(0)
	v_add_f32_e32 v0, v0, v1
	s_nop 1
	v_mov_b32_dpp v1, v0 quad_perm:[2,3,0,1] row_mask:0xf bank_mask:0xf
	s_waitcnt lgkmcnt(0)
	v_add_f32_e32 v0, v0, v1
	s_nop 1
	v_mov_b32_dpp v1, v0 row_ror:12 row_mask:0xf bank_mask:0xf
	s_waitcnt lgkmcnt(0)
	v_add_f32_e32 v0, v0, v1
	s_nop 1
	v_mov_b32_dpp v1, v0 row_ror:8 row_mask:0xf bank_mask:0xf
	s_waitcnt lgkmcnt(0)
	v_add_f32_e32 v0, v0, v1
	v_mov_b32_e32 v1, v0
	s_nop 1
	v_permlane16_swap_b32_e32 v0, v1
	s_waitcnt lgkmcnt(0)
	v_add_f32_e32 v0, v0, v1
	v_mov_b32_e32 v1, v0
	s_nop 1
	v_permlane32_swap_b32_e32 v0, v1
	s_and_saveexec_b64 s[2:3], vcc
	s_cbranch_execz .LBB0_1941
	s_lshl_b64 s[0:1], s[0:1], 5
	s_add_u32 s0, s4, s0
	s_addc_u32 s1, s5, s1
	v_mov_b32_e32 v2, 0
	s_waitcnt lgkmcnt(0)
	v_add_f32_e32 v0, v0, v1
	global_store_dword v2, v0, s[0:1] sc1
.LBB0_1941:
	s_or_b64 exec, exec, s[2:3]
	s_add_i32 s0, s14, s22
	s_ashr_i32 s1, s0, 31
	s_lshl_b64 s[2:3], s[0:1], 12
	s_waitcnt lgkmcnt(0)
	v_lshl_add_u64 v[0:1], v[136:137], 0, s[2:3]
	ds_read_b128 v[0:3], v146
	s_waitcnt vmcnt(15)
	v_mov_b32_e32 v4, v204
	v_mov_b32_e32 v5, v205
	v_lshlrev_b32_e32 v6, 16, v4
	v_and_b32_e32 v7, 0xffff0000, v4
	v_lshlrev_b32_e32 v4, 16, v5
	v_and_b32_e32 v5, 0xffff0000, v5
	s_waitcnt lgkmcnt(0)
	v_pk_fma_f32 v[32:33], v[66:67], v[2:3], v[4:5]
	v_pk_fma_f32 v[34:35], v[64:65], v[0:1], v[6:7]
	v_mul_f32_e32 v1, v33, v33
	v_mul_f32_e32 v0, v35, v35
	v_fmac_f32_e32 v0, v34, v34
	v_fmac_f32_e32 v1, v32, v32
	v_add_f32_e32 v0, v0, v1
	s_nop 1
	v_mov_b32_dpp v1, v0 quad_perm:[1,0,3,2] row_mask:0xf bank_mask:0xf
	s_waitcnt lgkmcnt(0)
	v_add_f32_e32 v0, v0, v1
	s_nop 1
	v_mov_b32_dpp v1, v0 quad_perm:[2,3,0,1] row_mask:0xf bank_mask:0xf
	s_waitcnt lgkmcnt(0)
	v_add_f32_e32 v0, v0, v1
	s_nop 1
	v_mov_b32_dpp v1, v0 row_ror:12 row_mask:0xf bank_mask:0xf
	s_waitcnt lgkmcnt(0)
	v_add_f32_e32 v0, v0, v1
	s_nop 1
	v_mov_b32_dpp v1, v0 row_ror:8 row_mask:0xf bank_mask:0xf
	s_waitcnt lgkmcnt(0)
	v_add_f32_e32 v0, v0, v1
	v_mov_b32_e32 v1, v0
	s_nop 1
	v_permlane16_swap_b32_e32 v0, v1
	s_waitcnt lgkmcnt(0)
	v_add_f32_e32 v0, v0, v1
	v_mov_b32_e32 v1, v0
	s_nop 1
	v_permlane32_swap_b32_e32 v0, v1
	s_and_saveexec_b64 s[2:3], vcc
	s_cbranch_execz .LBB0_1943
	s_lshl_b64 s[0:1], s[0:1], 5
	s_add_u32 s0, s4, s0
	s_addc_u32 s1, s5, s1
	v_mov_b32_e32 v2, 0
	s_waitcnt lgkmcnt(0)
	v_add_f32_e32 v0, v0, v1
	global_store_dword v2, v0, s[0:1] sc1
.LBB0_1943:
	s_or_b64 exec, exec, s[2:3]
	s_add_i32 s0, s15, s22
	s_ashr_i32 s1, s0, 31
	s_lshl_b64 s[2:3], s[0:1], 12
	s_waitcnt lgkmcnt(0)
	v_lshl_add_u64 v[0:1], v[136:137], 0, s[2:3]
	ds_read_b128 v[0:3], v147
	s_waitcnt vmcnt(15)
	v_mov_b32_e32 v4, v208
	v_mov_b32_e32 v5, v209
	v_lshlrev_b32_e32 v6, 16, v4
	v_and_b32_e32 v7, 0xffff0000, v4
	v_lshlrev_b32_e32 v4, 16, v5
	v_and_b32_e32 v5, 0xffff0000, v5
	s_waitcnt lgkmcnt(0)
	v_pk_fma_f32 v[28:29], v[66:67], v[2:3], v[4:5]
	v_pk_fma_f32 v[30:31], v[64:65], v[0:1], v[6:7]
	v_mul_f32_e32 v1, v29, v29
	v_mul_f32_e32 v0, v31, v31
	v_fmac_f32_e32 v0, v30, v30
	v_fmac_f32_e32 v1, v28, v28
	v_add_f32_e32 v0, v0, v1
	s_nop 1
	v_mov_b32_dpp v1, v0 quad_perm:[1,0,3,2] row_mask:0xf bank_mask:0xf
	s_waitcnt lgkmcnt(0)
	v_add_f32_e32 v0, v0, v1
	s_nop 1
	v_mov_b32_dpp v1, v0 quad_perm:[2,3,0,1] row_mask:0xf bank_mask:0xf
	s_waitcnt lgkmcnt(0)
	v_add_f32_e32 v0, v0, v1
	s_nop 1
	v_mov_b32_dpp v1, v0 row_ror:12 row_mask:0xf bank_mask:0xf
	s_waitcnt lgkmcnt(0)
	v_add_f32_e32 v0, v0, v1
	s_nop 1
	v_mov_b32_dpp v1, v0 row_ror:8 row_mask:0xf bank_mask:0xf
	s_waitcnt lgkmcnt(0)
	v_add_f32_e32 v0, v0, v1
	v_mov_b32_e32 v1, v0
	s_nop 1
	v_permlane16_swap_b32_e32 v0, v1
	s_waitcnt lgkmcnt(0)
	v_add_f32_e32 v0, v0, v1
	v_mov_b32_e32 v1, v0
	s_nop 1
	v_permlane32_swap_b32_e32 v0, v1
	s_and_saveexec_b64 s[2:3], vcc
	s_cbranch_execz .LBB0_1945
	s_lshl_b64 s[0:1], s[0:1], 5
	s_add_u32 s0, s4, s0
	s_addc_u32 s1, s5, s1
	v_mov_b32_e32 v2, 0
	s_waitcnt lgkmcnt(0)
	v_add_f32_e32 v0, v0, v1
	global_store_dword v2, v0, s[0:1] sc1
; #define LAS __attribute__((address_space(3)))
; __device__ __forceinline__ f32x4 ld_bf4(const bf16_t* p) { u32x2 w = *(const u32x2*)p; return (f32x4){__uint_as_float(w.x << 16), __uint_as_float(w.x & 0xffff0000u), __uint_as_float(w.y << 16), __uint_as_float(w.y & 0xffff0000u)}; }
; __device__ __forceinline__ void st_bf4(bf16_t* p, f32x4 v) { u32x2 w; w.x = pk2(v[0], v[1]); w.y = pk2(v[2], v[3]); *(u32x2*)p = w; }
; __device__ __forceinline__ float wave_sum(float v) {
; #pragma unroll
;     for (int o = 1; o < 64; o <<= 1) v += __shfl_xor(v, o);
;     return v;
; template <int MODOFF, int STORE  , bool BASE_BF16>
; __device__ __forceinline__ void epi_rows_part1(LAS unsigned char* lds, const f32x4 (&acc)[2][2][4][2], const Unit& u, const float* base, const float* mod, float* outp, float* slots, f32x4 (&xr)[2][16]) {
;     ...
;         for (int j = 0; j < 16; ++j) { const int rl = wid * 16 + j, row = u.pm * BM + ai * HALF + rl; const size_t o = (size_t)row * DM + colg;
;             const f32x4 v = *(const LAS f32x4*)(T + rl * 256 + ((lane ^ j) << 2));
;             const f32x4 bs = BASE_BF16 ? ld_bf4((const bf16_t*)base + o) : *(const f32x4*)(base + o);
;             const f32x4 x1 = bs + gt * v; xr[ai][j] = x1; if (STORE == 2) st_bf4((bf16_t*)outp + o, x1);
;             const float sq = wave_sum((x1[0] * x1[0] + x1[1] * x1[1]) + (x1[2] * x1[2] + x1[3] * x1[3]));
;             if (lane == 0) __hip_atomic_store((unsigned*)slots + (size_t)row * 8 + u.pn, __float_as_uint(sq), __ATOMIC_RELAXED, __HIP_MEMORY_SCOPE_AGENT); }
.LBB0_1945:
	s_or_b64 exec, exec, s[2:3]
	s_add_i32 s0, s16, s22
	s_ashr_i32 s1, s0, 31
	s_lshl_b64 s[2:3], s[0:1], 12
	s_waitcnt lgkmcnt(0)
	v_lshl_add_u64 v[0:1], v[136:137], 0, s[2:3]
	ds_read_b128 v[0:3], v148
	s_waitcnt vmcnt(15)
	v_mov_b32_e32 v4, v212
	v_mov_b32_e32 v5, v213
	v_lshlrev_b32_e32 v6, 16, v4
	v_and_b32_e32 v7, 0xffff0000, v4
	v_lshlrev_b32_e32 v4, 16, v5
	v_and_b32_e32 v5, 0xffff0000, v5
	s_waitcnt lgkmcnt(0)
	v_pk_fma_f32 v[24:25], v[66:67], v[2:3], v[4:5]
	v_pk_fma_f32 v[26:27], v[64:65], v[0:1], v[6:7]
	v_mul_f32_e32 v1, v25, v25
	v_mul_f32_e32 v0, v27, v27
	v_fmac_f32_e32 v0, v26, v26
	v_fmac_f32_e32 v1, v24, v24
	v_add_f32_e32 v0, v0, v1
	s_nop 1
	v_mov_b32_dpp v1, v0 quad_perm:[1,0,3,2] row_mask:0xf bank_mask:0xf
	s_waitcnt lgkmcnt(0)
	v_add_f32_e32 v0, v0, v1
	s_nop 1
	v_mov_b32_dpp v1, v0 quad_perm:[2,3,0,1] row_mask:0xf bank_mask:0xf
	s_waitcnt lgkmcnt(0)
	v_add_f32_e32 v0, v0, v1
	s_nop 1
	v_mov_b32_dpp v1, v0 row_ror:12 row_mask:0xf bank_mask:0xf
	s_waitcnt lgkmcnt(0)
	v_add_f32_e32 v0, v0, v1
	s_nop 1
	v_mov_b32_dpp v1, v0 row_ror:8 row_mask:0xf bank_mask:0xf
	s_waitcnt lgkmcnt(0)
	v_add_f32_e32 v0, v0, v1
	v_mov_b32_e32 v1, v0
	s_nop 1
	v_permlane16_swap_b32_e32 v0, v1
	s_waitcnt lgkmcnt(0)
	v_add_f32_e32 v0, v0, v1
	v_mov_b32_e32 v1, v0
	s_nop 1
	v_permlane32_swap_b32_e32 v0, v1
	s_and_saveexec_b64 s[2:3], vcc
	s_cbranch_execz .LBB0_1947
	s_lshl_b64 s[0:1], s[0:1], 5
	s_add_u32 s0, s4, s0
	s_addc_u32 s1, s5, s1
	v_mov_b32_e32 v2, 0
	s_waitcnt lgkmcnt(0)
	v_add_f32_e32 v0, v0, v1
	global_store_dword v2, v0, s[0:1] sc1
.LBB0_1947:
	s_or_b64 exec, exec, s[2:3]
	s_add_i32 s0, s17, s22
	s_ashr_i32 s1, s0, 31
	s_lshl_b64 s[2:3], s[0:1], 12
	s_waitcnt lgkmcnt(0)
	v_lshl_add_u64 v[0:1], v[136:137], 0, s[2:3]
	ds_read_b128 v[0:3], v149
	s_waitcnt vmcnt(15)
	v_mov_b32_e32 v4, v216
	v_mov_b32_e32 v5, v217
	v_lshlrev_b32_e32 v6, 16, v4
	v_and_b32_e32 v7, 0xffff0000, v4
	v_lshlrev_b32_e32 v4, 16, v5
	v_and_b32_e32 v5, 0xffff0000, v5
	s_waitcnt lgkmcnt(0)
	v_pk_fma_f32 v[20:21], v[66:67], v[2:3], v[4:5]
	v_pk_fma_f32 v[22:23], v[64:65], v[0:1], v[6:7]
	v_mul_f32_e32 v1, v21, v21
	v_mul_f32_e32 v0, v23, v23
	v_fmac_f32_e32 v0, v22, v22
	v_fmac_f32_e32 v1, v20, v20
	v_add_f32_e32 v0, v0, v1
	s_nop 1
	v_mov_b32_dpp v1, v0 quad_perm:[1,0,3,2] row_mask:0xf bank_mask:0xf
	s_waitcnt lgkmcnt(0)
	v_add_f32_e32 v0, v0, v1
	s_nop 1
	v_mov_b32_dpp v1, v0 quad_perm:[2,3,0,1] row_mask:0xf bank_mask:0xf
	s_waitcnt lgkmcnt(0)
	v_add_f32_e32 v0, v0, v1
	s_nop 1
	v_mov_b32_dpp v1, v0 row_ror:12 row_mask:0xf bank_mask:0xf
	s_waitcnt lgkmcnt(0)
	v_add_f32_e32 v0, v0, v1
	s_nop 1
	v_mov_b32_dpp v1, v0 row_ror:8 row_mask:0xf bank_mask:0xf
	s_waitcnt lgkmcnt(0)
	v_add_f32_e32 v0, v0, v1
	v_mov_b32_e32 v1, v0
	s_nop 1
	v_permlane16_swap_b32_e32 v0, v1
	s_waitcnt lgkmcnt(0)
	v_add_f32_e32 v0, v0, v1
	v_mov_b32_e32 v1, v0
	s_nop 1
	v_permlane32_swap_b32_e32 v0, v1
	s_and_saveexec_b64 s[2:3], vcc
	s_cbranch_execz .LBB0_1949
	s_lshl_b64 s[0:1], s[0:1], 5
	s_add_u32 s0, s4, s0
	s_addc_u32 s1, s5, s1
	v_mov_b32_e32 v2, 0
	s_waitcnt lgkmcnt(0)
	v_add_f32_e32 v0, v0, v1
	global_store_dword v2, v0, s[0:1] sc1
.LBB0_1949:
	s_or_b64 exec, exec, s[2:3]
	s_add_i32 s0, s18, s22
	s_ashr_i32 s1, s0, 31
	s_lshl_b64 s[2:3], s[0:1], 12
	s_waitcnt lgkmcnt(0)
	v_lshl_add_u64 v[0:1], v[136:137], 0, s[2:3]
	ds_read_b128 v[0:3], v150
	s_waitcnt vmcnt(15)
	v_mov_b32_e32 v4, v220
	v_mov_b32_e32 v5, v221
	v_lshlrev_b32_e32 v6, 16, v4
	v_and_b32_e32 v7, 0xffff0000, v4
	v_lshlrev_b32_e32 v4, 16, v5
	v_and_b32_e32 v5, 0xffff0000, v5
	s_waitcnt lgkmcnt(0)
	v_pk_fma_f32 v[14:15], v[66:67], v[2:3], v[4:5]
	v_pk_fma_f32 v[18:19], v[64:65], v[0:1], v[6:7]
	v_mul_f32_e32 v1, v15, v15
	v_mul_f32_e32 v0, v19, v19
	v_fmac_f32_e32 v0, v18, v18
	v_fmac_f32_e32 v1, v14, v14
	v_add_f32_e32 v0, v0, v1
	s_nop 1
	v_mov_b32_dpp v1, v0 quad_perm:[1,0,3,2] row_mask:0xf bank_mask:0xf
	s_waitcnt lgkmcnt(0)
	v_add_f32_e32 v0, v0, v1
	s_nop 1
	v_mov_b32_dpp v1, v0 quad_perm:[2,3,0,1] row_mask:0xf bank_mask:0xf
	s_waitcnt lgkmcnt(0)
	v_add_f32_e32 v0, v0, v1
	s_nop 1
	v_mov_b32_dpp v1, v0 row_ror:12 row_mask:0xf bank_mask:0xf
	s_waitcnt lgkmcnt(0)
	v_add_f32_e32 v0, v0, v1
	s_nop 1
	v_mov_b32_dpp v1, v0 row_ror:8 row_mask:0xf bank_mask:0xf
	s_waitcnt lgkmcnt(0)
	v_add_f32_e32 v0, v0, v1
	v_mov_b32_e32 v1, v0
	s_nop 1
	v_permlane16_swap_b32_e32 v0, v1
	s_waitcnt lgkmcnt(0)
	v_add_f32_e32 v0, v0, v1
	v_mov_b32_e32 v1, v0
	s_nop 1
	v_permlane32_swap_b32_e32 v0, v1
	s_and_saveexec_b64 s[2:3], vcc
	s_cbranch_execz .LBB0_1951
	s_lshl_b64 s[0:1], s[0:1], 5
	s_add_u32 s0, s4, s0
	s_addc_u32 s1, s5, s1
	v_mov_b32_e32 v2, 0
	s_waitcnt lgkmcnt(0)
	v_add_f32_e32 v0, v0, v1
	global_store_dword v2, v0, s[0:1] sc1
; #define LAS __attribute__((address_space(3)))
; __device__ __forceinline__ f32x4 ld_bf4(const bf16_t* p) { u32x2 w = *(const u32x2*)p; return (f32x4){__uint_as_float(w.x << 16), __uint_as_float(w.x & 0xffff0000u), __uint_as_float(w.y << 16), __uint_as_float(w.y & 0xffff0000u)}; }
; __device__ __forceinline__ void st_bf4(bf16_t* p, f32x4 v) { u32x2 w; w.x = pk2(v[0], v[1]); w.y = pk2(v[2], v[3]); *(u32x2*)p = w; }
; __device__ __forceinline__ float wave_sum(float v) {
; #pragma unroll
;     for (int o = 1; o < 64; o <<= 1) v += __shfl_xor(v, o);
;     return v;
; template <int MODOFF, int STORE  , bool BASE_BF16>
; __device__ __forceinline__ void epi_rows_part1(LAS unsigned char* lds, const f32x4 (&acc)[2][2][4][2], const Unit& u, const float* base, const float* mod, float* outp, float* slots, f32x4 (&xr)[2][16]) {
;     ...
;         for (int j = 0; j < 16; ++j) { const int rl = wid * 16 + j, row = u.pm * BM + ai * HALF + rl; const size_t o = (size_t)row * DM + colg;
;             const f32x4 v = *(const LAS f32x4*)(T + rl * 256 + ((lane ^ j) << 2));
;             const f32x4 bs = BASE_BF16 ? ld_bf4((const bf16_t*)base + o) : *(const f32x4*)(base + o);
;             const f32x4 x1 = bs + gt * v; xr[ai][j] = x1; if (STORE == 2) st_bf4((bf16_t*)outp + o, x1);
;             const float sq = wave_sum((x1[0] * x1[0] + x1[1] * x1[1]) + (x1[2] * x1[2] + x1[3] * x1[3]));
;             if (lane == 0) __hip_atomic_store((unsigned*)slots + (size_t)row * 8 + u.pn, __float_as_uint(sq), __ATOMIC_RELAXED, __HIP_MEMORY_SCOPE_AGENT); }
.LBB0_1951:
	s_or_b64 exec, exec, s[2:3]
	s_add_i32 s0, s19, s22
	s_ashr_i32 s1, s0, 31
	s_lshl_b64 s[2:3], s[0:1], 12
	s_waitcnt lgkmcnt(0)
	v_lshl_add_u64 v[0:1], v[136:137], 0, s[2:3]
	ds_read_b128 v[0:3], v151
	s_waitcnt vmcnt(15)
	v_mov_b32_e32 v4, v224
	v_mov_b32_e32 v5, v225
	v_lshlrev_b32_e32 v6, 16, v4
	v_and_b32_e32 v7, 0xffff0000, v4
	v_lshlrev_b32_e32 v4, 16, v5
	v_and_b32_e32 v5, 0xffff0000, v5
	s_waitcnt lgkmcnt(0)
	v_pk_fma_f32 v[8:9], v[66:67], v[2:3], v[4:5]
	v_pk_fma_f32 v[12:13], v[64:65], v[0:1], v[6:7]
	v_mul_f32_e32 v1, v9, v9
	v_mul_f32_e32 v0, v13, v13
	v_fmac_f32_e32 v0, v12, v12
	v_fmac_f32_e32 v1, v8, v8
	v_add_f32_e32 v0, v0, v1
	s_nop 1
	v_mov_b32_dpp v1, v0 quad_perm:[1,0,3,2] row_mask:0xf bank_mask:0xf
	s_waitcnt lgkmcnt(0)
	v_add_f32_e32 v0, v0, v1
	s_nop 1
	v_mov_b32_dpp v1, v0 quad_perm:[2,3,0,1] row_mask:0xf bank_mask:0xf
	s_waitcnt lgkmcnt(0)
	v_add_f32_e32 v0, v0, v1
	s_nop 1
	v_mov_b32_dpp v1, v0 row_ror:12 row_mask:0xf bank_mask:0xf
	s_waitcnt lgkmcnt(0)
	v_add_f32_e32 v0, v0, v1
	s_nop 1
	v_mov_b32_dpp v1, v0 row_ror:8 row_mask:0xf bank_mask:0xf
	s_waitcnt lgkmcnt(0)
	v_add_f32_e32 v0, v0, v1
	v_mov_b32_e32 v1, v0
	s_nop 1
	v_permlane16_swap_b32_e32 v0, v1
	s_waitcnt lgkmcnt(0)
	v_add_f32_e32 v0, v0, v1
	v_mov_b32_e32 v1, v0
	s_nop 1
	v_permlane32_swap_b32_e32 v0, v1
	s_and_saveexec_b64 s[2:3], vcc
	s_cbranch_execz .LBB0_1953
	s_lshl_b64 s[0:1], s[0:1], 5
	s_add_u32 s0, s4, s0
	s_addc_u32 s1, s5, s1
	v_mov_b32_e32 v2, 0
	s_waitcnt lgkmcnt(0)
	v_add_f32_e32 v0, v0, v1
	global_store_dword v2, v0, s[0:1] sc1
.LBB0_1953:
	s_or_b64 exec, exec, s[2:3]
	s_add_i32 s0, s20, s22
	s_ashr_i32 s1, s0, 31
	s_lshl_b64 s[2:3], s[0:1], 12
	s_waitcnt lgkmcnt(0)
	v_lshl_add_u64 v[0:1], v[136:137], 0, s[2:3]
	ds_read_b128 v[0:3], v152
	s_waitcnt vmcnt(15)
	v_mov_b32_e32 v4, v228
	v_mov_b32_e32 v5, v229
	v_lshlrev_b32_e32 v6, 16, v4
	v_and_b32_e32 v7, 0xffff0000, v4
	v_lshlrev_b32_e32 v4, 16, v5
	v_and_b32_e32 v5, 0xffff0000, v5
	s_waitcnt lgkmcnt(0)
	v_pk_fma_f32 v[4:5], v[66:67], v[2:3], v[4:5]
	v_pk_fma_f32 v[6:7], v[64:65], v[0:1], v[6:7]
	v_mul_f32_e32 v1, v5, v5
	v_mul_f32_e32 v0, v7, v7
	v_fmac_f32_e32 v0, v6, v6
	v_fmac_f32_e32 v1, v4, v4
	v_add_f32_e32 v0, v0, v1
	s_nop 1
	v_mov_b32_dpp v1, v0 quad_perm:[1,0,3,2] row_mask:0xf bank_mask:0xf
	s_waitcnt lgkmcnt(0)
	v_add_f32_e32 v0, v0, v1
	s_nop 1
	v_mov_b32_dpp v1, v0 quad_perm:[2,3,0,1] row_mask:0xf bank_mask:0xf
	s_waitcnt lgkmcnt(0)
	v_add_f32_e32 v0, v0, v1
	s_nop 1
	v_mov_b32_dpp v1, v0 row_ror:12 row_mask:0xf bank_mask:0xf
	s_waitcnt lgkmcnt(0)
	v_add_f32_e32 v0, v0, v1
	s_nop 1
	v_mov_b32_dpp v1, v0 row_ror:8 row_mask:0xf bank_mask:0xf
	s_waitcnt lgkmcnt(0)
	v_add_f32_e32 v0, v0, v1
	v_mov_b32_e32 v1, v0
	s_nop 1
	v_permlane16_swap_b32_e32 v0, v1
	s_waitcnt lgkmcnt(0)
	v_add_f32_e32 v0, v0, v1
	v_mov_b32_e32 v1, v0
	s_nop 1
	v_permlane32_swap_b32_e32 v0, v1
	s_and_saveexec_b64 s[2:3], vcc
	s_cbranch_execz .LBB0_1955
	s_lshl_b64 s[0:1], s[0:1], 5
	s_add_u32 s0, s4, s0
	s_addc_u32 s1, s5, s1
	v_mov_b32_e32 v2, 0
	s_waitcnt lgkmcnt(0)
	v_add_f32_e32 v0, v0, v1
	global_store_dword v2, v0, s[0:1] sc1
.LBB0_1955:
	s_or_b64 exec, exec, s[2:3]
	s_add_i32 s0, s21, s22
	s_ashr_i32 s1, s0, 31
	s_lshl_b64 s[2:3], s[0:1], 12
	s_waitcnt lgkmcnt(0)
	v_lshl_add_u64 v[0:1], v[136:137], 0, s[2:3]
	ds_read_b128 v[0:3], v153
	s_waitcnt vmcnt(15)
	v_mov_b32_e32 v10, v232
	v_mov_b32_e32 v11, v233
	v_lshlrev_b32_e32 v16, 16, v10
	v_and_b32_e32 v17, 0xffff0000, v10
	v_lshlrev_b32_e32 v10, 16, v11
	v_and_b32_e32 v11, 0xffff0000, v11
	s_waitcnt lgkmcnt(0)
	v_pk_fma_f32 v[10:11], v[66:67], v[2:3], v[10:11]
	v_pk_fma_f32 v[16:17], v[64:65], v[0:1], v[16:17]
	v_mul_f32_e32 v1, v11, v11
	v_mul_f32_e32 v0, v17, v17
	v_fmac_f32_e32 v0, v16, v16
	v_fmac_f32_e32 v1, v10, v10
	v_add_f32_e32 v0, v0, v1
	s_nop 1
	v_mov_b32_dpp v1, v0 quad_perm:[1,0,3,2] row_mask:0xf bank_mask:0xf
	s_waitcnt lgkmcnt(0)
	v_add_f32_e32 v0, v0, v1
	s_nop 1
	v_mov_b32_dpp v1, v0 quad_perm:[2,3,0,1] row_mask:0xf bank_mask:0xf
	s_waitcnt lgkmcnt(0)
	v_add_f32_e32 v0, v0, v1
	s_nop 1
	v_mov_b32_dpp v1, v0 row_ror:12 row_mask:0xf bank_mask:0xf
	s_waitcnt lgkmcnt(0)
	v_add_f32_e32 v0, v0, v1
	s_nop 1
	v_mov_b32_dpp v1, v0 row_ror:8 row_mask:0xf bank_mask:0xf
	s_waitcnt lgkmcnt(0)
	v_add_f32_e32 v0, v0, v1
	v_mov_b32_e32 v1, v0
	s_nop 1
	v_permlane16_swap_b32_e32 v0, v1
	s_waitcnt lgkmcnt(0)
	v_add_f32_e32 v0, v0, v1
	v_mov_b32_e32 v1, v0
	s_nop 1
	v_permlane32_swap_b32_e32 v0, v1
	s_and_saveexec_b64 s[2:3], vcc
	s_cbranch_execz .LBB0_1957
	s_lshl_b64 s[0:1], s[0:1], 5
	s_add_u32 s0, s4, s0
	s_addc_u32 s1, s5, s1
	v_mov_b32_e32 v2, 0
	s_waitcnt lgkmcnt(0)
	v_add_f32_e32 v0, v0, v1
	global_store_dword v2, v0, s[0:1] sc1

; __global__ void __launch_bounds__(NTHR, 2) fwd_kernel(Args a) {
	.amdhsa_kernel _Z10fwd_kernel4Args
		.amdhsa_group_segment_fixed_size 0
		.amdhsa_private_segment_fixed_size 0
		.amdhsa_kernarg_size 448
		.amdhsa_user_sgpr_count 2
		.amdhsa_user_sgpr_dispatch_ptr 0
		.amdhsa_user_sgpr_queue_ptr 0
		.amdhsa_user_sgpr_kernarg_segment_ptr 1
		.amdhsa_user_sgpr_dispatch_id 0
		.amdhsa_user_sgpr_kernarg_preload_length 0
		.amdhsa_user_sgpr_kernarg_preload_offset 0
		.amdhsa_user_sgpr_private_segment_size 0
		.amdhsa_uses_dynamic_stack 0
		.amdhsa_enable_private_segment 0
		.amdhsa_system_sgpr_workgroup_id_x 1
		.amdhsa_system_sgpr_workgroup_id_y 0
		.amdhsa_system_sgpr_workgroup_id_z 0
		.amdhsa_system_sgpr_workgroup_info 0
		.amdhsa_system_vgpr_workitem_id 2
		.amdhsa_next_free_vgpr 256
		.amdhsa_next_free_sgpr 102
		.amdhsa_accum_offset 256
		.amdhsa_reserve_vcc 1
		.amdhsa_float_round_mode_32 0
		.amdhsa_float_round_mode_16_64 0
		.amdhsa_float_denorm_mode_32 3
		.amdhsa_float_denorm_mode_16_64 3
		.amdhsa_dx10_clamp 1
		.amdhsa_ieee_mode 1
		.amdhsa_fp16_overflow 0
		.amdhsa_tg_split 0
		.amdhsa_exception_fp_ieee_invalid_op 0
		.amdhsa_exception_fp_denorm_src 0
		.amdhsa_exception_fp_ieee_div_zero 0
		.amdhsa_exception_fp_ieee_overflow 0
		.amdhsa_exception_fp_ieee_underflow 0
		.amdhsa_exception_fp_ieee_inexact 0
		.amdhsa_exception_int_div_zero 0
	.end_amdhsa_kernel

; __global__ void __launch_bounds__(NTHR, 2) fwd_kernel(Args a) {
amdhsa.kernels:
  - .agpr_count:     0
    .args:
      - .offset:         0
        .size:           192
        .value_kind:     by_value
      - .offset:         192
        .size:           4
        .value_kind:     hidden_block_count_x
      - .offset:         196
        .size:           4
        .value_kind:     hidden_block_count_y
      - .offset:         200
        .size:           4
        .value_kind:     hidden_block_count_z
      - .offset:         204
        .size:           2
        .value_kind:     hidden_group_size_x
      - .offset:         206
        .size:           2
        .value_kind:     hidden_group_size_y
      - .offset:         208
        .size:           2
        .value_kind:     hidden_group_size_z
      - .offset:         210
        .size:           2
        .value_kind:     hidden_remainder_x
      - .offset:         212
        .size:           2
        .value_kind:     hidden_remainder_y
      - .offset:         214
        .size:           2
        .value_kind:     hidden_remainder_z
      - .offset:         232
        .size:           8
        .value_kind:     hidden_global_offset_x
      - .offset:         240
        .size:           8
        .value_kind:     hidden_global_offset_y
      - .offset:         248
        .size:           8
        .value_kind:     hidden_global_offset_z
      - .offset:         256
        .size:           2
        .value_kind:     hidden_grid_dims
      - .offset:         280
        .size:           8
        .value_kind:     hidden_multigrid_sync_arg
      - .offset:         312
        .size:           4
        .value_kind:     hidden_dynamic_lds_size
    .group_segment_fixed_size: 0
    .kernarg_segment_align: 8
    .kernarg_segment_size: 448
    .language:       OpenCL C
    .language_version:
      - 2
      - 0
    .max_flat_workgroup_size: 512
    .name:           _Z10fwd_kernel4Args
    .private_segment_fixed_size: 0
    .sgpr_count:     108
    .sgpr_spill_count: 87
    .symbol:         _Z10fwd_kernel4Args.kd
    .uniform_work_group_size: 1
    .uses_dynamic_stack: false
    .vgpr_count:     256
    .vgpr_spill_count: 0
    .wavefront_size: 64
